# GEMM: first two counted vmcnt waits after a unit epilogue no longer wait for the 16 epilogue stores
# baseline (speedup 1.0000x reference)
.LBB0_496:
	s_mov_b32 s100, 0
	s_cmp_lt_i32 s72, 7
	s_cselect_b64 s[0:1], -1, 0
	s_cmp_gt_i32 s73, 6
	s_cselect_b64 s[4:5], -1, 0
	s_and_b64 s[0:1], s[0:1], s[4:5]
	s_andn2_b64 vcc, exec, s[0:1]
	s_cbranch_vccnz .LBB0_575
	s_cmpk_gt_i32 s2, 0x1ff
	v_readfirstlane_b32 s4, v0
	s_cbranch_scc1 .LBB0_525
	s_ashr_i32 s3, s2, 31
	s_lshr_b32 s0, s3, 29
	s_add_i32 s6, s2, s0
	s_and_b32 s0, s6, -8
	s_sub_i32 s7, s2, s0
	s_cmp_gt_i32 s7, -1
	s_cbranch_scc0 .LBB0_500
	s_lshl_b32 s5, s7, 6
	s_cbranch_execz .LBB0_501
	s_branch .LBB0_502

.LBB0_518:
	ds_read_b128 v[154:157], v150
	ds_read_b128 v[158:161], v150 offset:1024
	ds_read_b128 v[162:165], v150 offset:2048
	ds_read_b128 v[166:169], v150 offset:3072
	ds_read_b128 v[170:173], v151
	ds_read_b128 v[174:177], v151 offset:1024
	ds_read_b128 v[178:181], v151 offset:2048
	ds_read_b128 v[182:185], v151 offset:3072
	s_add_u32 s26, s24, 0xfffd0080
	s_addc_u32 s27, s25, -1
	s_cmp_eq_u32 s63, 8
	s_cselect_b32 s29, s5, s27
	s_cselect_b32 s28, s4, s26
	s_cselect_b32 s27, s23, s62
	s_cselect_b32 s26, s22, s61
	v_lshl_add_u64 v[146:147], s[24:25], 0, v[138:139]
	s_add_i32 m0, s36, 0xc000
	ds_read_b128 v[186:189], v152
	ds_read_b128 v[190:193], v152 offset:1024
	ds_read_b128 v[194:197], v152 offset:2048
	ds_read_b128 v[198:201], v152 offset:3072
	ds_read_b128 v[202:205], v152 offset:4096
	ds_read_b128 v[206:209], v152 offset:5120
	ds_read_b128 v[210:213], v152 offset:6144
	ds_read_b128 v[214:217], v152 offset:7168
	global_load_lds_dwordx4 v[146:147], off
	v_lshl_add_u64 v[146:147], s[24:25], 0, v[140:141]
	s_add_i32 m0, s36, 0xe000
	s_nop 0
	global_load_lds_dwordx4 v[146:147], off
	s_cmp_lg_u32 s100, 0
	s_cbranch_scc1 .Lrw0_0a
	s_waitcnt vmcnt(8)
	s_branch .Lrw0_0b
.Lrw0_0a:
	s_waitcnt vmcnt(24)
.Lrw0_0b:
	s_waitcnt lgkmcnt(0)
	s_barrier
	s_setprio 1
	s_waitcnt lgkmcnt(0)
	v_mfma_f32_16x16x32_bf16 v[126:129], v[154:157], v[186:189], v[126:129]
	v_mfma_f32_16x16x32_bf16 v[122:125], v[162:165], v[186:189], v[122:125]
	v_mfma_f32_16x16x32_bf16 v[118:121], v[154:157], v[194:197], v[118:121]
	v_mfma_f32_16x16x32_bf16 v[110:113], v[162:165], v[194:197], v[110:113]
	v_mfma_f32_16x16x32_bf16 v[102:105], v[154:157], v[202:205], v[102:105]
	v_mfma_f32_16x16x32_bf16 v[94:97], v[162:165], v[202:205], v[94:97]
	v_mfma_f32_16x16x32_bf16 v[86:89], v[154:157], v[210:213], v[86:89]
	v_mfma_f32_16x16x32_bf16 v[78:81], v[162:165], v[210:213], v[78:81]
	v_mfma_f32_16x16x32_bf16 v[126:129], v[158:161], v[190:193], v[126:129]
	v_mfma_f32_16x16x32_bf16 v[122:125], v[166:169], v[190:193], v[122:125]
	v_mfma_f32_16x16x32_bf16 v[118:121], v[158:161], v[198:201], v[118:121]
	v_mfma_f32_16x16x32_bf16 v[110:113], v[166:169], v[198:201], v[110:113]
	v_mfma_f32_16x16x32_bf16 v[102:105], v[158:161], v[206:209], v[102:105]
	v_mfma_f32_16x16x32_bf16 v[94:97], v[166:169], v[206:209], v[94:97]
	v_mfma_f32_16x16x32_bf16 v[86:89], v[158:161], v[214:217], v[86:89]
	v_mfma_f32_16x16x32_bf16 v[78:81], v[166:169], v[214:217], v[78:81]
	s_setprio 0
	s_setprio 1
	v_mfma_f32_16x16x32_bf16 v[114:117], v[170:173], v[186:189], v[114:117]
	v_mfma_f32_16x16x32_bf16 v[106:109], v[178:181], v[186:189], v[106:109]
	v_mfma_f32_16x16x32_bf16 v[98:101], v[170:173], v[194:197], v[98:101]
	v_mfma_f32_16x16x32_bf16 v[90:93], v[178:181], v[194:197], v[90:93]
	v_mfma_f32_16x16x32_bf16 v[82:85], v[170:173], v[202:205], v[82:85]
	v_mfma_f32_16x16x32_bf16 v[74:77], v[178:181], v[202:205], v[74:77]
	v_mfma_f32_16x16x32_bf16 v[70:73], v[170:173], v[210:213], v[70:73]
	v_mfma_f32_16x16x32_bf16 v[66:69], v[178:181], v[210:213], v[66:69]
	v_mfma_f32_16x16x32_bf16 v[114:117], v[174:177], v[190:193], v[114:117]
	v_mfma_f32_16x16x32_bf16 v[106:109], v[182:185], v[190:193], v[106:109]
	v_mfma_f32_16x16x32_bf16 v[98:101], v[174:177], v[198:201], v[98:101]
	v_mfma_f32_16x16x32_bf16 v[90:93], v[182:185], v[198:201], v[90:93]
	v_mfma_f32_16x16x32_bf16 v[82:85], v[174:177], v[206:209], v[82:85]
	v_mfma_f32_16x16x32_bf16 v[74:77], v[182:185], v[206:209], v[74:77]
	v_mfma_f32_16x16x32_bf16 v[70:73], v[174:177], v[214:217], v[70:73]
	v_mfma_f32_16x16x32_bf16 v[66:69], v[182:185], v[214:217], v[66:69]
	s_setprio 0
	s_barrier
	s_add_i32 s64, s47, s35
	v_lshl_add_u64 v[146:147], s[26:27], 0, v[132:133]
	s_mov_b32 m0, s64
	ds_read_b128 v[186:189], v152 offset:16384
	ds_read_b128 v[190:193], v152 offset:17408
	ds_read_b128 v[194:197], v152 offset:18432
	ds_read_b128 v[198:201], v152 offset:19456
	ds_read_b128 v[202:205], v152 offset:20480
	ds_read_b128 v[206:209], v152 offset:21504
	ds_read_b128 v[210:213], v152 offset:22528
	ds_read_b128 v[214:217], v152 offset:23552
	global_load_lds_dwordx4 v[146:147], off
	s_add_i32 m0, s64, 0x2000
	s_add_u32 s64, s26, 0x30000
	v_lshl_add_u64 v[218:219], s[26:27], 0, v[136:137]
	s_addc_u32 s65, s27, 0
	s_add_i32 s66, s52, s35
	global_load_lds_dwordx4 v[218:219], off
	v_lshl_add_u64 v[220:221], s[64:65], 0, v[132:133]
	s_mov_b32 m0, s66
	v_lshl_add_u64 v[222:223], s[28:29], 0, v[134:135]
	global_load_lds_dwordx4 v[220:221], off
	v_lshl_add_u64 v[220:221], s[64:65], 0, v[136:137]
	s_add_i32 m0, s66, 0x2000
	s_nop 0
	global_load_lds_dwordx4 v[220:221], off
	v_lshl_add_u64 v[220:221], s[28:29], 0, v[130:131]
	s_mov_b32 m0, s36
	s_nop 0
	global_load_lds_dwordx4 v[220:221], off
	s_mov_b32 m0, s37
	s_nop 0
	global_load_lds_dwordx4 v[222:223], off
	s_cmp_lg_u32 s100, 0
	s_cbranch_scc1 .Lrw0_1a
	s_waitcnt vmcnt(8)
	s_branch .Lrw0_1b

.Lrw0_1b:
	s_waitcnt lgkmcnt(0)
	s_barrier
	s_setprio 1
	s_waitcnt lgkmcnt(0)
	v_mfma_f32_16x16x32_bf16 v[62:65], v[154:157], v[186:189], v[62:65]
	v_mfma_f32_16x16x32_bf16 v[58:61], v[162:165], v[186:189], v[58:61]
	v_mfma_f32_16x16x32_bf16 v[54:57], v[154:157], v[194:197], v[54:57]
	v_mfma_f32_16x16x32_bf16 v[46:49], v[162:165], v[194:197], v[46:49]
	v_mfma_f32_16x16x32_bf16 v[38:41], v[154:157], v[202:205], v[38:41]
	v_mfma_f32_16x16x32_bf16 v[30:33], v[162:165], v[202:205], v[30:33]
	v_mfma_f32_16x16x32_bf16 v[22:25], v[154:157], v[210:213], v[22:25]
	v_mfma_f32_16x16x32_bf16 v[14:17], v[162:165], v[210:213], v[14:17]
	v_mfma_f32_16x16x32_bf16 v[62:65], v[158:161], v[190:193], v[62:65]
	v_mfma_f32_16x16x32_bf16 v[58:61], v[166:169], v[190:193], v[58:61]
	v_mfma_f32_16x16x32_bf16 v[54:57], v[158:161], v[198:201], v[54:57]
	v_mfma_f32_16x16x32_bf16 v[46:49], v[166:169], v[198:201], v[46:49]
	v_mfma_f32_16x16x32_bf16 v[38:41], v[158:161], v[206:209], v[38:41]
	v_mfma_f32_16x16x32_bf16 v[30:33], v[166:169], v[206:209], v[30:33]
	v_mfma_f32_16x16x32_bf16 v[22:25], v[158:161], v[214:217], v[22:25]
	v_mfma_f32_16x16x32_bf16 v[14:17], v[166:169], v[214:217], v[14:17]
	s_setprio 0
	s_setprio 1
	v_mfma_f32_16x16x32_bf16 v[50:53], v[170:173], v[186:189], v[50:53]
	v_mfma_f32_16x16x32_bf16 v[42:45], v[178:181], v[186:189], v[42:45]
	v_mfma_f32_16x16x32_bf16 v[34:37], v[170:173], v[194:197], v[34:37]
	v_mfma_f32_16x16x32_bf16 v[26:29], v[178:181], v[194:197], v[26:29]
	v_mfma_f32_16x16x32_bf16 v[18:21], v[170:173], v[202:205], v[18:21]
	v_mfma_f32_16x16x32_bf16 v[10:13], v[178:181], v[202:205], v[10:13]
	v_mfma_f32_16x16x32_bf16 v[6:9], v[170:173], v[210:213], v[6:9]
	v_mfma_f32_16x16x32_bf16 v[2:5], v[178:181], v[210:213], v[2:5]
	v_mfma_f32_16x16x32_bf16 v[50:53], v[174:177], v[190:193], v[50:53]
	v_mfma_f32_16x16x32_bf16 v[42:45], v[182:185], v[190:193], v[42:45]
	v_mfma_f32_16x16x32_bf16 v[34:37], v[174:177], v[198:201], v[34:37]
	v_mfma_f32_16x16x32_bf16 v[26:29], v[182:185], v[198:201], v[26:29]
	v_mfma_f32_16x16x32_bf16 v[18:21], v[174:177], v[206:209], v[18:21]
	v_mfma_f32_16x16x32_bf16 v[10:13], v[182:185], v[206:209], v[10:13]
	v_mfma_f32_16x16x32_bf16 v[6:9], v[174:177], v[214:217], v[6:9]
	v_mfma_f32_16x16x32_bf16 v[2:5], v[182:185], v[214:217], v[2:5]
	s_setprio 0
	s_barrier
	s_add_i32 s64, 0, 0x18000
	v_add_u32_e32 v153, s64, v148
	s_add_i32 s65, 0, 0x1c000
	ds_read_b128 v[154:157], v153
	ds_read_b128 v[158:161], v153 offset:1024
	ds_read_b128 v[162:165], v153 offset:2048
	ds_read_b128 v[166:169], v153 offset:3072
	v_add_u32_e32 v153, s65, v148
	ds_read_b128 v[170:173], v153
	ds_read_b128 v[174:177], v153 offset:1024
	ds_read_b128 v[178:181], v153 offset:2048
	ds_read_b128 v[182:185], v153 offset:3072
	s_add_u32 s28, s28, 0x30000
	s_addc_u32 s29, s29, 0
	s_mov_b32 m0, s38
	v_lshl_add_u64 v[224:225], s[28:29], 0, v[130:131]
	ds_read_b128 v[186:189], v152 offset:32768
	ds_read_b128 v[190:193], v152 offset:33792
	ds_read_b128 v[194:197], v152 offset:34816
	ds_read_b128 v[198:201], v152 offset:35840
	ds_read_b128 v[202:205], v152 offset:36864
	ds_read_b128 v[206:209], v152 offset:37888
	ds_read_b128 v[210:213], v152 offset:38912
	ds_read_b128 v[214:217], v152 offset:39936
	global_load_lds_dwordx4 v[224:225], off
	v_lshl_add_u64 v[224:225], s[28:29], 0, v[134:135]
	s_mov_b32 m0, s39
	s_nop 0
	global_load_lds_dwordx4 v[224:225], off
	s_waitcnt vmcnt(8)
	s_waitcnt lgkmcnt(0)
	s_barrier
	s_setprio 1
	s_waitcnt lgkmcnt(0)
	v_mfma_f32_16x16x32_bf16 v[126:129], v[154:157], v[186:189], v[126:129]
	v_mfma_f32_16x16x32_bf16 v[122:125], v[162:165], v[186:189], v[122:125]
	v_mfma_f32_16x16x32_bf16 v[118:121], v[154:157], v[194:197], v[118:121]
	v_mfma_f32_16x16x32_bf16 v[110:113], v[162:165], v[194:197], v[110:113]
	v_mfma_f32_16x16x32_bf16 v[102:105], v[154:157], v[202:205], v[102:105]
	v_mfma_f32_16x16x32_bf16 v[94:97], v[162:165], v[202:205], v[94:97]
	v_mfma_f32_16x16x32_bf16 v[86:89], v[154:157], v[210:213], v[86:89]
	v_mfma_f32_16x16x32_bf16 v[78:81], v[162:165], v[210:213], v[78:81]
	v_mfma_f32_16x16x32_bf16 v[126:129], v[158:161], v[190:193], v[126:129]
	v_mfma_f32_16x16x32_bf16 v[122:125], v[166:169], v[190:193], v[122:125]
	v_mfma_f32_16x16x32_bf16 v[118:121], v[158:161], v[198:201], v[118:121]
	v_mfma_f32_16x16x32_bf16 v[110:113], v[166:169], v[198:201], v[110:113]
	v_mfma_f32_16x16x32_bf16 v[102:105], v[158:161], v[206:209], v[102:105]
	v_mfma_f32_16x16x32_bf16 v[94:97], v[166:169], v[206:209], v[94:97]
	v_mfma_f32_16x16x32_bf16 v[86:89], v[158:161], v[214:217], v[86:89]
	v_mfma_f32_16x16x32_bf16 v[78:81], v[166:169], v[214:217], v[78:81]
	s_setprio 0
	s_setprio 1
	v_mfma_f32_16x16x32_bf16 v[114:117], v[170:173], v[186:189], v[114:117]
	v_mfma_f32_16x16x32_bf16 v[106:109], v[178:181], v[186:189], v[106:109]
	v_mfma_f32_16x16x32_bf16 v[98:101], v[170:173], v[194:197], v[98:101]
	v_mfma_f32_16x16x32_bf16 v[90:93], v[178:181], v[194:197], v[90:93]
	v_mfma_f32_16x16x32_bf16 v[82:85], v[170:173], v[202:205], v[82:85]
	v_mfma_f32_16x16x32_bf16 v[74:77], v[178:181], v[202:205], v[74:77]
	v_mfma_f32_16x16x32_bf16 v[70:73], v[170:173], v[210:213], v[70:73]
	v_mfma_f32_16x16x32_bf16 v[66:69], v[178:181], v[210:213], v[66:69]
	v_mfma_f32_16x16x32_bf16 v[114:117], v[174:177], v[190:193], v[114:117]
	v_mfma_f32_16x16x32_bf16 v[106:109], v[182:185], v[190:193], v[106:109]
	v_mfma_f32_16x16x32_bf16 v[98:101], v[174:177], v[198:201], v[98:101]
	v_mfma_f32_16x16x32_bf16 v[90:93], v[182:185], v[198:201], v[90:93]
	v_mfma_f32_16x16x32_bf16 v[82:85], v[174:177], v[206:209], v[82:85]
	v_mfma_f32_16x16x32_bf16 v[74:77], v[182:185], v[206:209], v[74:77]
	v_mfma_f32_16x16x32_bf16 v[70:73], v[174:177], v[214:217], v[70:73]
	v_mfma_f32_16x16x32_bf16 v[66:69], v[182:185], v[214:217], v[66:69]
	s_setprio 0
	s_barrier
	s_add_i32 s28, s64, s35
	v_lshl_add_u64 v[146:147], v[146:147], 0, s[10:11]
	s_mov_b32 m0, s28
	ds_read_b128 v[186:189], v152 offset:49152
	ds_read_b128 v[190:193], v152 offset:50176
	ds_read_b128 v[194:197], v152 offset:51200
	ds_read_b128 v[198:201], v152 offset:52224
	ds_read_b128 v[202:205], v152 offset:53248
	ds_read_b128 v[206:209], v152 offset:54272
	ds_read_b128 v[210:213], v152 offset:55296
	ds_read_b128 v[214:217], v152 offset:56320
	global_load_lds_dwordx4 v[146:147], off
	s_add_i32 m0, s28, 0x2000
	s_add_u32 s26, s26, 0x30080
	v_lshl_add_u64 v[146:147], v[218:219], 0, s[10:11]
	s_addc_u32 s27, s27, 0
	s_add_i32 s28, s65, s35
	global_load_lds_dwordx4 v[146:147], off
	v_lshl_add_u64 v[146:147], s[26:27], 0, v[132:133]
	s_mov_b32 m0, s28
	s_nop 0
	global_load_lds_dwordx4 v[146:147], off
	v_lshl_add_u64 v[146:147], s[26:27], 0, v[136:137]
	s_add_i32 m0, s28, 0x2000
	s_nop 0
	global_load_lds_dwordx4 v[146:147], off
	v_lshl_add_u64 v[146:147], v[220:221], 0, s[10:11]
	s_mov_b32 m0, s41
	s_nop 0
	global_load_lds_dwordx4 v[146:147], off
	v_lshl_add_u64 v[146:147], v[222:223], 0, s[10:11]
	s_mov_b32 m0, s44
	s_nop 0
	global_load_lds_dwordx4 v[146:147], off
	s_waitcnt vmcnt(8)
	s_waitcnt lgkmcnt(0)
	s_barrier
	s_setprio 1
	s_waitcnt lgkmcnt(0)
	v_mfma_f32_16x16x32_bf16 v[62:65], v[154:157], v[186:189], v[62:65]
	v_mfma_f32_16x16x32_bf16 v[58:61], v[162:165], v[186:189], v[58:61]
	v_mfma_f32_16x16x32_bf16 v[54:57], v[154:157], v[194:197], v[54:57]
	v_mfma_f32_16x16x32_bf16 v[46:49], v[162:165], v[194:197], v[46:49]
	v_mfma_f32_16x16x32_bf16 v[38:41], v[154:157], v[202:205], v[38:41]
	v_mfma_f32_16x16x32_bf16 v[30:33], v[162:165], v[202:205], v[30:33]
	v_mfma_f32_16x16x32_bf16 v[22:25], v[154:157], v[210:213], v[22:25]
	v_mfma_f32_16x16x32_bf16 v[14:17], v[162:165], v[210:213], v[14:17]
	v_mfma_f32_16x16x32_bf16 v[62:65], v[158:161], v[190:193], v[62:65]
	v_mfma_f32_16x16x32_bf16 v[58:61], v[166:169], v[190:193], v[58:61]
	v_mfma_f32_16x16x32_bf16 v[54:57], v[158:161], v[198:201], v[54:57]
	v_mfma_f32_16x16x32_bf16 v[46:49], v[166:169], v[198:201], v[46:49]
	v_mfma_f32_16x16x32_bf16 v[38:41], v[158:161], v[206:209], v[38:41]
	v_mfma_f32_16x16x32_bf16 v[30:33], v[166:169], v[206:209], v[30:33]
	v_mfma_f32_16x16x32_bf16 v[22:25], v[158:161], v[214:217], v[22:25]
	v_mfma_f32_16x16x32_bf16 v[14:17], v[166:169], v[214:217], v[14:17]
	s_setprio 0
	s_setprio 1
	v_mfma_f32_16x16x32_bf16 v[50:53], v[170:173], v[186:189], v[50:53]
	v_mfma_f32_16x16x32_bf16 v[42:45], v[178:181], v[186:189], v[42:45]
	v_mfma_f32_16x16x32_bf16 v[34:37], v[170:173], v[194:197], v[34:37]
	v_mfma_f32_16x16x32_bf16 v[26:29], v[178:181], v[194:197], v[26:29]
	v_mfma_f32_16x16x32_bf16 v[18:21], v[170:173], v[202:205], v[18:21]
	v_mfma_f32_16x16x32_bf16 v[10:13], v[178:181], v[202:205], v[10:13]
	v_mfma_f32_16x16x32_bf16 v[6:9], v[170:173], v[210:213], v[6:9]
	v_mfma_f32_16x16x32_bf16 v[2:5], v[178:181], v[210:213], v[2:5]
	v_mfma_f32_16x16x32_bf16 v[50:53], v[174:177], v[190:193], v[50:53]
	v_mfma_f32_16x16x32_bf16 v[42:45], v[182:185], v[190:193], v[42:45]
	v_mfma_f32_16x16x32_bf16 v[34:37], v[174:177], v[198:201], v[34:37]
	v_mfma_f32_16x16x32_bf16 v[26:29], v[182:185], v[198:201], v[26:29]
	v_mfma_f32_16x16x32_bf16 v[18:21], v[174:177], v[206:209], v[18:21]
	v_mfma_f32_16x16x32_bf16 v[10:13], v[182:185], v[206:209], v[10:13]
	v_mfma_f32_16x16x32_bf16 v[6:9], v[174:177], v[214:217], v[6:9]
	v_mfma_f32_16x16x32_bf16 v[2:5], v[182:185], v[214:217], v[2:5]
	s_setprio 0
	s_barrier
	s_add_i32 s63, s63, 2
	s_add_u32 s24, s24, 0x100
	s_addc_u32 s25, s25, 0
	s_add_u32 s61, s61, 0x100
	s_addc_u32 s62, s62, 0
	s_mov_b32 s100, 0
	s_cmp_gt_u32 s63, 9
	s_cbranch_scc0 .LBB0_518
	s_and_b64 vcc, exec, s[12:13]
	s_cbranch_vccz .LBB0_521
	s_barrier
.LBB0_521:
	v_lshl_add_u32 v154, s59, 8, v1
	v_lshl_or_b32 v146, s60, 8, v149
	v_ashrrev_i32_e32 v155, 31, v154
	v_ashrrev_i32_e32 v147, 31, v146
	v_lshlrev_b64 v[156:157], 11, v[154:155]
	v_lshl_add_u64 v[156:157], s[8:9], 0, v[156:157]
	v_lshlrev_b64 v[158:159], 1, v[146:147]
	v_lshl_add_u64 v[146:147], v[156:157], 0, v[158:159]
	v_cvt_pk_bf16_f32 v126, v126, v127
	v_cvt_pk_bf16_f32 v127, v128, v129
	v_cvt_pk_bf16_f32 v128, v122, v123
	v_cvt_pk_bf16_f32 v129, v124, v125
	global_store_dwordx4 v[146:147], v[126:129], off
	v_cvt_pk_bf16_f32 v114, v114, v115
	v_cvt_pk_bf16_f32 v115, v116, v117
	v_cvt_pk_bf16_f32 v116, v106, v107
	v_or_b32_e32 v106, 16, v154
	v_ashrrev_i32_e32 v107, 31, v106
	v_lshlrev_b64 v[106:107], 11, v[106:107]
	v_lshl_add_u64 v[106:107], s[8:9], 0, v[106:107]
	v_cvt_pk_bf16_f32 v117, v108, v109
	global_store_dwordx4 v[146:147], v[114:117], off offset:256
	s_nop 1
	v_lshl_add_u64 v[114:115], v[106:107], 0, v[158:159]
	v_cvt_pk_bf16_f32 v106, v118, v119
	v_cvt_pk_bf16_f32 v107, v120, v121
	v_cvt_pk_bf16_f32 v108, v110, v111
	v_cvt_pk_bf16_f32 v109, v112, v113
	global_store_dwordx4 v[114:115], v[106:109], off
	v_cvt_pk_bf16_f32 v98, v98, v99
	v_cvt_pk_bf16_f32 v99, v100, v101
	v_cvt_pk_bf16_f32 v100, v90, v91
	v_or_b32_e32 v90, 32, v154
	v_ashrrev_i32_e32 v91, 31, v90
	v_lshlrev_b64 v[90:91], 11, v[90:91]
	v_lshl_add_u64 v[90:91], s[8:9], 0, v[90:91]
	v_cvt_pk_bf16_f32 v101, v92, v93
	global_store_dwordx4 v[114:115], v[98:101], off offset:256
	s_nop 1
	v_lshl_add_u64 v[98:99], v[90:91], 0, v[158:159]
	v_cvt_pk_bf16_f32 v90, v102, v103
	v_cvt_pk_bf16_f32 v91, v104, v105
	v_cvt_pk_bf16_f32 v92, v94, v95
	v_cvt_pk_bf16_f32 v93, v96, v97
	global_store_dwordx4 v[98:99], v[90:93], off
	v_cvt_pk_bf16_f32 v82, v82, v83
	v_cvt_pk_bf16_f32 v83, v84, v85
	v_cvt_pk_bf16_f32 v84, v74, v75
	v_or_b32_e32 v74, 48, v154
	v_ashrrev_i32_e32 v75, 31, v74
	v_lshlrev_b64 v[74:75], 11, v[74:75]
	v_lshl_add_u64 v[74:75], s[8:9], 0, v[74:75]
	v_cvt_pk_bf16_f32 v85, v76, v77
	global_store_dwordx4 v[98:99], v[82:85], off offset:256
	s_nop 1
	v_lshl_add_u64 v[82:83], v[74:75], 0, v[158:159]
	v_cvt_pk_bf16_f32 v74, v86, v87
	v_cvt_pk_bf16_f32 v75, v88, v89
	v_cvt_pk_bf16_f32 v76, v78, v79
	v_cvt_pk_bf16_f32 v77, v80, v81
	global_store_dwordx4 v[82:83], v[74:77], off
	v_cvt_pk_bf16_f32 v70, v70, v71
	v_cvt_pk_bf16_f32 v71, v72, v73
	v_cvt_pk_bf16_f32 v72, v66, v67
	v_cvt_pk_bf16_f32 v73, v68, v69
	global_store_dwordx4 v[82:83], v[70:73], off offset:256
	v_cvt_pk_bf16_f32 v62, v62, v63
	v_cvt_pk_bf16_f32 v63, v64, v65
	v_cvt_pk_bf16_f32 v64, v58, v59
	v_add_co_u32_e32 v58, vcc, s53, v146
	v_lshl_add_u64 v[66:67], v[146:147], 0, s[14:15]
	s_nop 0
	v_addc_co_u32_e32 v59, vcc, 0, v147, vcc
	v_cvt_pk_bf16_f32 v65, v60, v61
	global_store_dwordx4 v[58:59], v[62:65], off
	v_cvt_pk_bf16_f32 v50, v50, v51
	v_cvt_pk_bf16_f32 v51, v52, v53
	v_cvt_pk_bf16_f32 v52, v42, v43
	v_cvt_pk_bf16_f32 v53, v44, v45
	global_store_dwordx4 v[66:67], v[50:53], off offset:256
	v_cvt_pk_bf16_f32 v42, v54, v55
	v_cvt_pk_bf16_f32 v43, v56, v57
	v_cvt_pk_bf16_f32 v44, v46, v47
	v_add_co_u32_e32 v46, vcc, s54, v146
	s_nop 0
	v_lshl_add_u64 v[50:51], v[146:147], 0, s[16:17]
	v_addc_co_u32_e32 v47, vcc, 0, v147, vcc
	v_cvt_pk_bf16_f32 v45, v48, v49
	global_store_dwordx4 v[46:47], v[42:45], off
	v_cvt_pk_bf16_f32 v34, v34, v35
	v_cvt_pk_bf16_f32 v35, v36, v37
	v_cvt_pk_bf16_f32 v36, v26, v27
	v_cvt_pk_bf16_f32 v37, v28, v29
	global_store_dwordx4 v[50:51], v[34:37], off offset:256
	v_cvt_pk_bf16_f32 v26, v38, v39
	v_cvt_pk_bf16_f32 v27, v40, v41
	v_cvt_pk_bf16_f32 v28, v30, v31
	v_add_co_u32_e32 v30, vcc, s55, v146
	s_nop 0
	v_lshl_add_u64 v[34:35], v[146:147], 0, s[18:19]
	v_addc_co_u32_e32 v31, vcc, 0, v147, vcc
	v_cvt_pk_bf16_f32 v29, v32, v33
	global_store_dwordx4 v[30:31], v[26:29], off
	v_cvt_pk_bf16_f32 v18, v18, v19
	v_cvt_pk_bf16_f32 v19, v20, v21
	v_cvt_pk_bf16_f32 v20, v10, v11
	v_cvt_pk_bf16_f32 v21, v12, v13
	global_store_dwordx4 v[34:35], v[18:21], off offset:256
	v_cvt_pk_bf16_f32 v10, v22, v23
	v_cvt_pk_bf16_f32 v11, v24, v25
	v_cvt_pk_bf16_f32 v12, v14, v15
	v_add_co_u32_e32 v14, vcc, s56, v146
	s_nop 0
	v_lshl_add_u64 v[18:19], v[146:147], 0, s[20:21]
	v_addc_co_u32_e32 v15, vcc, 0, v147, vcc
	s_and_b64 vcc, exec, s[0:1]
	s_mov_b64 s[0:1], -1
	v_cvt_pk_bf16_f32 v13, v16, v17
	global_store_dwordx4 v[14:15], v[10:13], off
	v_cvt_pk_bf16_f32 v6, v6, v7
	v_cvt_pk_bf16_f32 v7, v8, v9
	v_cvt_pk_bf16_f32 v8, v2, v3
	v_cvt_pk_bf16_f32 v9, v4, v5
	global_store_dwordx4 v[18:19], v[6:9], off offset:256
	s_mov_b32 s100, 1
	s_cbranch_vccnz .LBB0_506
	s_andn2_b64 vcc, exec, s[6:7]
	s_cbranch_vccnz .LBB0_505
	s_barrier
	s_branch .LBB0_505

.LBB0_635:
	s_mov_b32 s100, 0
	s_cmp_lt_i32 s72, 9
	s_cselect_b64 s[0:1], -1, 0
	s_cmp_gt_i32 s73, 8
	s_cselect_b64 s[4:5], -1, 0
	s_and_b64 s[0:1], s[0:1], s[4:5]
	s_andn2_b64 vcc, exec, s[0:1]
	s_cbranch_vccnz .LBB0_710
	s_cmpk_gt_i32 s2, 0x7ff
	v_readfirstlane_b32 s10, v0
	s_cbranch_scc1 .LBB0_660
	s_ashr_i32 s3, s2, 31
	s_lshr_b32 s0, s3, 29
	s_add_i32 s5, s2, s0
	s_and_b32 s0, s5, -8
	s_sub_i32 s6, s2, s0
	s_cmp_gt_i32 s6, -1
	s_cbranch_scc0 .LBB0_639
	s_lshl_b32 s4, s6, 8
	s_cbranch_execz .LBB0_640
	s_branch .LBB0_641

.LBB0_653:
	ds_read_b128 v[154:157], v150
	ds_read_b128 v[158:161], v150 offset:1024
	ds_read_b128 v[162:165], v150 offset:2048
	ds_read_b128 v[166:169], v150 offset:3072
	ds_read_b128 v[170:173], v151
	ds_read_b128 v[174:177], v151 offset:1024
	ds_read_b128 v[178:181], v151 offset:2048
	ds_read_b128 v[182:185], v151 offset:3072
	s_add_u32 s34, s30, 0xfffc0080
	s_addc_u32 s35, s31, -1
	s_cmp_eq_u32 s67, 12
	s_cselect_b32 s37, s23, s35
	s_cselect_b32 s36, s63, s34
	s_cselect_b32 s35, s21, s66
	s_cselect_b32 s34, s64, s65
	v_lshl_add_u64 v[146:147], s[30:31], 0, v[138:139]
	s_add_i32 m0, s29, 0xc000
	ds_read_b128 v[186:189], v152
	ds_read_b128 v[190:193], v152 offset:1024
	ds_read_b128 v[194:197], v152 offset:2048
	ds_read_b128 v[198:201], v152 offset:3072
	ds_read_b128 v[202:205], v152 offset:4096
	ds_read_b128 v[206:209], v152 offset:5120
	ds_read_b128 v[210:213], v152 offset:6144
	ds_read_b128 v[214:217], v152 offset:7168
	global_load_lds_dwordx4 v[146:147], off
	v_lshl_add_u64 v[146:147], s[30:31], 0, v[140:141]
	s_add_i32 m0, s29, 0xe000
	s_nop 0
	global_load_lds_dwordx4 v[146:147], off
	s_cmp_lg_u32 s100, 0
	s_cbranch_scc1 .Lrw1_0a
	s_waitcnt vmcnt(8)
	s_branch .Lrw1_0b

.Lrw1_0b:
	s_waitcnt lgkmcnt(0)
	s_barrier
	s_setprio 1
	s_waitcnt lgkmcnt(0)
	v_mfma_f32_16x16x32_bf16 v[126:129], v[154:157], v[186:189], v[126:129]
	v_mfma_f32_16x16x32_bf16 v[122:125], v[162:165], v[186:189], v[122:125]
	v_mfma_f32_16x16x32_bf16 v[110:113], v[154:157], v[194:197], v[110:113]
	v_mfma_f32_16x16x32_bf16 v[106:109], v[162:165], v[194:197], v[106:109]
	v_mfma_f32_16x16x32_bf16 v[94:97], v[154:157], v[202:205], v[94:97]
	v_mfma_f32_16x16x32_bf16 v[90:93], v[162:165], v[202:205], v[90:93]
	v_mfma_f32_16x16x32_bf16 v[78:81], v[154:157], v[210:213], v[78:81]
	v_mfma_f32_16x16x32_bf16 v[74:77], v[162:165], v[210:213], v[74:77]
	v_mfma_f32_16x16x32_bf16 v[126:129], v[158:161], v[190:193], v[126:129]
	v_mfma_f32_16x16x32_bf16 v[122:125], v[166:169], v[190:193], v[122:125]
	v_mfma_f32_16x16x32_bf16 v[110:113], v[158:161], v[198:201], v[110:113]
	v_mfma_f32_16x16x32_bf16 v[106:109], v[166:169], v[198:201], v[106:109]
	v_mfma_f32_16x16x32_bf16 v[94:97], v[158:161], v[206:209], v[94:97]
	v_mfma_f32_16x16x32_bf16 v[90:93], v[166:169], v[206:209], v[90:93]
	v_mfma_f32_16x16x32_bf16 v[78:81], v[158:161], v[214:217], v[78:81]
	v_mfma_f32_16x16x32_bf16 v[74:77], v[166:169], v[214:217], v[74:77]
	s_setprio 0
	s_setprio 1
	v_mfma_f32_16x16x32_bf16 v[118:121], v[170:173], v[186:189], v[118:121]
	v_mfma_f32_16x16x32_bf16 v[114:117], v[178:181], v[186:189], v[114:117]
	v_mfma_f32_16x16x32_bf16 v[102:105], v[170:173], v[194:197], v[102:105]
	v_mfma_f32_16x16x32_bf16 v[98:101], v[178:181], v[194:197], v[98:101]
	v_mfma_f32_16x16x32_bf16 v[86:89], v[170:173], v[202:205], v[86:89]
	v_mfma_f32_16x16x32_bf16 v[82:85], v[178:181], v[202:205], v[82:85]
	v_mfma_f32_16x16x32_bf16 v[70:73], v[170:173], v[210:213], v[70:73]
	v_mfma_f32_16x16x32_bf16 v[66:69], v[178:181], v[210:213], v[66:69]
	v_mfma_f32_16x16x32_bf16 v[118:121], v[174:177], v[190:193], v[118:121]
	v_mfma_f32_16x16x32_bf16 v[114:117], v[182:185], v[190:193], v[114:117]
	v_mfma_f32_16x16x32_bf16 v[102:105], v[174:177], v[198:201], v[102:105]
	v_mfma_f32_16x16x32_bf16 v[98:101], v[182:185], v[198:201], v[98:101]
	v_mfma_f32_16x16x32_bf16 v[86:89], v[174:177], v[206:209], v[86:89]
	v_mfma_f32_16x16x32_bf16 v[82:85], v[182:185], v[206:209], v[82:85]
	v_mfma_f32_16x16x32_bf16 v[70:73], v[174:177], v[214:217], v[70:73]
	v_mfma_f32_16x16x32_bf16 v[66:69], v[182:185], v[214:217], v[66:69]
	s_setprio 0
	s_barrier
	s_add_i32 s68, s56, s41
	v_lshl_add_u64 v[146:147], s[34:35], 0, v[132:133]
	s_mov_b32 m0, s68
	ds_read_b128 v[186:189], v152 offset:16384
	ds_read_b128 v[190:193], v152 offset:17408
	ds_read_b128 v[194:197], v152 offset:18432
	ds_read_b128 v[198:201], v152 offset:19456
	ds_read_b128 v[202:205], v152 offset:20480
	ds_read_b128 v[206:209], v152 offset:21504
	ds_read_b128 v[210:213], v152 offset:22528
	ds_read_b128 v[214:217], v152 offset:23552
	global_load_lds_dwordx4 v[146:147], off
	s_add_i32 m0, s68, 0x2000
	s_add_u32 s68, s34, 0x40000
	v_lshl_add_u64 v[218:219], s[34:35], 0, v[136:137]
	s_addc_u32 s69, s35, 0
	s_add_i32 s70, s57, s41
	global_load_lds_dwordx4 v[218:219], off
	v_lshl_add_u64 v[220:221], s[68:69], 0, v[132:133]
	s_mov_b32 m0, s70
	v_lshl_add_u64 v[222:223], s[36:37], 0, v[134:135]
	global_load_lds_dwordx4 v[220:221], off
	v_lshl_add_u64 v[220:221], s[68:69], 0, v[136:137]
	s_add_i32 m0, s70, 0x2000
	s_nop 0
	global_load_lds_dwordx4 v[220:221], off
	v_lshl_add_u64 v[220:221], s[36:37], 0, v[130:131]
	s_mov_b32 m0, s29
	s_nop 0
	global_load_lds_dwordx4 v[220:221], off
	s_mov_b32 m0, s44
	s_nop 0
	global_load_lds_dwordx4 v[222:223], off
	s_cmp_lg_u32 s100, 0
	s_cbranch_scc1 .Lrw1_1a
	s_waitcnt vmcnt(8)
	s_branch .Lrw1_1b

.Lrw1_1b:
	s_waitcnt lgkmcnt(0)
	s_barrier
	s_setprio 1
	s_waitcnt lgkmcnt(0)
	v_mfma_f32_16x16x32_bf16 v[62:65], v[154:157], v[186:189], v[62:65]
	v_mfma_f32_16x16x32_bf16 v[58:61], v[162:165], v[186:189], v[58:61]
	v_mfma_f32_16x16x32_bf16 v[46:49], v[154:157], v[194:197], v[46:49]
	v_mfma_f32_16x16x32_bf16 v[42:45], v[162:165], v[194:197], v[42:45]
	v_mfma_f32_16x16x32_bf16 v[30:33], v[154:157], v[202:205], v[30:33]
	v_mfma_f32_16x16x32_bf16 v[26:29], v[162:165], v[202:205], v[26:29]
	v_mfma_f32_16x16x32_bf16 v[14:17], v[154:157], v[210:213], v[14:17]
	v_mfma_f32_16x16x32_bf16 v[10:13], v[162:165], v[210:213], v[10:13]
	v_mfma_f32_16x16x32_bf16 v[62:65], v[158:161], v[190:193], v[62:65]
	v_mfma_f32_16x16x32_bf16 v[58:61], v[166:169], v[190:193], v[58:61]
	v_mfma_f32_16x16x32_bf16 v[46:49], v[158:161], v[198:201], v[46:49]
	v_mfma_f32_16x16x32_bf16 v[42:45], v[166:169], v[198:201], v[42:45]
	v_mfma_f32_16x16x32_bf16 v[30:33], v[158:161], v[206:209], v[30:33]
	v_mfma_f32_16x16x32_bf16 v[26:29], v[166:169], v[206:209], v[26:29]
	v_mfma_f32_16x16x32_bf16 v[14:17], v[158:161], v[214:217], v[14:17]
	v_mfma_f32_16x16x32_bf16 v[10:13], v[166:169], v[214:217], v[10:13]
	s_setprio 0
	s_setprio 1
	v_mfma_f32_16x16x32_bf16 v[54:57], v[170:173], v[186:189], v[54:57]
	v_mfma_f32_16x16x32_bf16 v[50:53], v[178:181], v[186:189], v[50:53]
	v_mfma_f32_16x16x32_bf16 v[38:41], v[170:173], v[194:197], v[38:41]
	v_mfma_f32_16x16x32_bf16 v[34:37], v[178:181], v[194:197], v[34:37]
	v_mfma_f32_16x16x32_bf16 v[22:25], v[170:173], v[202:205], v[22:25]
	v_mfma_f32_16x16x32_bf16 v[18:21], v[178:181], v[202:205], v[18:21]
	v_mfma_f32_16x16x32_bf16 v[6:9], v[170:173], v[210:213], v[6:9]
	v_mfma_f32_16x16x32_bf16 v[2:5], v[178:181], v[210:213], v[2:5]
	v_mfma_f32_16x16x32_bf16 v[54:57], v[174:177], v[190:193], v[54:57]
	v_mfma_f32_16x16x32_bf16 v[50:53], v[182:185], v[190:193], v[50:53]
	v_mfma_f32_16x16x32_bf16 v[38:41], v[174:177], v[198:201], v[38:41]
	v_mfma_f32_16x16x32_bf16 v[34:37], v[182:185], v[198:201], v[34:37]
	v_mfma_f32_16x16x32_bf16 v[22:25], v[174:177], v[206:209], v[22:25]
	v_mfma_f32_16x16x32_bf16 v[18:21], v[182:185], v[206:209], v[18:21]
	v_mfma_f32_16x16x32_bf16 v[6:9], v[174:177], v[214:217], v[6:9]
	v_mfma_f32_16x16x32_bf16 v[2:5], v[182:185], v[214:217], v[2:5]
	s_setprio 0
	s_barrier
	s_add_i32 s68, 0, 0x18000
	v_add_u32_e32 v153, s68, v148
	s_add_i32 s69, 0, 0x1c000
	ds_read_b128 v[154:157], v153
	ds_read_b128 v[158:161], v153 offset:1024
	ds_read_b128 v[162:165], v153 offset:2048
	ds_read_b128 v[166:169], v153 offset:3072
	v_add_u32_e32 v153, s69, v148
	ds_read_b128 v[170:173], v153
	ds_read_b128 v[174:177], v153 offset:1024
	ds_read_b128 v[178:181], v153 offset:2048
	ds_read_b128 v[182:185], v153 offset:3072
	s_add_u32 s36, s36, 0x40000
	s_addc_u32 s37, s37, 0
	s_mov_b32 m0, s45
	v_lshl_add_u64 v[224:225], s[36:37], 0, v[130:131]
	ds_read_b128 v[186:189], v152 offset:32768
	ds_read_b128 v[190:193], v152 offset:33792
	ds_read_b128 v[194:197], v152 offset:34816
	ds_read_b128 v[198:201], v152 offset:35840
	ds_read_b128 v[202:205], v152 offset:36864
	ds_read_b128 v[206:209], v152 offset:37888
	ds_read_b128 v[210:213], v152 offset:38912
	ds_read_b128 v[214:217], v152 offset:39936
	global_load_lds_dwordx4 v[224:225], off
	v_lshl_add_u64 v[224:225], s[36:37], 0, v[134:135]
	s_mov_b32 m0, s46
	s_nop 0
	global_load_lds_dwordx4 v[224:225], off
	s_waitcnt vmcnt(8)
	s_waitcnt lgkmcnt(0)
	s_barrier
	s_setprio 1
	s_waitcnt lgkmcnt(0)
	v_mfma_f32_16x16x32_bf16 v[126:129], v[154:157], v[186:189], v[126:129]
	v_mfma_f32_16x16x32_bf16 v[122:125], v[162:165], v[186:189], v[122:125]
	v_mfma_f32_16x16x32_bf16 v[110:113], v[154:157], v[194:197], v[110:113]
	v_mfma_f32_16x16x32_bf16 v[106:109], v[162:165], v[194:197], v[106:109]
	v_mfma_f32_16x16x32_bf16 v[94:97], v[154:157], v[202:205], v[94:97]
	v_mfma_f32_16x16x32_bf16 v[90:93], v[162:165], v[202:205], v[90:93]
	v_mfma_f32_16x16x32_bf16 v[78:81], v[154:157], v[210:213], v[78:81]
	v_mfma_f32_16x16x32_bf16 v[74:77], v[162:165], v[210:213], v[74:77]
	v_mfma_f32_16x16x32_bf16 v[126:129], v[158:161], v[190:193], v[126:129]
	v_mfma_f32_16x16x32_bf16 v[122:125], v[166:169], v[190:193], v[122:125]
	v_mfma_f32_16x16x32_bf16 v[110:113], v[158:161], v[198:201], v[110:113]
	v_mfma_f32_16x16x32_bf16 v[106:109], v[166:169], v[198:201], v[106:109]
	v_mfma_f32_16x16x32_bf16 v[94:97], v[158:161], v[206:209], v[94:97]
	v_mfma_f32_16x16x32_bf16 v[90:93], v[166:169], v[206:209], v[90:93]
	v_mfma_f32_16x16x32_bf16 v[78:81], v[158:161], v[214:217], v[78:81]
	v_mfma_f32_16x16x32_bf16 v[74:77], v[166:169], v[214:217], v[74:77]
	s_setprio 0
	s_setprio 1
	v_mfma_f32_16x16x32_bf16 v[118:121], v[170:173], v[186:189], v[118:121]
	v_mfma_f32_16x16x32_bf16 v[114:117], v[178:181], v[186:189], v[114:117]
	v_mfma_f32_16x16x32_bf16 v[102:105], v[170:173], v[194:197], v[102:105]
	v_mfma_f32_16x16x32_bf16 v[98:101], v[178:181], v[194:197], v[98:101]
	v_mfma_f32_16x16x32_bf16 v[86:89], v[170:173], v[202:205], v[86:89]
	v_mfma_f32_16x16x32_bf16 v[82:85], v[178:181], v[202:205], v[82:85]
	v_mfma_f32_16x16x32_bf16 v[70:73], v[170:173], v[210:213], v[70:73]
	v_mfma_f32_16x16x32_bf16 v[66:69], v[178:181], v[210:213], v[66:69]
	v_mfma_f32_16x16x32_bf16 v[118:121], v[174:177], v[190:193], v[118:121]
	v_mfma_f32_16x16x32_bf16 v[114:117], v[182:185], v[190:193], v[114:117]
	v_mfma_f32_16x16x32_bf16 v[102:105], v[174:177], v[198:201], v[102:105]
	v_mfma_f32_16x16x32_bf16 v[98:101], v[182:185], v[198:201], v[98:101]
	v_mfma_f32_16x16x32_bf16 v[86:89], v[174:177], v[206:209], v[86:89]
	v_mfma_f32_16x16x32_bf16 v[82:85], v[182:185], v[206:209], v[82:85]
	v_mfma_f32_16x16x32_bf16 v[70:73], v[174:177], v[214:217], v[70:73]
	v_mfma_f32_16x16x32_bf16 v[66:69], v[182:185], v[214:217], v[66:69]
	s_setprio 0
	s_barrier
	s_add_i32 s36, s68, s41
	v_lshl_add_u64 v[146:147], v[146:147], 0, s[8:9]
	s_mov_b32 m0, s36
	ds_read_b128 v[186:189], v152 offset:49152
	ds_read_b128 v[190:193], v152 offset:50176
	ds_read_b128 v[194:197], v152 offset:51200
	ds_read_b128 v[198:201], v152 offset:52224
	ds_read_b128 v[202:205], v152 offset:53248
	ds_read_b128 v[206:209], v152 offset:54272
	ds_read_b128 v[210:213], v152 offset:55296
	ds_read_b128 v[214:217], v152 offset:56320
	global_load_lds_dwordx4 v[146:147], off
	s_add_i32 m0, s36, 0x2000
	s_add_u32 s34, s34, 0x40080
	v_lshl_add_u64 v[146:147], v[218:219], 0, s[8:9]
	s_addc_u32 s35, s35, 0
	s_add_i32 s36, s69, s41
	global_load_lds_dwordx4 v[146:147], off
	v_lshl_add_u64 v[146:147], s[34:35], 0, v[132:133]
	s_mov_b32 m0, s36
	s_nop 0
	global_load_lds_dwordx4 v[146:147], off
	v_lshl_add_u64 v[146:147], s[34:35], 0, v[136:137]
	s_add_i32 m0, s36, 0x2000
	s_nop 0
	global_load_lds_dwordx4 v[146:147], off
	v_lshl_add_u64 v[146:147], v[220:221], 0, s[8:9]
	s_mov_b32 m0, s52
	s_nop 0
	global_load_lds_dwordx4 v[146:147], off
	v_lshl_add_u64 v[146:147], v[222:223], 0, s[8:9]
	s_mov_b32 m0, s53
	s_nop 0
	global_load_lds_dwordx4 v[146:147], off
	s_waitcnt vmcnt(8)
	s_waitcnt lgkmcnt(0)
	s_barrier
	s_setprio 1
	s_waitcnt lgkmcnt(0)
	v_mfma_f32_16x16x32_bf16 v[62:65], v[154:157], v[186:189], v[62:65]
	v_mfma_f32_16x16x32_bf16 v[58:61], v[162:165], v[186:189], v[58:61]
	v_mfma_f32_16x16x32_bf16 v[46:49], v[154:157], v[194:197], v[46:49]
	v_mfma_f32_16x16x32_bf16 v[42:45], v[162:165], v[194:197], v[42:45]
	v_mfma_f32_16x16x32_bf16 v[30:33], v[154:157], v[202:205], v[30:33]
	v_mfma_f32_16x16x32_bf16 v[26:29], v[162:165], v[202:205], v[26:29]
	v_mfma_f32_16x16x32_bf16 v[14:17], v[154:157], v[210:213], v[14:17]
	v_mfma_f32_16x16x32_bf16 v[10:13], v[162:165], v[210:213], v[10:13]
	v_mfma_f32_16x16x32_bf16 v[62:65], v[158:161], v[190:193], v[62:65]
	v_mfma_f32_16x16x32_bf16 v[58:61], v[166:169], v[190:193], v[58:61]
	v_mfma_f32_16x16x32_bf16 v[46:49], v[158:161], v[198:201], v[46:49]
	v_mfma_f32_16x16x32_bf16 v[42:45], v[166:169], v[198:201], v[42:45]
	v_mfma_f32_16x16x32_bf16 v[30:33], v[158:161], v[206:209], v[30:33]
	v_mfma_f32_16x16x32_bf16 v[26:29], v[166:169], v[206:209], v[26:29]
	v_mfma_f32_16x16x32_bf16 v[14:17], v[158:161], v[214:217], v[14:17]
	v_mfma_f32_16x16x32_bf16 v[10:13], v[166:169], v[214:217], v[10:13]
	s_setprio 0
	s_setprio 1
	v_mfma_f32_16x16x32_bf16 v[54:57], v[170:173], v[186:189], v[54:57]
	v_mfma_f32_16x16x32_bf16 v[50:53], v[178:181], v[186:189], v[50:53]
	v_mfma_f32_16x16x32_bf16 v[38:41], v[170:173], v[194:197], v[38:41]
	v_mfma_f32_16x16x32_bf16 v[34:37], v[178:181], v[194:197], v[34:37]
	v_mfma_f32_16x16x32_bf16 v[22:25], v[170:173], v[202:205], v[22:25]
	v_mfma_f32_16x16x32_bf16 v[18:21], v[178:181], v[202:205], v[18:21]
	v_mfma_f32_16x16x32_bf16 v[6:9], v[170:173], v[210:213], v[6:9]
	v_mfma_f32_16x16x32_bf16 v[2:5], v[178:181], v[210:213], v[2:5]
	v_mfma_f32_16x16x32_bf16 v[54:57], v[174:177], v[190:193], v[54:57]
	v_mfma_f32_16x16x32_bf16 v[50:53], v[182:185], v[190:193], v[50:53]
	v_mfma_f32_16x16x32_bf16 v[38:41], v[174:177], v[198:201], v[38:41]
	v_mfma_f32_16x16x32_bf16 v[34:37], v[182:185], v[198:201], v[34:37]
	v_mfma_f32_16x16x32_bf16 v[22:25], v[174:177], v[206:209], v[22:25]
	v_mfma_f32_16x16x32_bf16 v[18:21], v[182:185], v[206:209], v[18:21]
	v_mfma_f32_16x16x32_bf16 v[6:9], v[174:177], v[214:217], v[6:9]
	v_mfma_f32_16x16x32_bf16 v[2:5], v[182:185], v[214:217], v[2:5]
	s_setprio 0
	s_barrier
	s_add_i32 s67, s67, 2
	s_add_u32 s30, s30, 0x100
	s_addc_u32 s31, s31, 0
	s_add_u32 s65, s65, 0x100
	s_addc_u32 s66, s66, 0
	s_mov_b32 s100, 0
	s_cmp_gt_u32 s67, 13
	s_cbranch_scc0 .LBB0_653
	s_and_b64 vcc, exec, s[10:11]
	s_cbranch_vccz .LBB0_656
	s_barrier
.LBB0_656:
	v_max_f32_e32 v122, v122, v122
	v_lshl_add_u32 v154, s28, 8, v1
	v_max_f32_e32 v122, 0, v122
	v_max_f32_e32 v123, v123, v123
	v_max_f32_e32 v124, v124, v124
	v_lshl_or_b32 v146, s62, 8, v149
	v_ashrrev_i32_e32 v155, 31, v154
	v_mul_f32_e32 v153, v122, v122
	v_max_f32_e32 v122, v127, v127
	v_max_f32_e32 v123, 0, v123
	v_max_f32_e32 v124, 0, v124
	v_ashrrev_i32_e32 v147, 31, v146
	v_lshlrev_b64 v[156:157], 13, v[154:155]
	v_max_f32_e32 v126, v126, v126
	v_max_f32_e32 v122, 0, v122
	v_mul_f32_e32 v127, v123, v123
	v_max_f32_e32 v123, v128, v128
	v_mul_f32_e32 v128, v124, v124
	v_max_f32_e32 v124, v129, v129
	v_max_f32_e32 v125, v125, v125
	v_lshl_add_u64 v[156:157], s[6:7], 0, v[156:157]
	v_lshlrev_b64 v[158:159], 1, v[146:147]
	v_max_f32_e32 v126, 0, v126
	v_mul_f32_e32 v122, v122, v122
	v_max_f32_e32 v123, 0, v123
	v_max_f32_e32 v124, 0, v124
	v_max_f32_e32 v125, 0, v125
	v_max_f32_e32 v114, v114, v114
	v_lshl_add_u64 v[146:147], v[156:157], 0, v[158:159]
	v_mul_f32_e32 v126, v126, v126
	v_mul_f32_e32 v123, v123, v123
	v_mul_f32_e32 v124, v124, v124
	v_mul_f32_e32 v125, v125, v125
	v_cvt_pk_bf16_f32 v122, v126, v122
	v_max_f32_e32 v114, 0, v114
	v_max_f32_e32 v115, v115, v115
	v_max_f32_e32 v116, v116, v116
	v_cvt_pk_bf16_f32 v123, v123, v124
	v_cvt_pk_bf16_f32 v124, v153, v127
	v_cvt_pk_bf16_f32 v125, v128, v125
	global_store_dwordx4 v[146:147], v[122:125], off
	v_max_f32_e32 v115, 0, v115
	v_max_f32_e32 v116, 0, v116
	v_mul_f32_e32 v122, v114, v114
	v_max_f32_e32 v114, v119, v119
	v_max_f32_e32 v118, v118, v118
	v_max_f32_e32 v114, 0, v114
	v_mul_f32_e32 v119, v115, v115
	v_max_f32_e32 v115, v120, v120
	v_mul_f32_e32 v120, v116, v116
	v_max_f32_e32 v116, v121, v121
	v_max_f32_e32 v117, v117, v117
	v_max_f32_e32 v118, 0, v118
	v_mul_f32_e32 v114, v114, v114
	v_max_f32_e32 v115, 0, v115
	v_max_f32_e32 v116, 0, v116
	v_max_f32_e32 v117, 0, v117
	v_mul_f32_e32 v118, v118, v118
	v_mul_f32_e32 v115, v115, v115
	v_mul_f32_e32 v116, v116, v116
	v_mul_f32_e32 v117, v117, v117
	v_cvt_pk_bf16_f32 v114, v118, v114
	v_max_f32_e32 v106, v106, v106
	v_cvt_pk_bf16_f32 v115, v115, v116
	v_cvt_pk_bf16_f32 v116, v122, v119
	v_cvt_pk_bf16_f32 v117, v120, v117
	global_store_dwordx4 v[146:147], v[114:117], off offset:256
	v_max_f32_e32 v106, 0, v106
	v_max_f32_e32 v107, v107, v107
	v_or_b32_e32 v114, 16, v154
	v_max_f32_e32 v108, v108, v108
	v_ashrrev_i32_e32 v115, 31, v114
	v_mul_f32_e32 v116, v106, v106
	v_max_f32_e32 v106, v111, v111
	v_max_f32_e32 v107, 0, v107
	v_max_f32_e32 v108, 0, v108
	v_lshlrev_b64 v[114:115], 13, v[114:115]
	v_max_f32_e32 v110, v110, v110
	v_max_f32_e32 v106, 0, v106
	v_mul_f32_e32 v111, v107, v107
	v_max_f32_e32 v107, v112, v112
	v_mul_f32_e32 v112, v108, v108
	v_max_f32_e32 v108, v113, v113
	v_max_f32_e32 v109, v109, v109
	v_lshl_add_u64 v[114:115], s[6:7], 0, v[114:115]
	v_max_f32_e32 v110, 0, v110
	v_mul_f32_e32 v106, v106, v106
	v_max_f32_e32 v107, 0, v107
	v_max_f32_e32 v108, 0, v108
	v_max_f32_e32 v109, 0, v109
	v_max_f32_e32 v98, v98, v98
	v_lshl_add_u64 v[114:115], v[114:115], 0, v[158:159]
	v_mul_f32_e32 v110, v110, v110
	v_mul_f32_e32 v107, v107, v107
	v_mul_f32_e32 v108, v108, v108
	v_mul_f32_e32 v109, v109, v109
	v_cvt_pk_bf16_f32 v106, v110, v106
	v_max_f32_e32 v98, 0, v98
	v_max_f32_e32 v99, v99, v99
	v_max_f32_e32 v100, v100, v100
	v_cvt_pk_bf16_f32 v107, v107, v108
	v_cvt_pk_bf16_f32 v108, v116, v111
	v_cvt_pk_bf16_f32 v109, v112, v109
	global_store_dwordx4 v[114:115], v[106:109], off
	v_max_f32_e32 v99, 0, v99
	v_max_f32_e32 v100, 0, v100
	v_mul_f32_e32 v106, v98, v98
	v_max_f32_e32 v98, v103, v103
	v_max_f32_e32 v102, v102, v102
	v_max_f32_e32 v98, 0, v98
	v_mul_f32_e32 v103, v99, v99
	v_max_f32_e32 v99, v104, v104
	v_mul_f32_e32 v104, v100, v100
	v_max_f32_e32 v100, v105, v105
	v_max_f32_e32 v101, v101, v101
	v_max_f32_e32 v102, 0, v102
	v_mul_f32_e32 v98, v98, v98
	v_max_f32_e32 v99, 0, v99
	v_max_f32_e32 v100, 0, v100
	v_max_f32_e32 v101, 0, v101
	v_mul_f32_e32 v102, v102, v102
	v_mul_f32_e32 v99, v99, v99
	v_mul_f32_e32 v100, v100, v100
	v_mul_f32_e32 v101, v101, v101
	v_cvt_pk_bf16_f32 v98, v102, v98
	v_max_f32_e32 v90, v90, v90
	v_cvt_pk_bf16_f32 v99, v99, v100
	v_cvt_pk_bf16_f32 v100, v106, v103
	v_cvt_pk_bf16_f32 v101, v104, v101
	global_store_dwordx4 v[114:115], v[98:101], off offset:256
	v_max_f32_e32 v90, 0, v90
	v_max_f32_e32 v91, v91, v91
	v_or_b32_e32 v98, 32, v154
	v_max_f32_e32 v92, v92, v92
	v_ashrrev_i32_e32 v99, 31, v98
	v_mul_f32_e32 v100, v90, v90
	v_max_f32_e32 v90, v95, v95
	v_max_f32_e32 v91, 0, v91
	v_max_f32_e32 v92, 0, v92
	v_lshlrev_b64 v[98:99], 13, v[98:99]
	v_max_f32_e32 v94, v94, v94
	v_max_f32_e32 v90, 0, v90
	v_mul_f32_e32 v95, v91, v91
	v_max_f32_e32 v91, v96, v96
	v_mul_f32_e32 v96, v92, v92
	v_max_f32_e32 v92, v97, v97
	v_max_f32_e32 v93, v93, v93
	v_lshl_add_u64 v[98:99], s[6:7], 0, v[98:99]
	v_max_f32_e32 v94, 0, v94
	v_mul_f32_e32 v90, v90, v90
	v_max_f32_e32 v91, 0, v91
	v_max_f32_e32 v92, 0, v92
	v_max_f32_e32 v93, 0, v93
	v_max_f32_e32 v82, v82, v82
	v_lshl_add_u64 v[98:99], v[98:99], 0, v[158:159]
	v_mul_f32_e32 v94, v94, v94
	v_mul_f32_e32 v91, v91, v91
	v_mul_f32_e32 v92, v92, v92
	v_mul_f32_e32 v93, v93, v93
	v_cvt_pk_bf16_f32 v90, v94, v90
	v_max_f32_e32 v82, 0, v82
	v_max_f32_e32 v83, v83, v83
	v_max_f32_e32 v84, v84, v84
	v_cvt_pk_bf16_f32 v91, v91, v92
	v_cvt_pk_bf16_f32 v92, v100, v95
	v_cvt_pk_bf16_f32 v93, v96, v93
	global_store_dwordx4 v[98:99], v[90:93], off
	v_max_f32_e32 v83, 0, v83
	v_max_f32_e32 v84, 0, v84
	v_mul_f32_e32 v90, v82, v82
	v_max_f32_e32 v82, v87, v87
	v_max_f32_e32 v86, v86, v86
	v_max_f32_e32 v82, 0, v82
	v_mul_f32_e32 v87, v83, v83
	v_max_f32_e32 v83, v88, v88
	v_mul_f32_e32 v88, v84, v84
	v_max_f32_e32 v84, v89, v89
	v_max_f32_e32 v85, v85, v85
	v_max_f32_e32 v86, 0, v86
	v_mul_f32_e32 v82, v82, v82
	v_max_f32_e32 v83, 0, v83
	v_max_f32_e32 v84, 0, v84
	v_max_f32_e32 v85, 0, v85
	v_mul_f32_e32 v86, v86, v86
	v_mul_f32_e32 v83, v83, v83
	v_mul_f32_e32 v84, v84, v84
	v_mul_f32_e32 v85, v85, v85
	v_cvt_pk_bf16_f32 v82, v86, v82
	v_max_f32_e32 v74, v74, v74
	v_cvt_pk_bf16_f32 v83, v83, v84
	v_cvt_pk_bf16_f32 v84, v90, v87
	v_cvt_pk_bf16_f32 v85, v88, v85
	global_store_dwordx4 v[98:99], v[82:85], off offset:256
	v_max_f32_e32 v74, 0, v74
	v_max_f32_e32 v75, v75, v75
	v_or_b32_e32 v82, 48, v154
	v_max_f32_e32 v76, v76, v76
	v_ashrrev_i32_e32 v83, 31, v82
	v_mul_f32_e32 v84, v74, v74
	v_max_f32_e32 v74, v79, v79
	v_max_f32_e32 v75, 0, v75
	v_max_f32_e32 v76, 0, v76
	v_lshlrev_b64 v[82:83], 13, v[82:83]
	v_max_f32_e32 v78, v78, v78
	v_max_f32_e32 v74, 0, v74
	v_mul_f32_e32 v79, v75, v75
	v_max_f32_e32 v75, v80, v80
	v_mul_f32_e32 v80, v76, v76
	v_max_f32_e32 v76, v81, v81
	v_max_f32_e32 v77, v77, v77
	v_lshl_add_u64 v[82:83], s[6:7], 0, v[82:83]
	v_max_f32_e32 v78, 0, v78
	v_mul_f32_e32 v74, v74, v74
	v_max_f32_e32 v75, 0, v75
	v_max_f32_e32 v76, 0, v76
	v_max_f32_e32 v77, 0, v77
	v_max_f32_e32 v66, v66, v66
	v_max_f32_e32 v67, v67, v67
	v_max_f32_e32 v68, v68, v68
	v_lshl_add_u64 v[82:83], v[82:83], 0, v[158:159]
	v_mul_f32_e32 v78, v78, v78
	v_mul_f32_e32 v75, v75, v75
	v_mul_f32_e32 v76, v76, v76
	v_mul_f32_e32 v77, v77, v77
	v_cvt_pk_bf16_f32 v74, v78, v74
	v_max_f32_e32 v66, 0, v66
	v_max_f32_e32 v67, 0, v67
	v_max_f32_e32 v68, 0, v68
	v_cvt_pk_bf16_f32 v75, v75, v76
	v_cvt_pk_bf16_f32 v76, v84, v79
	v_cvt_pk_bf16_f32 v77, v80, v77
	global_store_dwordx4 v[82:83], v[74:77], off
	v_max_f32_e32 v70, v70, v70
	v_max_f32_e32 v69, v69, v69
	v_mul_f32_e32 v74, v66, v66
	v_max_f32_e32 v66, v71, v71
	v_mul_f32_e32 v71, v67, v67
	v_max_f32_e32 v67, v72, v72
	v_mul_f32_e32 v72, v68, v68
	v_max_f32_e32 v68, v73, v73
	v_max_f32_e32 v66, 0, v66
	v_max_f32_e32 v67, 0, v67
	v_max_f32_e32 v68, 0, v68
	v_max_f32_e32 v70, 0, v70
	v_mul_f32_e32 v66, v66, v66
	v_mul_f32_e32 v67, v67, v67
	v_max_f32_e32 v69, 0, v69
	v_mul_f32_e32 v68, v68, v68
	v_max_f32_e32 v58, v58, v58
	v_mul_f32_e32 v70, v70, v70
	v_mul_f32_e32 v69, v69, v69
	v_cvt_pk_bf16_f32 v66, v70, v66
	v_cvt_pk_bf16_f32 v67, v67, v68
	v_cvt_pk_bf16_f32 v68, v74, v71
	v_max_f32_e32 v58, 0, v58
	v_max_f32_e32 v59, v59, v59
	v_max_f32_e32 v60, v60, v60
	v_cvt_pk_bf16_f32 v69, v72, v69
	global_store_dwordx4 v[82:83], v[66:69], off offset:256
	v_max_f32_e32 v62, v62, v62
	v_max_f32_e32 v59, 0, v59
	v_mul_f32_e32 v68, v58, v58
	v_max_f32_e32 v58, v63, v63
	v_max_f32_e32 v60, 0, v60
	v_max_f32_e32 v62, 0, v62
	v_max_f32_e32 v58, 0, v58
	v_mul_f32_e32 v63, v59, v59
	v_max_f32_e32 v59, v64, v64
	v_mul_f32_e32 v64, v60, v60
	v_max_f32_e32 v60, v65, v65
	v_mul_f32_e32 v62, v62, v62
	v_mul_f32_e32 v58, v58, v58
	v_max_f32_e32 v59, 0, v59
	v_max_f32_e32 v60, 0, v60
	v_max_f32_e32 v61, v61, v61
	v_mul_f32_e32 v59, v59, v59
	v_max_f32_e32 v61, 0, v61
	v_mul_f32_e32 v60, v60, v60
	v_cvt_pk_bf16_f32 v58, v62, v58
	v_add_co_u32_e32 v62, vcc, s58, v146
	v_max_f32_e32 v50, v50, v50
	v_max_f32_e32 v51, v51, v51
	v_max_f32_e32 v52, v52, v52
	v_mul_f32_e32 v61, v61, v61
	v_cvt_pk_bf16_f32 v59, v59, v60
	v_cvt_pk_bf16_f32 v60, v68, v63
	v_addc_co_u32_e32 v63, vcc, 0, v147, vcc
	v_max_f32_e32 v50, 0, v50
	v_max_f32_e32 v51, 0, v51
	v_max_f32_e32 v52, 0, v52
	v_cvt_pk_bf16_f32 v61, v64, v61
	global_store_dwordx4 v[62:63], v[58:61], off
	v_max_f32_e32 v54, v54, v54
	v_max_f32_e32 v53, v53, v53
	v_mul_f32_e32 v58, v50, v50
	v_max_f32_e32 v50, v55, v55
	v_mul_f32_e32 v55, v51, v51
	v_max_f32_e32 v51, v56, v56
	v_mul_f32_e32 v56, v52, v52
	v_max_f32_e32 v52, v57, v57
	v_max_f32_e32 v50, 0, v50
	v_max_f32_e32 v51, 0, v51
	v_max_f32_e32 v52, 0, v52
	v_max_f32_e32 v54, 0, v54
	v_mul_f32_e32 v50, v50, v50
	v_mul_f32_e32 v51, v51, v51
	v_max_f32_e32 v53, 0, v53
	v_mul_f32_e32 v52, v52, v52
	v_max_f32_e32 v42, v42, v42
	v_lshl_add_u64 v[66:67], v[146:147], 0, s[12:13]
	v_mul_f32_e32 v54, v54, v54
	v_mul_f32_e32 v53, v53, v53
	v_cvt_pk_bf16_f32 v50, v54, v50
	v_cvt_pk_bf16_f32 v51, v51, v52
	v_cvt_pk_bf16_f32 v52, v58, v55
	v_max_f32_e32 v42, 0, v42
	v_max_f32_e32 v43, v43, v43
	v_max_f32_e32 v44, v44, v44
	v_cvt_pk_bf16_f32 v53, v56, v53
	global_store_dwordx4 v[66:67], v[50:53], off offset:256
	v_max_f32_e32 v46, v46, v46
	v_max_f32_e32 v43, 0, v43
	v_mul_f32_e32 v52, v42, v42
	v_max_f32_e32 v42, v47, v47
	v_max_f32_e32 v44, 0, v44
	v_max_f32_e32 v46, 0, v46
	v_max_f32_e32 v42, 0, v42
	v_mul_f32_e32 v47, v43, v43
	v_max_f32_e32 v43, v48, v48
	v_mul_f32_e32 v48, v44, v44
	v_max_f32_e32 v44, v49, v49
	v_mul_f32_e32 v46, v46, v46
	v_mul_f32_e32 v42, v42, v42
	v_max_f32_e32 v43, 0, v43
	v_max_f32_e32 v44, 0, v44
	v_max_f32_e32 v45, v45, v45
	v_mul_f32_e32 v43, v43, v43
	v_max_f32_e32 v45, 0, v45
	v_mul_f32_e32 v44, v44, v44
	v_cvt_pk_bf16_f32 v42, v46, v42
	v_add_co_u32_e32 v46, vcc, s59, v146
	v_max_f32_e32 v34, v34, v34
	v_max_f32_e32 v35, v35, v35
	v_max_f32_e32 v36, v36, v36
	v_mul_f32_e32 v45, v45, v45
	v_cvt_pk_bf16_f32 v43, v43, v44
	v_cvt_pk_bf16_f32 v44, v52, v47
	v_addc_co_u32_e32 v47, vcc, 0, v147, vcc
	v_max_f32_e32 v34, 0, v34
	v_max_f32_e32 v35, 0, v35
	v_max_f32_e32 v36, 0, v36
	v_cvt_pk_bf16_f32 v45, v48, v45
	global_store_dwordx4 v[46:47], v[42:45], off
	v_max_f32_e32 v38, v38, v38
	v_max_f32_e32 v37, v37, v37
	v_mul_f32_e32 v42, v34, v34
	v_max_f32_e32 v34, v39, v39
	v_mul_f32_e32 v39, v35, v35
	v_max_f32_e32 v35, v40, v40
	v_mul_f32_e32 v40, v36, v36
	v_max_f32_e32 v36, v41, v41
	v_max_f32_e32 v34, 0, v34
	v_max_f32_e32 v35, 0, v35
	v_max_f32_e32 v36, 0, v36
	v_max_f32_e32 v38, 0, v38
	v_mul_f32_e32 v34, v34, v34
	v_mul_f32_e32 v35, v35, v35
	v_max_f32_e32 v37, 0, v37
	v_mul_f32_e32 v36, v36, v36
	v_max_f32_e32 v26, v26, v26
	v_lshl_add_u64 v[50:51], v[146:147], 0, s[14:15]
	v_mul_f32_e32 v38, v38, v38
	v_mul_f32_e32 v37, v37, v37
	v_cvt_pk_bf16_f32 v34, v38, v34
	v_cvt_pk_bf16_f32 v35, v35, v36
	v_cvt_pk_bf16_f32 v36, v42, v39
	v_max_f32_e32 v26, 0, v26
	v_max_f32_e32 v27, v27, v27
	v_max_f32_e32 v28, v28, v28
	v_cvt_pk_bf16_f32 v37, v40, v37
	global_store_dwordx4 v[50:51], v[34:37], off offset:256
	v_max_f32_e32 v30, v30, v30
	v_max_f32_e32 v27, 0, v27
	v_mul_f32_e32 v36, v26, v26
	v_max_f32_e32 v26, v31, v31
	v_max_f32_e32 v28, 0, v28
	v_max_f32_e32 v30, 0, v30
	v_max_f32_e32 v26, 0, v26
	v_mul_f32_e32 v31, v27, v27
	v_max_f32_e32 v27, v32, v32
	v_mul_f32_e32 v32, v28, v28
	v_max_f32_e32 v28, v33, v33
	v_mul_f32_e32 v30, v30, v30
	v_mul_f32_e32 v26, v26, v26
	v_max_f32_e32 v27, 0, v27
	v_max_f32_e32 v28, 0, v28
	v_max_f32_e32 v29, v29, v29
	v_mul_f32_e32 v27, v27, v27
	v_max_f32_e32 v29, 0, v29
	v_mul_f32_e32 v28, v28, v28
	v_cvt_pk_bf16_f32 v26, v30, v26
	v_add_co_u32_e32 v30, vcc, s60, v146
	v_max_f32_e32 v18, v18, v18
	v_max_f32_e32 v19, v19, v19
	v_max_f32_e32 v20, v20, v20
	v_mul_f32_e32 v29, v29, v29
	v_cvt_pk_bf16_f32 v27, v27, v28
	v_cvt_pk_bf16_f32 v28, v36, v31
	v_addc_co_u32_e32 v31, vcc, 0, v147, vcc
	v_max_f32_e32 v18, 0, v18
	v_max_f32_e32 v19, 0, v19
	v_max_f32_e32 v20, 0, v20
	v_cvt_pk_bf16_f32 v29, v32, v29
	global_store_dwordx4 v[30:31], v[26:29], off
	v_max_f32_e32 v22, v22, v22
	v_max_f32_e32 v21, v21, v21
	v_mul_f32_e32 v26, v18, v18
	v_max_f32_e32 v18, v23, v23
	v_mul_f32_e32 v23, v19, v19
	v_max_f32_e32 v19, v24, v24
	v_mul_f32_e32 v24, v20, v20
	v_max_f32_e32 v20, v25, v25
	v_max_f32_e32 v18, 0, v18
	v_max_f32_e32 v19, 0, v19
	v_max_f32_e32 v20, 0, v20
	v_max_f32_e32 v22, 0, v22
	v_mul_f32_e32 v18, v18, v18
	v_mul_f32_e32 v19, v19, v19
	v_max_f32_e32 v21, 0, v21
	v_mul_f32_e32 v20, v20, v20
	v_max_f32_e32 v10, v10, v10
	v_lshl_add_u64 v[34:35], v[146:147], 0, s[16:17]
	v_mul_f32_e32 v22, v22, v22
	v_mul_f32_e32 v21, v21, v21
	v_cvt_pk_bf16_f32 v18, v22, v18
	v_cvt_pk_bf16_f32 v19, v19, v20
	v_cvt_pk_bf16_f32 v20, v26, v23
	v_max_f32_e32 v10, 0, v10
	v_max_f32_e32 v11, v11, v11
	v_max_f32_e32 v12, v12, v12
	v_cvt_pk_bf16_f32 v21, v24, v21
	global_store_dwordx4 v[34:35], v[18:21], off offset:256
	v_max_f32_e32 v14, v14, v14
	v_max_f32_e32 v11, 0, v11
	v_mul_f32_e32 v20, v10, v10
	v_max_f32_e32 v10, v15, v15
	v_max_f32_e32 v12, 0, v12
	v_max_f32_e32 v14, 0, v14
	v_max_f32_e32 v10, 0, v10
	v_mul_f32_e32 v15, v11, v11
	v_max_f32_e32 v11, v16, v16
	v_mul_f32_e32 v16, v12, v12
	v_max_f32_e32 v12, v17, v17
	v_mul_f32_e32 v14, v14, v14
	v_mul_f32_e32 v10, v10, v10
	v_max_f32_e32 v11, 0, v11
	v_max_f32_e32 v12, 0, v12
	v_max_f32_e32 v13, v13, v13
	v_mul_f32_e32 v11, v11, v11
	v_max_f32_e32 v13, 0, v13
	v_mul_f32_e32 v12, v12, v12
	v_cvt_pk_bf16_f32 v10, v14, v10
	v_add_co_u32_e32 v14, vcc, s61, v146
	v_max_f32_e32 v2, v2, v2
	v_max_f32_e32 v3, v3, v3
	v_max_f32_e32 v4, v4, v4
	v_mul_f32_e32 v13, v13, v13
	v_cvt_pk_bf16_f32 v11, v11, v12
	v_cvt_pk_bf16_f32 v12, v20, v15
	v_addc_co_u32_e32 v15, vcc, 0, v147, vcc
	v_max_f32_e32 v2, 0, v2
	v_max_f32_e32 v3, 0, v3
	v_max_f32_e32 v4, 0, v4
	v_cvt_pk_bf16_f32 v13, v16, v13
	global_store_dwordx4 v[14:15], v[10:13], off
	v_max_f32_e32 v5, v5, v5
	v_max_f32_e32 v6, v6, v6
	v_mul_f32_e32 v10, v2, v2
	v_max_f32_e32 v2, v7, v7
	v_mul_f32_e32 v7, v3, v3
	v_max_f32_e32 v3, v8, v8
	v_mul_f32_e32 v8, v4, v4
	v_max_f32_e32 v4, v9, v9
	v_max_f32_e32 v2, 0, v2
	v_max_f32_e32 v3, 0, v3
	v_max_f32_e32 v4, 0, v4
	v_max_f32_e32 v5, 0, v5
	v_lshl_add_u64 v[18:19], v[146:147], 0, s[18:19]
	v_max_f32_e32 v6, 0, v6
	v_mul_f32_e32 v2, v2, v2
	v_mul_f32_e32 v3, v3, v3
	v_mul_f32_e32 v4, v4, v4
	v_mul_f32_e32 v5, v5, v5
	s_andn2_b64 vcc, exec, s[0:1]
	s_mov_b64 s[0:1], -1
	v_mul_f32_e32 v6, v6, v6
	v_cvt_pk_bf16_f32 v2, v6, v2
	v_cvt_pk_bf16_f32 v3, v3, v4
	v_cvt_pk_bf16_f32 v4, v10, v7
	v_cvt_pk_bf16_f32 v5, v8, v5
	global_store_dwordx4 v[18:19], v[2:5], off offset:256
	s_mov_b32 s100, 1
	s_cbranch_vccnz .LBB0_645
	s_andn2_b64 vcc, exec, s[4:5]
	s_cbranch_vccnz .LBB0_644
	s_barrier
	s_branch .LBB0_644

.LBB0_710:
	s_mov_b32 s100, 0
	s_cmp_lt_i32 s72, 10
	s_cselect_b64 s[0:1], -1, 0
	s_cmp_gt_i32 s73, 9
	s_cselect_b64 s[4:5], -1, 0
	s_and_b64 s[0:1], s[0:1], s[4:5]
	s_andn2_b64 vcc, exec, s[0:1]
	s_cbranch_vccnz .LBB0_785
	s_cmpk_gt_i32 s2, 0x1ff
	v_readfirstlane_b32 s10, v0
	s_cbranch_scc1 .LBB0_735
	s_ashr_i32 s3, s2, 31
	s_lshr_b32 s0, s3, 29
	s_add_i32 s5, s2, s0
	s_and_b32 s0, s5, -8
	s_sub_i32 s6, s2, s0
	s_cmp_gt_i32 s6, -1
	s_cbranch_scc0 .LBB0_714
	s_lshl_b32 s4, s6, 6
	s_cbranch_execz .LBB0_715
	s_branch .LBB0_716

.LBB0_728:
	ds_read_b128 v[154:157], v150
	ds_read_b128 v[158:161], v150 offset:1024
	ds_read_b128 v[162:165], v150 offset:2048
	ds_read_b128 v[166:169], v150 offset:3072
	ds_read_b128 v[170:173], v151
	ds_read_b128 v[174:177], v151 offset:1024
	ds_read_b128 v[178:181], v151 offset:2048
	ds_read_b128 v[182:185], v151 offset:3072
	s_add_u32 s34, s30, 0xfff00080
	s_addc_u32 s35, s31, -1
	s_cmp_eq_u32 s67, 60
	s_cselect_b32 s37, s23, s35
	s_cselect_b32 s36, s63, s34
	s_cselect_b32 s35, s21, s66
	s_cselect_b32 s34, s64, s65
	v_lshl_add_u64 v[146:147], s[30:31], 0, v[138:139]
	s_add_i32 m0, s29, 0xc000
	ds_read_b128 v[186:189], v152
	ds_read_b128 v[190:193], v152 offset:1024
	ds_read_b128 v[194:197], v152 offset:2048
	ds_read_b128 v[198:201], v152 offset:3072
	ds_read_b128 v[202:205], v152 offset:4096
	ds_read_b128 v[206:209], v152 offset:5120
	ds_read_b128 v[210:213], v152 offset:6144
	ds_read_b128 v[214:217], v152 offset:7168
	global_load_lds_dwordx4 v[146:147], off
	v_lshl_add_u64 v[146:147], s[30:31], 0, v[140:141]
	s_add_i32 m0, s29, 0xe000
	s_nop 0
	global_load_lds_dwordx4 v[146:147], off
	s_cmp_lg_u32 s100, 0
	s_cbranch_scc1 .Lrw2_0a
	s_waitcnt vmcnt(8)
	s_branch .Lrw2_0b

.Lrw2_0b:
	s_waitcnt lgkmcnt(0)
	s_barrier
	s_setprio 1
	s_waitcnt lgkmcnt(0)
	v_mfma_f32_16x16x32_bf16 v[126:129], v[154:157], v[186:189], v[126:129]
	v_mfma_f32_16x16x32_bf16 v[122:125], v[162:165], v[186:189], v[122:125]
	v_mfma_f32_16x16x32_bf16 v[118:121], v[154:157], v[194:197], v[118:121]
	v_mfma_f32_16x16x32_bf16 v[110:113], v[162:165], v[194:197], v[110:113]
	v_mfma_f32_16x16x32_bf16 v[102:105], v[154:157], v[202:205], v[102:105]
	v_mfma_f32_16x16x32_bf16 v[94:97], v[162:165], v[202:205], v[94:97]
	v_mfma_f32_16x16x32_bf16 v[86:89], v[154:157], v[210:213], v[86:89]
	v_mfma_f32_16x16x32_bf16 v[78:81], v[162:165], v[210:213], v[78:81]
	v_mfma_f32_16x16x32_bf16 v[126:129], v[158:161], v[190:193], v[126:129]
	v_mfma_f32_16x16x32_bf16 v[122:125], v[166:169], v[190:193], v[122:125]
	v_mfma_f32_16x16x32_bf16 v[118:121], v[158:161], v[198:201], v[118:121]
	v_mfma_f32_16x16x32_bf16 v[110:113], v[166:169], v[198:201], v[110:113]
	v_mfma_f32_16x16x32_bf16 v[102:105], v[158:161], v[206:209], v[102:105]
	v_mfma_f32_16x16x32_bf16 v[94:97], v[166:169], v[206:209], v[94:97]
	v_mfma_f32_16x16x32_bf16 v[86:89], v[158:161], v[214:217], v[86:89]
	v_mfma_f32_16x16x32_bf16 v[78:81], v[166:169], v[214:217], v[78:81]
	s_setprio 0
	s_setprio 1
	v_mfma_f32_16x16x32_bf16 v[114:117], v[170:173], v[186:189], v[114:117]
	v_mfma_f32_16x16x32_bf16 v[106:109], v[178:181], v[186:189], v[106:109]
	v_mfma_f32_16x16x32_bf16 v[98:101], v[170:173], v[194:197], v[98:101]
	v_mfma_f32_16x16x32_bf16 v[90:93], v[178:181], v[194:197], v[90:93]
	v_mfma_f32_16x16x32_bf16 v[82:85], v[170:173], v[202:205], v[82:85]
	v_mfma_f32_16x16x32_bf16 v[74:77], v[178:181], v[202:205], v[74:77]
	v_mfma_f32_16x16x32_bf16 v[70:73], v[170:173], v[210:213], v[70:73]
	v_mfma_f32_16x16x32_bf16 v[66:69], v[178:181], v[210:213], v[66:69]
	v_mfma_f32_16x16x32_bf16 v[114:117], v[174:177], v[190:193], v[114:117]
	v_mfma_f32_16x16x32_bf16 v[106:109], v[182:185], v[190:193], v[106:109]
	v_mfma_f32_16x16x32_bf16 v[98:101], v[174:177], v[198:201], v[98:101]
	v_mfma_f32_16x16x32_bf16 v[90:93], v[182:185], v[198:201], v[90:93]
	v_mfma_f32_16x16x32_bf16 v[82:85], v[174:177], v[206:209], v[82:85]
	v_mfma_f32_16x16x32_bf16 v[74:77], v[182:185], v[206:209], v[74:77]
	v_mfma_f32_16x16x32_bf16 v[70:73], v[174:177], v[214:217], v[70:73]
	v_mfma_f32_16x16x32_bf16 v[66:69], v[182:185], v[214:217], v[66:69]
	s_setprio 0
	s_barrier
	s_add_i32 s68, s56, s41
	v_lshl_add_u64 v[146:147], s[34:35], 0, v[132:133]
	s_mov_b32 m0, s68
	ds_read_b128 v[186:189], v152 offset:16384
	ds_read_b128 v[190:193], v152 offset:17408
	ds_read_b128 v[194:197], v152 offset:18432
	ds_read_b128 v[198:201], v152 offset:19456
	ds_read_b128 v[202:205], v152 offset:20480
	ds_read_b128 v[206:209], v152 offset:21504
	ds_read_b128 v[210:213], v152 offset:22528
	ds_read_b128 v[214:217], v152 offset:23552
	global_load_lds_dwordx4 v[146:147], off
	s_add_i32 m0, s68, 0x2000
	s_add_u32 s68, s34, 0x100000
	v_lshl_add_u64 v[218:219], s[34:35], 0, v[136:137]
	s_addc_u32 s69, s35, 0
	s_add_i32 s70, s57, s41
	global_load_lds_dwordx4 v[218:219], off
	v_lshl_add_u64 v[220:221], s[68:69], 0, v[132:133]
	s_mov_b32 m0, s70
	v_lshl_add_u64 v[222:223], s[36:37], 0, v[134:135]
	global_load_lds_dwordx4 v[220:221], off
	v_lshl_add_u64 v[220:221], s[68:69], 0, v[136:137]
	s_add_i32 m0, s70, 0x2000
	s_nop 0
	global_load_lds_dwordx4 v[220:221], off
	v_lshl_add_u64 v[220:221], s[36:37], 0, v[130:131]
	s_mov_b32 m0, s29
	s_nop 0
	global_load_lds_dwordx4 v[220:221], off
	s_mov_b32 m0, s44
	s_nop 0
	global_load_lds_dwordx4 v[222:223], off
	s_cmp_lg_u32 s100, 0
	s_cbranch_scc1 .Lrw2_1a
	s_waitcnt vmcnt(8)
	s_branch .Lrw2_1b

.Lrw2_1b:
	s_waitcnt lgkmcnt(0)
	s_barrier
	s_setprio 1
	s_waitcnt lgkmcnt(0)
	v_mfma_f32_16x16x32_bf16 v[62:65], v[154:157], v[186:189], v[62:65]
	v_mfma_f32_16x16x32_bf16 v[58:61], v[162:165], v[186:189], v[58:61]
	v_mfma_f32_16x16x32_bf16 v[54:57], v[154:157], v[194:197], v[54:57]
	v_mfma_f32_16x16x32_bf16 v[46:49], v[162:165], v[194:197], v[46:49]
	v_mfma_f32_16x16x32_bf16 v[38:41], v[154:157], v[202:205], v[38:41]
	v_mfma_f32_16x16x32_bf16 v[30:33], v[162:165], v[202:205], v[30:33]
	v_mfma_f32_16x16x32_bf16 v[22:25], v[154:157], v[210:213], v[22:25]
	v_mfma_f32_16x16x32_bf16 v[14:17], v[162:165], v[210:213], v[14:17]
	v_mfma_f32_16x16x32_bf16 v[62:65], v[158:161], v[190:193], v[62:65]
	v_mfma_f32_16x16x32_bf16 v[58:61], v[166:169], v[190:193], v[58:61]
	v_mfma_f32_16x16x32_bf16 v[54:57], v[158:161], v[198:201], v[54:57]
	v_mfma_f32_16x16x32_bf16 v[46:49], v[166:169], v[198:201], v[46:49]
	v_mfma_f32_16x16x32_bf16 v[38:41], v[158:161], v[206:209], v[38:41]
	v_mfma_f32_16x16x32_bf16 v[30:33], v[166:169], v[206:209], v[30:33]
	v_mfma_f32_16x16x32_bf16 v[22:25], v[158:161], v[214:217], v[22:25]
	v_mfma_f32_16x16x32_bf16 v[14:17], v[166:169], v[214:217], v[14:17]
	s_setprio 0
	s_setprio 1
	v_mfma_f32_16x16x32_bf16 v[50:53], v[170:173], v[186:189], v[50:53]
	v_mfma_f32_16x16x32_bf16 v[42:45], v[178:181], v[186:189], v[42:45]
	v_mfma_f32_16x16x32_bf16 v[34:37], v[170:173], v[194:197], v[34:37]
	v_mfma_f32_16x16x32_bf16 v[26:29], v[178:181], v[194:197], v[26:29]
	v_mfma_f32_16x16x32_bf16 v[18:21], v[170:173], v[202:205], v[18:21]
	v_mfma_f32_16x16x32_bf16 v[10:13], v[178:181], v[202:205], v[10:13]
	v_mfma_f32_16x16x32_bf16 v[6:9], v[170:173], v[210:213], v[6:9]
	v_mfma_f32_16x16x32_bf16 v[2:5], v[178:181], v[210:213], v[2:5]
	v_mfma_f32_16x16x32_bf16 v[50:53], v[174:177], v[190:193], v[50:53]
	v_mfma_f32_16x16x32_bf16 v[42:45], v[182:185], v[190:193], v[42:45]
	v_mfma_f32_16x16x32_bf16 v[34:37], v[174:177], v[198:201], v[34:37]
	v_mfma_f32_16x16x32_bf16 v[26:29], v[182:185], v[198:201], v[26:29]
	v_mfma_f32_16x16x32_bf16 v[18:21], v[174:177], v[206:209], v[18:21]
	v_mfma_f32_16x16x32_bf16 v[10:13], v[182:185], v[206:209], v[10:13]
	v_mfma_f32_16x16x32_bf16 v[6:9], v[174:177], v[214:217], v[6:9]
	v_mfma_f32_16x16x32_bf16 v[2:5], v[182:185], v[214:217], v[2:5]
	s_setprio 0
	s_barrier
	s_add_i32 s68, 0, 0x18000
	v_add_u32_e32 v153, s68, v148
	s_add_i32 s69, 0, 0x1c000
	ds_read_b128 v[154:157], v153
	ds_read_b128 v[158:161], v153 offset:1024
	ds_read_b128 v[162:165], v153 offset:2048
	ds_read_b128 v[166:169], v153 offset:3072
	v_add_u32_e32 v153, s69, v148
	ds_read_b128 v[170:173], v153
	ds_read_b128 v[174:177], v153 offset:1024
	ds_read_b128 v[178:181], v153 offset:2048
	ds_read_b128 v[182:185], v153 offset:3072
	s_add_u32 s36, s36, 0x100000
	s_addc_u32 s37, s37, 0
	s_mov_b32 m0, s45
	v_lshl_add_u64 v[224:225], s[36:37], 0, v[130:131]
	ds_read_b128 v[186:189], v152 offset:32768
	ds_read_b128 v[190:193], v152 offset:33792
	ds_read_b128 v[194:197], v152 offset:34816
	ds_read_b128 v[198:201], v152 offset:35840
	ds_read_b128 v[202:205], v152 offset:36864
	ds_read_b128 v[206:209], v152 offset:37888
	ds_read_b128 v[210:213], v152 offset:38912
	ds_read_b128 v[214:217], v152 offset:39936
	global_load_lds_dwordx4 v[224:225], off
	v_lshl_add_u64 v[224:225], s[36:37], 0, v[134:135]
	s_mov_b32 m0, s46
	s_nop 0
	global_load_lds_dwordx4 v[224:225], off
	s_waitcnt vmcnt(8)
	s_waitcnt lgkmcnt(0)
	s_barrier
	s_setprio 1
	s_waitcnt lgkmcnt(0)
	v_mfma_f32_16x16x32_bf16 v[126:129], v[154:157], v[186:189], v[126:129]
	v_mfma_f32_16x16x32_bf16 v[122:125], v[162:165], v[186:189], v[122:125]
	v_mfma_f32_16x16x32_bf16 v[118:121], v[154:157], v[194:197], v[118:121]
	v_mfma_f32_16x16x32_bf16 v[110:113], v[162:165], v[194:197], v[110:113]
	v_mfma_f32_16x16x32_bf16 v[102:105], v[154:157], v[202:205], v[102:105]
	v_mfma_f32_16x16x32_bf16 v[94:97], v[162:165], v[202:205], v[94:97]
	v_mfma_f32_16x16x32_bf16 v[86:89], v[154:157], v[210:213], v[86:89]
	v_mfma_f32_16x16x32_bf16 v[78:81], v[162:165], v[210:213], v[78:81]
	v_mfma_f32_16x16x32_bf16 v[126:129], v[158:161], v[190:193], v[126:129]
	v_mfma_f32_16x16x32_bf16 v[122:125], v[166:169], v[190:193], v[122:125]
	v_mfma_f32_16x16x32_bf16 v[118:121], v[158:161], v[198:201], v[118:121]
	v_mfma_f32_16x16x32_bf16 v[110:113], v[166:169], v[198:201], v[110:113]
	v_mfma_f32_16x16x32_bf16 v[102:105], v[158:161], v[206:209], v[102:105]
	v_mfma_f32_16x16x32_bf16 v[94:97], v[166:169], v[206:209], v[94:97]
	v_mfma_f32_16x16x32_bf16 v[86:89], v[158:161], v[214:217], v[86:89]
	v_mfma_f32_16x16x32_bf16 v[78:81], v[166:169], v[214:217], v[78:81]
	s_setprio 0
	s_setprio 1
	v_mfma_f32_16x16x32_bf16 v[114:117], v[170:173], v[186:189], v[114:117]
	v_mfma_f32_16x16x32_bf16 v[106:109], v[178:181], v[186:189], v[106:109]
	v_mfma_f32_16x16x32_bf16 v[98:101], v[170:173], v[194:197], v[98:101]
	v_mfma_f32_16x16x32_bf16 v[90:93], v[178:181], v[194:197], v[90:93]
	v_mfma_f32_16x16x32_bf16 v[82:85], v[170:173], v[202:205], v[82:85]
	v_mfma_f32_16x16x32_bf16 v[74:77], v[178:181], v[202:205], v[74:77]
	v_mfma_f32_16x16x32_bf16 v[70:73], v[170:173], v[210:213], v[70:73]
	v_mfma_f32_16x16x32_bf16 v[66:69], v[178:181], v[210:213], v[66:69]
	v_mfma_f32_16x16x32_bf16 v[114:117], v[174:177], v[190:193], v[114:117]
	v_mfma_f32_16x16x32_bf16 v[106:109], v[182:185], v[190:193], v[106:109]
	v_mfma_f32_16x16x32_bf16 v[98:101], v[174:177], v[198:201], v[98:101]
	v_mfma_f32_16x16x32_bf16 v[90:93], v[182:185], v[198:201], v[90:93]
	v_mfma_f32_16x16x32_bf16 v[82:85], v[174:177], v[206:209], v[82:85]
	v_mfma_f32_16x16x32_bf16 v[74:77], v[182:185], v[206:209], v[74:77]
	v_mfma_f32_16x16x32_bf16 v[70:73], v[174:177], v[214:217], v[70:73]
	v_mfma_f32_16x16x32_bf16 v[66:69], v[182:185], v[214:217], v[66:69]
	s_setprio 0
	s_barrier
	s_add_i32 s36, s68, s41
	v_lshl_add_u64 v[146:147], v[146:147], 0, s[8:9]
	s_mov_b32 m0, s36
	ds_read_b128 v[186:189], v152 offset:49152
	ds_read_b128 v[190:193], v152 offset:50176
	ds_read_b128 v[194:197], v152 offset:51200
	ds_read_b128 v[198:201], v152 offset:52224
	ds_read_b128 v[202:205], v152 offset:53248
	ds_read_b128 v[206:209], v152 offset:54272
	ds_read_b128 v[210:213], v152 offset:55296
	ds_read_b128 v[214:217], v152 offset:56320
	global_load_lds_dwordx4 v[146:147], off
	s_add_i32 m0, s36, 0x2000
	s_add_u32 s34, s34, 0x100080
	v_lshl_add_u64 v[146:147], v[218:219], 0, s[8:9]
	s_addc_u32 s35, s35, 0
	s_add_i32 s36, s69, s41
	global_load_lds_dwordx4 v[146:147], off
	v_lshl_add_u64 v[146:147], s[34:35], 0, v[132:133]
	s_mov_b32 m0, s36
	s_nop 0
	global_load_lds_dwordx4 v[146:147], off
	v_lshl_add_u64 v[146:147], s[34:35], 0, v[136:137]
	s_add_i32 m0, s36, 0x2000
	s_nop 0
	global_load_lds_dwordx4 v[146:147], off
	v_lshl_add_u64 v[146:147], v[220:221], 0, s[8:9]
	s_mov_b32 m0, s52
	s_nop 0
	global_load_lds_dwordx4 v[146:147], off
	v_lshl_add_u64 v[146:147], v[222:223], 0, s[8:9]
	s_mov_b32 m0, s53
	s_nop 0
	global_load_lds_dwordx4 v[146:147], off
	s_waitcnt vmcnt(8)
	s_waitcnt lgkmcnt(0)
	s_barrier
	s_setprio 1
	s_waitcnt lgkmcnt(0)
	v_mfma_f32_16x16x32_bf16 v[62:65], v[154:157], v[186:189], v[62:65]
	v_mfma_f32_16x16x32_bf16 v[58:61], v[162:165], v[186:189], v[58:61]
	v_mfma_f32_16x16x32_bf16 v[54:57], v[154:157], v[194:197], v[54:57]
	v_mfma_f32_16x16x32_bf16 v[46:49], v[162:165], v[194:197], v[46:49]
	v_mfma_f32_16x16x32_bf16 v[38:41], v[154:157], v[202:205], v[38:41]
	v_mfma_f32_16x16x32_bf16 v[30:33], v[162:165], v[202:205], v[30:33]
	v_mfma_f32_16x16x32_bf16 v[22:25], v[154:157], v[210:213], v[22:25]
	v_mfma_f32_16x16x32_bf16 v[14:17], v[162:165], v[210:213], v[14:17]
	v_mfma_f32_16x16x32_bf16 v[62:65], v[158:161], v[190:193], v[62:65]
	v_mfma_f32_16x16x32_bf16 v[58:61], v[166:169], v[190:193], v[58:61]
	v_mfma_f32_16x16x32_bf16 v[54:57], v[158:161], v[198:201], v[54:57]
	v_mfma_f32_16x16x32_bf16 v[46:49], v[166:169], v[198:201], v[46:49]
	v_mfma_f32_16x16x32_bf16 v[38:41], v[158:161], v[206:209], v[38:41]
	v_mfma_f32_16x16x32_bf16 v[30:33], v[166:169], v[206:209], v[30:33]
	v_mfma_f32_16x16x32_bf16 v[22:25], v[158:161], v[214:217], v[22:25]
	v_mfma_f32_16x16x32_bf16 v[14:17], v[166:169], v[214:217], v[14:17]
	s_setprio 0
	s_setprio 1
	v_mfma_f32_16x16x32_bf16 v[50:53], v[170:173], v[186:189], v[50:53]
	v_mfma_f32_16x16x32_bf16 v[42:45], v[178:181], v[186:189], v[42:45]
	v_mfma_f32_16x16x32_bf16 v[34:37], v[170:173], v[194:197], v[34:37]
	v_mfma_f32_16x16x32_bf16 v[26:29], v[178:181], v[194:197], v[26:29]
	v_mfma_f32_16x16x32_bf16 v[18:21], v[170:173], v[202:205], v[18:21]
	v_mfma_f32_16x16x32_bf16 v[10:13], v[178:181], v[202:205], v[10:13]
	v_mfma_f32_16x16x32_bf16 v[6:9], v[170:173], v[210:213], v[6:9]
	v_mfma_f32_16x16x32_bf16 v[2:5], v[178:181], v[210:213], v[2:5]
	v_mfma_f32_16x16x32_bf16 v[50:53], v[174:177], v[190:193], v[50:53]
	v_mfma_f32_16x16x32_bf16 v[42:45], v[182:185], v[190:193], v[42:45]
	v_mfma_f32_16x16x32_bf16 v[34:37], v[174:177], v[198:201], v[34:37]
	v_mfma_f32_16x16x32_bf16 v[26:29], v[182:185], v[198:201], v[26:29]
	v_mfma_f32_16x16x32_bf16 v[18:21], v[174:177], v[206:209], v[18:21]
	v_mfma_f32_16x16x32_bf16 v[10:13], v[182:185], v[206:209], v[10:13]
	v_mfma_f32_16x16x32_bf16 v[6:9], v[174:177], v[214:217], v[6:9]
	v_mfma_f32_16x16x32_bf16 v[2:5], v[182:185], v[214:217], v[2:5]
	s_setprio 0
	s_barrier
	s_add_i32 s67, s67, 2
	s_add_u32 s30, s30, 0x100
	s_addc_u32 s31, s31, 0
	s_add_u32 s65, s65, 0x100
	s_addc_u32 s66, s66, 0
	s_mov_b32 s100, 0
	s_cmp_gt_u32 s67, 61
	s_cbranch_scc0 .LBB0_728
	s_and_b64 vcc, exec, s[10:11]
	s_cbranch_vccz .LBB0_731
	s_barrier
.LBB0_731:
	v_lshl_add_u32 v154, s28, 8, v1
	v_lshl_or_b32 v146, s62, 8, v149
	v_ashrrev_i32_e32 v155, 31, v154
	v_ashrrev_i32_e32 v147, 31, v146
	v_lshlrev_b64 v[156:157], 11, v[154:155]
	v_lshl_add_u64 v[156:157], s[6:7], 0, v[156:157]
	v_lshlrev_b64 v[158:159], 1, v[146:147]
	v_lshl_add_u64 v[146:147], v[156:157], 0, v[158:159]
	v_cvt_pk_bf16_f32 v126, v126, v127
	v_cvt_pk_bf16_f32 v127, v128, v129
	v_cvt_pk_bf16_f32 v128, v122, v123
	v_cvt_pk_bf16_f32 v129, v124, v125
	global_store_dwordx4 v[146:147], v[126:129], off
	v_cvt_pk_bf16_f32 v114, v114, v115
	v_cvt_pk_bf16_f32 v115, v116, v117
	v_cvt_pk_bf16_f32 v116, v106, v107
	v_or_b32_e32 v106, 16, v154
	v_ashrrev_i32_e32 v107, 31, v106
	v_lshlrev_b64 v[106:107], 11, v[106:107]
	v_lshl_add_u64 v[106:107], s[6:7], 0, v[106:107]
	v_cvt_pk_bf16_f32 v117, v108, v109
	global_store_dwordx4 v[146:147], v[114:117], off offset:256
	s_nop 1
	v_lshl_add_u64 v[114:115], v[106:107], 0, v[158:159]
	v_cvt_pk_bf16_f32 v106, v118, v119
	v_cvt_pk_bf16_f32 v107, v120, v121
	v_cvt_pk_bf16_f32 v108, v110, v111
	v_cvt_pk_bf16_f32 v109, v112, v113
	global_store_dwordx4 v[114:115], v[106:109], off
	v_cvt_pk_bf16_f32 v98, v98, v99
	v_cvt_pk_bf16_f32 v99, v100, v101
	v_cvt_pk_bf16_f32 v100, v90, v91
	v_or_b32_e32 v90, 32, v154
	v_ashrrev_i32_e32 v91, 31, v90
	v_lshlrev_b64 v[90:91], 11, v[90:91]
	v_lshl_add_u64 v[90:91], s[6:7], 0, v[90:91]
	v_cvt_pk_bf16_f32 v101, v92, v93
	global_store_dwordx4 v[114:115], v[98:101], off offset:256
	s_nop 1
	v_lshl_add_u64 v[98:99], v[90:91], 0, v[158:159]
	v_cvt_pk_bf16_f32 v90, v102, v103
	v_cvt_pk_bf16_f32 v91, v104, v105
	v_cvt_pk_bf16_f32 v92, v94, v95
	v_cvt_pk_bf16_f32 v93, v96, v97
	global_store_dwordx4 v[98:99], v[90:93], off
	v_cvt_pk_bf16_f32 v82, v82, v83
	v_cvt_pk_bf16_f32 v83, v84, v85
	v_cvt_pk_bf16_f32 v84, v74, v75
	v_or_b32_e32 v74, 48, v154
	v_ashrrev_i32_e32 v75, 31, v74
	v_lshlrev_b64 v[74:75], 11, v[74:75]
	v_lshl_add_u64 v[74:75], s[6:7], 0, v[74:75]
	v_cvt_pk_bf16_f32 v85, v76, v77
	global_store_dwordx4 v[98:99], v[82:85], off offset:256
	s_nop 1
	v_lshl_add_u64 v[82:83], v[74:75], 0, v[158:159]
	v_cvt_pk_bf16_f32 v74, v86, v87
	v_cvt_pk_bf16_f32 v75, v88, v89
	v_cvt_pk_bf16_f32 v76, v78, v79
	v_cvt_pk_bf16_f32 v77, v80, v81
	global_store_dwordx4 v[82:83], v[74:77], off
	v_cvt_pk_bf16_f32 v70, v70, v71
	v_cvt_pk_bf16_f32 v71, v72, v73
	v_cvt_pk_bf16_f32 v72, v66, v67
	v_cvt_pk_bf16_f32 v73, v68, v69
	global_store_dwordx4 v[82:83], v[70:73], off offset:256
	v_cvt_pk_bf16_f32 v62, v62, v63
	v_cvt_pk_bf16_f32 v63, v64, v65
	v_cvt_pk_bf16_f32 v64, v58, v59
	v_add_co_u32_e32 v58, vcc, s58, v146
	v_lshl_add_u64 v[66:67], v[146:147], 0, s[12:13]
	s_nop 0
	v_addc_co_u32_e32 v59, vcc, 0, v147, vcc
	v_cvt_pk_bf16_f32 v65, v60, v61
	global_store_dwordx4 v[58:59], v[62:65], off
	v_cvt_pk_bf16_f32 v50, v50, v51
	v_cvt_pk_bf16_f32 v51, v52, v53
	v_cvt_pk_bf16_f32 v52, v42, v43
	v_cvt_pk_bf16_f32 v53, v44, v45
	global_store_dwordx4 v[66:67], v[50:53], off offset:256
	v_cvt_pk_bf16_f32 v42, v54, v55
	v_cvt_pk_bf16_f32 v43, v56, v57
	v_cvt_pk_bf16_f32 v44, v46, v47
	v_add_co_u32_e32 v46, vcc, s59, v146
	s_nop 0
	v_lshl_add_u64 v[50:51], v[146:147], 0, s[14:15]
	v_addc_co_u32_e32 v47, vcc, 0, v147, vcc
	v_cvt_pk_bf16_f32 v45, v48, v49
	global_store_dwordx4 v[46:47], v[42:45], off
	v_cvt_pk_bf16_f32 v34, v34, v35
	v_cvt_pk_bf16_f32 v35, v36, v37
	v_cvt_pk_bf16_f32 v36, v26, v27
	v_cvt_pk_bf16_f32 v37, v28, v29
	global_store_dwordx4 v[50:51], v[34:37], off offset:256
	v_cvt_pk_bf16_f32 v26, v38, v39
	v_cvt_pk_bf16_f32 v27, v40, v41
	v_cvt_pk_bf16_f32 v28, v30, v31
	v_add_co_u32_e32 v30, vcc, s60, v146
	s_nop 0
	v_lshl_add_u64 v[34:35], v[146:147], 0, s[16:17]
	v_addc_co_u32_e32 v31, vcc, 0, v147, vcc
	v_cvt_pk_bf16_f32 v29, v32, v33
	global_store_dwordx4 v[30:31], v[26:29], off
	v_cvt_pk_bf16_f32 v18, v18, v19
	v_cvt_pk_bf16_f32 v19, v20, v21
	v_cvt_pk_bf16_f32 v20, v10, v11
	v_cvt_pk_bf16_f32 v21, v12, v13
	global_store_dwordx4 v[34:35], v[18:21], off offset:256
	v_cvt_pk_bf16_f32 v10, v22, v23
	v_cvt_pk_bf16_f32 v11, v24, v25
	v_cvt_pk_bf16_f32 v12, v14, v15
	v_add_co_u32_e32 v14, vcc, s61, v146
	s_nop 0
	v_lshl_add_u64 v[18:19], v[146:147], 0, s[18:19]
	v_addc_co_u32_e32 v15, vcc, 0, v147, vcc
	s_andn2_b64 vcc, exec, s[0:1]
	s_mov_b64 s[0:1], -1
	v_cvt_pk_bf16_f32 v13, v16, v17
	global_store_dwordx4 v[14:15], v[10:13], off
	v_cvt_pk_bf16_f32 v6, v6, v7
	v_cvt_pk_bf16_f32 v7, v8, v9
	v_cvt_pk_bf16_f32 v8, v2, v3
	v_cvt_pk_bf16_f32 v9, v4, v5
	global_store_dwordx4 v[18:19], v[6:9], off offset:256
	s_mov_b32 s100, 1
	s_cbranch_vccnz .LBB0_720
	s_andn2_b64 vcc, exec, s[4:5]
	s_cbranch_vccnz .LBB0_719
	s_barrier
	s_branch .LBB0_719

.LBB0_845:
	s_mov_b32 s100, 0
	s_cmp_lt_i32 s72, 12
	s_cselect_b64 s[0:1], -1, 0
	s_cmp_gt_i32 s73, 11
	s_cselect_b64 s[4:5], -1, 0
	s_and_b64 s[0:1], s[0:1], s[4:5]
	s_andn2_b64 vcc, exec, s[0:1]
	s_cbranch_vccnz .LBB0_912
	s_cmpk_gt_i32 s2, 0x5ff
	v_readfirstlane_b32 s1, v0
	s_cbranch_scc1 .LBB0_862
	v_lshrrev_b32_e32 v1, 5, v0
	v_lshrrev_b32_e32 v3, 1, v0
	v_and_b32_e32 v1, 4, v1
	v_bfe_u32 v2, v0, 2, 2
	v_and_b32_e32 v13, 24, v3
	s_add_u32 s3, s94, 0x3800000
	v_or3_b32 v1, v1, v2, v13
	v_lshlrev_b32_e32 v2, 4, v0
	s_addc_u32 s28, s95, 0
	v_or_b32_e32 v10, 0x2000, v2
	s_add_u32 s29, s94, 0xe00000
	v_lshrrev_b32_e32 v3, 7, v10
	s_movk_i32 s0, 0x60
	s_addc_u32 s30, s95, 0
	v_and_or_b32 v4, v3, s0, v1
	v_bfe_u32 v14, v0, 2, 4
	s_movk_i32 s0, 0x70
	s_ashr_i32 s33, s2, 31
	v_and_or_b32 v3, v3, s0, v14
	s_lshr_b32 s0, s33, 29
	s_add_i32 s0, s2, s0
	s_lshr_b32 s8, s1, 6
	s_ashr_i32 s4, s0, 3
	s_and_b32 s0, s0, -8
	s_lshr_b32 s10, s1, 8
	s_lshl_b32 s31, s8, 10
	s_sub_i32 s0, s2, s0
	s_cmp_lt_i32 s0, 0
	s_movk_i32 s34, 0xc1
	s_cselect_b32 s5, s34, 0xc0
	s_mul_i32 s0, s5, s0
	s_add_i32 s0, s0, s4
	s_mul_hi_i32 s4, s0, 0x2aaaaaab
	s_lshr_b32 s5, s4, 31
	s_ashr_i32 s4, s4, 4
	s_add_i32 s4, s4, s5
	s_lshl_b32 s5, s4, 3
	s_mulk_i32 s4, 0x60
	s_sub_i32 s4, s0, s4
	s_bfe_i32 s0, s4, 0x80000
	s_bfe_u32 s0, s0, 0x3000c
	s_add_i32 s6, s4, s0
	s_bfe_i32 s0, s6, 0x80000
	s_and_b32 s6, s6, 0xf8
	s_sub_i32 s4, s4, s6
	s_sext_i32_i16 s0, s0
	s_sext_i32_i8 s4, s4
	v_and_b32_e32 v5, 32, v0
	s_lshr_b32 s0, s0, 3
	s_add_i32 s20, s5, s4
	v_bitop3_b32 v11, v2, v5, 48 bitop3:0x6c
	v_and_b32_e32 v12, 64, v0
	s_ashr_i32 s21, s20, 31
	s_bfe_i64 s[6:7], s[0:1], 0x100000
	v_or_b32_e32 v2, v11, v12
	s_lshl_b64 s[4:5], s[20:21], 19
	s_lshl_b64 s[6:7], s[6:7], 19
	v_lshl_or_b32 v132, v3, 11, v2
	v_lshrrev_b32_e32 v3, 3, v0
	s_add_u32 s24, s29, s6
	v_and_or_b32 v1, v3, 32, v1
	s_addc_u32 s25, s30, s7
	s_add_i32 s21, s31, 0
	v_lshl_or_b32 v134, v1, 11, v2
	s_add_i32 m0, s21, 0x10000
	v_lshl_or_b32 v130, v4, 11, v2
	global_load_lds_dwordx4 v134, s[24:25]
	s_add_i32 m0, s21, 0x12000
	s_add_u32 s6, s24, 0x40000
	global_load_lds_dwordx4 v130, s[24:25]
	s_addc_u32 s7, s25, 0
	s_add_i32 m0, s21, 0x14000
	v_and_or_b32 v1, v3, 48, v14
	global_load_lds_dwordx4 v134, s[6:7]
	s_add_i32 m0, s21, 0x16000
	s_add_u32 s22, s3, s4
	s_addc_u32 s23, s28, s5
	s_add_i32 s35, s21, 0x2000
	v_lshl_or_b32 v136, v1, 11, v2
	global_load_lds_dwordx4 v130, s[6:7]
	s_mov_b32 m0, s21
	s_add_u32 s4, s22, 0x40000
	global_load_lds_dwordx4 v136, s[22:23]
	s_mov_b32 m0, s35
	s_addc_u32 s5, s23, 0
	s_add_i32 s36, s21, 0x4000
	global_load_lds_dwordx4 v132, s[22:23]
	s_mov_b32 m0, s36
	s_add_i32 s37, s21, 0x6000
	global_load_lds_dwordx4 v136, s[4:5]
	s_mov_b32 m0, s37
	v_mov_b32_e32 v135, 0
	global_load_lds_dwordx4 v132, s[4:5]
	v_mov_b32_e32 v131, v135
	v_mov_b32_e32 v137, v135
	v_mov_b32_e32 v133, v135
	s_cmp_eq_u32 s10, 1
	s_mov_b32 s38, 0
	v_lshl_add_u64 v[8:9], s[24:25], 0, v[134:135]
	v_lshl_add_u64 v[6:7], s[24:25], 0, v[130:131]
	v_lshl_add_u64 v[2:3], s[22:23], 0, v[136:137]
	s_cselect_b64 s[4:5], -1, 0
	s_cmp_lg_u32 s10, 1
	v_lshl_add_u64 v[4:5], s[22:23], 0, v[132:133]
	s_cbranch_scc1 .LBB0_849
	s_barrier

.LBB0_855:
	ds_read_b128 v[146:149], v152
	ds_read_b128 v[156:159], v152 offset:1024
	ds_read_b128 v[160:163], v152 offset:2048
	ds_read_b128 v[164:167], v152 offset:3072
	ds_read_b128 v[168:171], v153
	ds_read_b128 v[172:175], v153 offset:1024
	ds_read_b128 v[176:179], v153 offset:2048
	ds_read_b128 v[180:183], v153 offset:3072
	s_add_u32 s24, s22, 0xfffc0080
	s_addc_u32 s25, s23, -1
	s_cmp_eq_u32 s57, 12
	s_cselect_b32 s27, s15, s25
	s_cselect_b32 s26, s53, s24
	s_cselect_b32 s25, s13, s56
	s_cselect_b32 s24, s54, s55
	v_lshl_add_u64 v[216:217], s[22:23], 0, v[138:139]
	s_add_i32 m0, s21, 0xc000
	ds_read_b128 v[184:187], v154
	ds_read_b128 v[188:191], v154 offset:1024
	ds_read_b128 v[192:195], v154 offset:2048
	ds_read_b128 v[196:199], v154 offset:3072
	ds_read_b128 v[200:203], v154 offset:4096
	ds_read_b128 v[204:207], v154 offset:5120
	ds_read_b128 v[208:211], v154 offset:6144
	ds_read_b128 v[212:215], v154 offset:7168
	global_load_lds_dwordx4 v[216:217], off
	v_lshl_add_u64 v[216:217], s[22:23], 0, v[140:141]
	s_add_i32 m0, s21, 0xe000
	s_nop 0
	global_load_lds_dwordx4 v[216:217], off
	s_cmp_lg_u32 s100, 0
	s_cbranch_scc1 .Lrw3_0a
	s_waitcnt vmcnt(8)
	s_branch .Lrw3_0b

.Lrw3_0b:
	s_waitcnt lgkmcnt(0)
	s_barrier
	s_setprio 1
	s_waitcnt lgkmcnt(0)
	v_mfma_f32_16x16x32_bf16 v[126:129], v[146:149], v[184:187], v[126:129]
	v_mfma_f32_16x16x32_bf16 v[122:125], v[160:163], v[184:187], v[122:125]
	v_mfma_f32_16x16x32_bf16 v[118:121], v[146:149], v[192:195], v[118:121]
	v_mfma_f32_16x16x32_bf16 v[110:113], v[160:163], v[192:195], v[110:113]
	v_mfma_f32_16x16x32_bf16 v[102:105], v[146:149], v[200:203], v[102:105]
	v_mfma_f32_16x16x32_bf16 v[94:97], v[160:163], v[200:203], v[94:97]
	v_mfma_f32_16x16x32_bf16 v[86:89], v[146:149], v[208:211], v[86:89]
	v_mfma_f32_16x16x32_bf16 v[78:81], v[160:163], v[208:211], v[78:81]
	v_mfma_f32_16x16x32_bf16 v[126:129], v[156:159], v[188:191], v[126:129]
	v_mfma_f32_16x16x32_bf16 v[122:125], v[164:167], v[188:191], v[122:125]
	v_mfma_f32_16x16x32_bf16 v[118:121], v[156:159], v[196:199], v[118:121]
	v_mfma_f32_16x16x32_bf16 v[110:113], v[164:167], v[196:199], v[110:113]
	v_mfma_f32_16x16x32_bf16 v[102:105], v[156:159], v[204:207], v[102:105]
	v_mfma_f32_16x16x32_bf16 v[94:97], v[164:167], v[204:207], v[94:97]
	v_mfma_f32_16x16x32_bf16 v[86:89], v[156:159], v[212:215], v[86:89]
	v_mfma_f32_16x16x32_bf16 v[78:81], v[164:167], v[212:215], v[78:81]
	s_setprio 0
	s_setprio 1
	v_mfma_f32_16x16x32_bf16 v[114:117], v[168:171], v[184:187], v[114:117]
	v_mfma_f32_16x16x32_bf16 v[106:109], v[176:179], v[184:187], v[106:109]
	v_mfma_f32_16x16x32_bf16 v[98:101], v[168:171], v[192:195], v[98:101]
	v_mfma_f32_16x16x32_bf16 v[90:93], v[176:179], v[192:195], v[90:93]
	v_mfma_f32_16x16x32_bf16 v[82:85], v[168:171], v[200:203], v[82:85]
	v_mfma_f32_16x16x32_bf16 v[74:77], v[176:179], v[200:203], v[74:77]
	v_mfma_f32_16x16x32_bf16 v[70:73], v[168:171], v[208:211], v[70:73]
	v_mfma_f32_16x16x32_bf16 v[66:69], v[176:179], v[208:211], v[66:69]
	v_mfma_f32_16x16x32_bf16 v[114:117], v[172:175], v[188:191], v[114:117]
	v_mfma_f32_16x16x32_bf16 v[106:109], v[180:183], v[188:191], v[106:109]
	v_mfma_f32_16x16x32_bf16 v[98:101], v[172:175], v[196:199], v[98:101]
	v_mfma_f32_16x16x32_bf16 v[90:93], v[180:183], v[196:199], v[90:93]
	v_mfma_f32_16x16x32_bf16 v[82:85], v[172:175], v[204:207], v[82:85]
	v_mfma_f32_16x16x32_bf16 v[74:77], v[180:183], v[204:207], v[74:77]
	v_mfma_f32_16x16x32_bf16 v[70:73], v[172:175], v[212:215], v[70:73]
	v_mfma_f32_16x16x32_bf16 v[66:69], v[180:183], v[212:215], v[66:69]
	s_setprio 0
	s_barrier
	s_add_i32 s58, s45, s31
	v_lshl_add_u64 v[216:217], s[24:25], 0, v[134:135]
	s_mov_b32 m0, s58
	ds_read_b128 v[184:187], v154 offset:16384
	ds_read_b128 v[188:191], v154 offset:17408
	ds_read_b128 v[192:195], v154 offset:18432
	ds_read_b128 v[196:199], v154 offset:19456
	ds_read_b128 v[200:203], v154 offset:20480
	ds_read_b128 v[204:207], v154 offset:21504
	ds_read_b128 v[208:211], v154 offset:22528
	ds_read_b128 v[212:215], v154 offset:23552
	global_load_lds_dwordx4 v[216:217], off
	s_add_i32 m0, s58, 0x2000
	s_add_u32 s58, s24, 0x40000
	v_lshl_add_u64 v[218:219], s[24:25], 0, v[130:131]
	s_addc_u32 s59, s25, 0
	s_add_i32 s60, s46, s31
	global_load_lds_dwordx4 v[218:219], off
	v_lshl_add_u64 v[220:221], s[58:59], 0, v[134:135]
	s_mov_b32 m0, s60
	v_lshl_add_u64 v[222:223], s[26:27], 0, v[132:133]
	global_load_lds_dwordx4 v[220:221], off
	v_lshl_add_u64 v[220:221], s[58:59], 0, v[130:131]
	s_add_i32 m0, s60, 0x2000
	s_nop 0
	global_load_lds_dwordx4 v[220:221], off
	v_lshl_add_u64 v[220:221], s[26:27], 0, v[136:137]
	s_mov_b32 m0, s21
	s_nop 0
	global_load_lds_dwordx4 v[220:221], off
	s_mov_b32 m0, s35
	s_nop 0
	global_load_lds_dwordx4 v[222:223], off
	s_cmp_lg_u32 s100, 0
	s_cbranch_scc1 .Lrw3_1a
	s_waitcnt vmcnt(8)
	s_branch .Lrw3_1b

.Lrw3_1b:
	s_waitcnt lgkmcnt(0)
	s_barrier
	s_setprio 1
	s_waitcnt lgkmcnt(0)
	v_mfma_f32_16x16x32_bf16 v[62:65], v[146:149], v[184:187], v[62:65]
	v_mfma_f32_16x16x32_bf16 v[58:61], v[160:163], v[184:187], v[58:61]
	v_mfma_f32_16x16x32_bf16 v[54:57], v[146:149], v[192:195], v[54:57]
	v_mfma_f32_16x16x32_bf16 v[46:49], v[160:163], v[192:195], v[46:49]
	v_mfma_f32_16x16x32_bf16 v[38:41], v[146:149], v[200:203], v[38:41]
	v_mfma_f32_16x16x32_bf16 v[30:33], v[160:163], v[200:203], v[30:33]
	v_mfma_f32_16x16x32_bf16 v[22:25], v[146:149], v[208:211], v[22:25]
	v_mfma_f32_16x16x32_bf16 v[14:17], v[160:163], v[208:211], v[14:17]
	v_mfma_f32_16x16x32_bf16 v[62:65], v[156:159], v[188:191], v[62:65]
	v_mfma_f32_16x16x32_bf16 v[58:61], v[164:167], v[188:191], v[58:61]
	v_mfma_f32_16x16x32_bf16 v[54:57], v[156:159], v[196:199], v[54:57]
	v_mfma_f32_16x16x32_bf16 v[46:49], v[164:167], v[196:199], v[46:49]
	v_mfma_f32_16x16x32_bf16 v[38:41], v[156:159], v[204:207], v[38:41]
	v_mfma_f32_16x16x32_bf16 v[30:33], v[164:167], v[204:207], v[30:33]
	v_mfma_f32_16x16x32_bf16 v[22:25], v[156:159], v[212:215], v[22:25]
	v_mfma_f32_16x16x32_bf16 v[14:17], v[164:167], v[212:215], v[14:17]
	s_setprio 0
	s_setprio 1
	v_mfma_f32_16x16x32_bf16 v[50:53], v[168:171], v[184:187], v[50:53]
	v_mfma_f32_16x16x32_bf16 v[42:45], v[176:179], v[184:187], v[42:45]
	v_mfma_f32_16x16x32_bf16 v[34:37], v[168:171], v[192:195], v[34:37]
	v_mfma_f32_16x16x32_bf16 v[26:29], v[176:179], v[192:195], v[26:29]
	v_mfma_f32_16x16x32_bf16 v[18:21], v[168:171], v[200:203], v[18:21]
	v_mfma_f32_16x16x32_bf16 v[10:13], v[176:179], v[200:203], v[10:13]
	v_mfma_f32_16x16x32_bf16 v[6:9], v[168:171], v[208:211], v[6:9]
	v_mfma_f32_16x16x32_bf16 v[2:5], v[176:179], v[208:211], v[2:5]
	v_mfma_f32_16x16x32_bf16 v[50:53], v[172:175], v[188:191], v[50:53]
	v_mfma_f32_16x16x32_bf16 v[42:45], v[180:183], v[188:191], v[42:45]
	v_mfma_f32_16x16x32_bf16 v[34:37], v[172:175], v[196:199], v[34:37]
	v_mfma_f32_16x16x32_bf16 v[26:29], v[180:183], v[196:199], v[26:29]
	v_mfma_f32_16x16x32_bf16 v[18:21], v[172:175], v[204:207], v[18:21]
	v_mfma_f32_16x16x32_bf16 v[10:13], v[180:183], v[204:207], v[10:13]
	v_mfma_f32_16x16x32_bf16 v[6:9], v[172:175], v[212:215], v[6:9]
	v_mfma_f32_16x16x32_bf16 v[2:5], v[180:183], v[212:215], v[2:5]
	s_setprio 0
	s_barrier
	s_add_i32 s58, 0, 0x18000
	v_add_u32_e32 v155, s58, v150
	s_add_i32 s59, 0, 0x1c000
	ds_read_b128 v[146:149], v155
	ds_read_b128 v[156:159], v155 offset:1024
	ds_read_b128 v[160:163], v155 offset:2048
	ds_read_b128 v[164:167], v155 offset:3072
	v_add_u32_e32 v155, s59, v150
	ds_read_b128 v[168:171], v155
	ds_read_b128 v[172:175], v155 offset:1024
	ds_read_b128 v[176:179], v155 offset:2048
	ds_read_b128 v[180:183], v155 offset:3072
	s_add_u32 s26, s26, 0x40000
	s_addc_u32 s27, s27, 0
	s_mov_b32 m0, s36
	v_lshl_add_u64 v[224:225], s[26:27], 0, v[136:137]
	ds_read_b128 v[184:187], v154 offset:32768
	ds_read_b128 v[188:191], v154 offset:33792
	ds_read_b128 v[192:195], v154 offset:34816
	ds_read_b128 v[196:199], v154 offset:35840
	ds_read_b128 v[200:203], v154 offset:36864
	ds_read_b128 v[204:207], v154 offset:37888
	ds_read_b128 v[208:211], v154 offset:38912
	ds_read_b128 v[212:215], v154 offset:39936
	global_load_lds_dwordx4 v[224:225], off
	v_lshl_add_u64 v[224:225], s[26:27], 0, v[132:133]
	s_mov_b32 m0, s37
	s_nop 0
	global_load_lds_dwordx4 v[224:225], off
	s_waitcnt vmcnt(8)
	s_waitcnt lgkmcnt(0)
	s_barrier
	s_setprio 1
	s_waitcnt lgkmcnt(0)
	v_mfma_f32_16x16x32_bf16 v[126:129], v[146:149], v[184:187], v[126:129]
	v_mfma_f32_16x16x32_bf16 v[122:125], v[160:163], v[184:187], v[122:125]
	v_mfma_f32_16x16x32_bf16 v[118:121], v[146:149], v[192:195], v[118:121]
	v_mfma_f32_16x16x32_bf16 v[110:113], v[160:163], v[192:195], v[110:113]
	v_mfma_f32_16x16x32_bf16 v[102:105], v[146:149], v[200:203], v[102:105]
	v_mfma_f32_16x16x32_bf16 v[94:97], v[160:163], v[200:203], v[94:97]
	v_mfma_f32_16x16x32_bf16 v[86:89], v[146:149], v[208:211], v[86:89]
	v_mfma_f32_16x16x32_bf16 v[78:81], v[160:163], v[208:211], v[78:81]
	v_mfma_f32_16x16x32_bf16 v[126:129], v[156:159], v[188:191], v[126:129]
	v_mfma_f32_16x16x32_bf16 v[122:125], v[164:167], v[188:191], v[122:125]
	v_mfma_f32_16x16x32_bf16 v[118:121], v[156:159], v[196:199], v[118:121]
	v_mfma_f32_16x16x32_bf16 v[110:113], v[164:167], v[196:199], v[110:113]
	v_mfma_f32_16x16x32_bf16 v[102:105], v[156:159], v[204:207], v[102:105]
	v_mfma_f32_16x16x32_bf16 v[94:97], v[164:167], v[204:207], v[94:97]
	v_mfma_f32_16x16x32_bf16 v[86:89], v[156:159], v[212:215], v[86:89]
	v_mfma_f32_16x16x32_bf16 v[78:81], v[164:167], v[212:215], v[78:81]
	s_setprio 0
	s_setprio 1
	v_mfma_f32_16x16x32_bf16 v[114:117], v[168:171], v[184:187], v[114:117]
	v_mfma_f32_16x16x32_bf16 v[106:109], v[176:179], v[184:187], v[106:109]
	v_mfma_f32_16x16x32_bf16 v[98:101], v[168:171], v[192:195], v[98:101]
	v_mfma_f32_16x16x32_bf16 v[90:93], v[176:179], v[192:195], v[90:93]
	v_mfma_f32_16x16x32_bf16 v[82:85], v[168:171], v[200:203], v[82:85]
	v_mfma_f32_16x16x32_bf16 v[74:77], v[176:179], v[200:203], v[74:77]
	v_mfma_f32_16x16x32_bf16 v[70:73], v[168:171], v[208:211], v[70:73]
	v_mfma_f32_16x16x32_bf16 v[66:69], v[176:179], v[208:211], v[66:69]
	v_mfma_f32_16x16x32_bf16 v[114:117], v[172:175], v[188:191], v[114:117]
	v_mfma_f32_16x16x32_bf16 v[106:109], v[180:183], v[188:191], v[106:109]
	v_mfma_f32_16x16x32_bf16 v[98:101], v[172:175], v[196:199], v[98:101]
	v_mfma_f32_16x16x32_bf16 v[90:93], v[180:183], v[196:199], v[90:93]
	v_mfma_f32_16x16x32_bf16 v[82:85], v[172:175], v[204:207], v[82:85]
	v_mfma_f32_16x16x32_bf16 v[74:77], v[180:183], v[204:207], v[74:77]
	v_mfma_f32_16x16x32_bf16 v[70:73], v[172:175], v[212:215], v[70:73]
	v_mfma_f32_16x16x32_bf16 v[66:69], v[180:183], v[212:215], v[66:69]
	s_setprio 0
	s_barrier
	s_add_i32 s26, s58, s31
	v_lshl_add_u64 v[216:217], v[216:217], 0, s[8:9]
	s_mov_b32 m0, s26
	ds_read_b128 v[184:187], v154 offset:49152
	ds_read_b128 v[188:191], v154 offset:50176
	ds_read_b128 v[192:195], v154 offset:51200
	ds_read_b128 v[196:199], v154 offset:52224
	ds_read_b128 v[200:203], v154 offset:53248
	ds_read_b128 v[204:207], v154 offset:54272
	ds_read_b128 v[208:211], v154 offset:55296
	ds_read_b128 v[212:215], v154 offset:56320
	global_load_lds_dwordx4 v[216:217], off
	s_add_i32 m0, s26, 0x2000
	s_add_u32 s24, s24, 0x40080
	v_lshl_add_u64 v[216:217], v[218:219], 0, s[8:9]
	s_addc_u32 s25, s25, 0
	s_add_i32 s26, s59, s31
	global_load_lds_dwordx4 v[216:217], off
	v_lshl_add_u64 v[216:217], s[24:25], 0, v[134:135]
	s_mov_b32 m0, s26
	s_nop 0
	global_load_lds_dwordx4 v[216:217], off
	v_lshl_add_u64 v[216:217], s[24:25], 0, v[130:131]
	s_add_i32 m0, s26, 0x2000
	s_nop 0
	global_load_lds_dwordx4 v[216:217], off
	v_lshl_add_u64 v[216:217], v[220:221], 0, s[8:9]
	s_mov_b32 m0, s39
	s_nop 0
	global_load_lds_dwordx4 v[216:217], off
	v_lshl_add_u64 v[216:217], v[222:223], 0, s[8:9]
	s_mov_b32 m0, s40
	s_nop 0
	global_load_lds_dwordx4 v[216:217], off
	s_waitcnt vmcnt(8)
	s_waitcnt lgkmcnt(0)
	s_barrier
	s_setprio 1
	s_waitcnt lgkmcnt(0)
	v_mfma_f32_16x16x32_bf16 v[62:65], v[146:149], v[184:187], v[62:65]
	v_mfma_f32_16x16x32_bf16 v[58:61], v[160:163], v[184:187], v[58:61]
	v_mfma_f32_16x16x32_bf16 v[54:57], v[146:149], v[192:195], v[54:57]
	v_mfma_f32_16x16x32_bf16 v[46:49], v[160:163], v[192:195], v[46:49]
	v_mfma_f32_16x16x32_bf16 v[38:41], v[146:149], v[200:203], v[38:41]
	v_mfma_f32_16x16x32_bf16 v[30:33], v[160:163], v[200:203], v[30:33]
	v_mfma_f32_16x16x32_bf16 v[22:25], v[146:149], v[208:211], v[22:25]
	v_mfma_f32_16x16x32_bf16 v[14:17], v[160:163], v[208:211], v[14:17]
	v_mfma_f32_16x16x32_bf16 v[62:65], v[156:159], v[188:191], v[62:65]
	v_mfma_f32_16x16x32_bf16 v[58:61], v[164:167], v[188:191], v[58:61]
	v_mfma_f32_16x16x32_bf16 v[54:57], v[156:159], v[196:199], v[54:57]
	v_mfma_f32_16x16x32_bf16 v[46:49], v[164:167], v[196:199], v[46:49]
	v_mfma_f32_16x16x32_bf16 v[38:41], v[156:159], v[204:207], v[38:41]
	v_mfma_f32_16x16x32_bf16 v[30:33], v[164:167], v[204:207], v[30:33]
	v_mfma_f32_16x16x32_bf16 v[22:25], v[156:159], v[212:215], v[22:25]
	v_mfma_f32_16x16x32_bf16 v[14:17], v[164:167], v[212:215], v[14:17]
	s_setprio 0
	s_setprio 1
	v_mfma_f32_16x16x32_bf16 v[50:53], v[168:171], v[184:187], v[50:53]
	v_mfma_f32_16x16x32_bf16 v[42:45], v[176:179], v[184:187], v[42:45]
	v_mfma_f32_16x16x32_bf16 v[34:37], v[168:171], v[192:195], v[34:37]
	v_mfma_f32_16x16x32_bf16 v[26:29], v[176:179], v[192:195], v[26:29]
	v_mfma_f32_16x16x32_bf16 v[18:21], v[168:171], v[200:203], v[18:21]
	v_mfma_f32_16x16x32_bf16 v[10:13], v[176:179], v[200:203], v[10:13]
	v_mfma_f32_16x16x32_bf16 v[6:9], v[168:171], v[208:211], v[6:9]
	v_mfma_f32_16x16x32_bf16 v[2:5], v[176:179], v[208:211], v[2:5]
	v_mfma_f32_16x16x32_bf16 v[50:53], v[172:175], v[188:191], v[50:53]
	v_mfma_f32_16x16x32_bf16 v[42:45], v[180:183], v[188:191], v[42:45]
	v_mfma_f32_16x16x32_bf16 v[34:37], v[172:175], v[196:199], v[34:37]
	v_mfma_f32_16x16x32_bf16 v[26:29], v[180:183], v[196:199], v[26:29]
	v_mfma_f32_16x16x32_bf16 v[18:21], v[172:175], v[204:207], v[18:21]
	v_mfma_f32_16x16x32_bf16 v[10:13], v[180:183], v[204:207], v[10:13]
	v_mfma_f32_16x16x32_bf16 v[6:9], v[172:175], v[212:215], v[6:9]
	v_mfma_f32_16x16x32_bf16 v[2:5], v[180:183], v[212:215], v[2:5]
	s_setprio 0
	s_barrier
	s_add_i32 s57, s57, 2
	s_add_u32 s22, s22, 0x100
	s_addc_u32 s23, s23, 0
	s_add_u32 s55, s55, 0x100
	s_addc_u32 s56, s56, 0
	s_mov_b32 s100, 0
	s_cmp_gt_u32 s57, 13
	s_cbranch_scc0 .LBB0_855
	s_and_b64 vcc, exec, s[10:11]
	s_cbranch_vccz .LBB0_858
	s_barrier
.LBB0_858:
	v_lshl_or_b32 v148, s52, 8, v151
	v_lshl_add_u32 v155, s20, 8, v1
	v_ashrrev_i32_e32 v149, 31, v148
	v_mov_b64_e32 v[146:147], s[6:7]
	v_mad_i64_i32 v[156:157], s[22:23], v155, s47, v[146:147]
	v_lshlrev_b64 v[148:149], 1, v[148:149]
	v_lshl_add_u64 v[156:157], v[156:157], 0, v[148:149]
	v_cvt_pk_bf16_f32 v126, v126, v127
	v_cvt_pk_bf16_f32 v127, v128, v129
	v_cvt_pk_bf16_f32 v128, v122, v123
	v_cvt_pk_bf16_f32 v129, v124, v125
	global_store_dwordx4 v[156:157], v[126:129], off
	v_cvt_pk_bf16_f32 v114, v114, v115
	v_cvt_pk_bf16_f32 v115, v116, v117
	v_cvt_pk_bf16_f32 v116, v106, v107
	v_or_b32_e32 v106, 16, v155
	v_mad_i64_i32 v[106:107], s[22:23], v106, s47, v[146:147]
	v_cvt_pk_bf16_f32 v117, v108, v109
	global_store_dwordx4 v[156:157], v[114:117], off offset:256
	s_andn2_b64 vcc, exec, s[0:1]
	s_mov_b64 s[0:1], -1
	v_lshl_add_u64 v[114:115], v[106:107], 0, v[148:149]
	v_cvt_pk_bf16_f32 v106, v118, v119
	v_cvt_pk_bf16_f32 v107, v120, v121
	v_cvt_pk_bf16_f32 v108, v110, v111
	v_cvt_pk_bf16_f32 v109, v112, v113
	global_store_dwordx4 v[114:115], v[106:109], off
	v_cvt_pk_bf16_f32 v98, v98, v99
	v_cvt_pk_bf16_f32 v99, v100, v101
	v_cvt_pk_bf16_f32 v100, v90, v91
	v_or_b32_e32 v90, 32, v155
	v_mad_i64_i32 v[90:91], s[22:23], v90, s47, v[146:147]
	v_cvt_pk_bf16_f32 v101, v92, v93
	global_store_dwordx4 v[114:115], v[98:101], off offset:256
	s_nop 1
	v_lshl_add_u64 v[98:99], v[90:91], 0, v[148:149]
	v_cvt_pk_bf16_f32 v90, v102, v103
	v_cvt_pk_bf16_f32 v91, v104, v105
	v_cvt_pk_bf16_f32 v92, v94, v95
	v_cvt_pk_bf16_f32 v93, v96, v97
	global_store_dwordx4 v[98:99], v[90:93], off
	v_cvt_pk_bf16_f32 v82, v82, v83
	v_cvt_pk_bf16_f32 v83, v84, v85
	v_cvt_pk_bf16_f32 v84, v74, v75
	v_or_b32_e32 v74, 48, v155
	v_mad_i64_i32 v[74:75], s[22:23], v74, s47, v[146:147]
	v_cvt_pk_bf16_f32 v85, v76, v77
	global_store_dwordx4 v[98:99], v[82:85], off offset:256
	s_nop 1
	v_lshl_add_u64 v[82:83], v[74:75], 0, v[148:149]
	v_cvt_pk_bf16_f32 v74, v86, v87
	v_cvt_pk_bf16_f32 v75, v88, v89
	v_cvt_pk_bf16_f32 v76, v78, v79
	v_cvt_pk_bf16_f32 v77, v80, v81
	global_store_dwordx4 v[82:83], v[74:77], off
	v_cvt_pk_bf16_f32 v70, v70, v71
	v_cvt_pk_bf16_f32 v71, v72, v73
	v_cvt_pk_bf16_f32 v72, v66, v67
	v_add_u32_e32 v66, 0x80, v155
	v_mad_i64_i32 v[66:67], s[22:23], v66, s47, v[146:147]
	v_lshl_add_u64 v[66:67], v[66:67], 0, v[148:149]
	v_cvt_pk_bf16_f32 v73, v68, v69
	global_store_dwordx4 v[82:83], v[70:73], off offset:256
	v_cvt_pk_bf16_f32 v62, v62, v63
	v_cvt_pk_bf16_f32 v63, v64, v65
	v_cvt_pk_bf16_f32 v64, v58, v59
	v_cvt_pk_bf16_f32 v65, v60, v61
	global_store_dwordx4 v[66:67], v[62:65], off
	v_cvt_pk_bf16_f32 v50, v50, v51
	v_cvt_pk_bf16_f32 v51, v52, v53
	v_cvt_pk_bf16_f32 v52, v42, v43
	v_add_u32_e32 v42, 0x90, v155
	v_mad_i64_i32 v[42:43], s[22:23], v42, s47, v[146:147]
	v_cvt_pk_bf16_f32 v53, v44, v45
	global_store_dwordx4 v[66:67], v[50:53], off offset:256
	s_nop 1
	v_lshl_add_u64 v[50:51], v[42:43], 0, v[148:149]
	v_cvt_pk_bf16_f32 v42, v54, v55
	v_cvt_pk_bf16_f32 v43, v56, v57
	v_cvt_pk_bf16_f32 v44, v46, v47
	v_cvt_pk_bf16_f32 v45, v48, v49
	global_store_dwordx4 v[50:51], v[42:45], off
	v_cvt_pk_bf16_f32 v34, v34, v35
	v_cvt_pk_bf16_f32 v35, v36, v37
	v_cvt_pk_bf16_f32 v36, v26, v27
	v_add_u32_e32 v26, 0xa0, v155
	v_mad_i64_i32 v[26:27], s[22:23], v26, s47, v[146:147]
	v_cvt_pk_bf16_f32 v37, v28, v29
	global_store_dwordx4 v[50:51], v[34:37], off offset:256
	s_nop 1
	v_lshl_add_u64 v[34:35], v[26:27], 0, v[148:149]
	v_cvt_pk_bf16_f32 v26, v38, v39
	v_cvt_pk_bf16_f32 v27, v40, v41
	v_cvt_pk_bf16_f32 v28, v30, v31
	v_cvt_pk_bf16_f32 v29, v32, v33
	global_store_dwordx4 v[34:35], v[26:29], off
	v_cvt_pk_bf16_f32 v18, v18, v19
	v_cvt_pk_bf16_f32 v19, v20, v21
	v_cvt_pk_bf16_f32 v20, v10, v11
	v_add_u32_e32 v10, 0xb0, v155
	v_mad_i64_i32 v[10:11], s[22:23], v10, s47, v[146:147]
	v_cvt_pk_bf16_f32 v21, v12, v13
	global_store_dwordx4 v[34:35], v[18:21], off offset:256
	s_nop 1
	v_lshl_add_u64 v[18:19], v[10:11], 0, v[148:149]
	v_cvt_pk_bf16_f32 v10, v22, v23
	v_cvt_pk_bf16_f32 v11, v24, v25
	v_cvt_pk_bf16_f32 v12, v14, v15
	v_cvt_pk_bf16_f32 v13, v16, v17
	global_store_dwordx4 v[18:19], v[10:13], off
	v_cvt_pk_bf16_f32 v6, v6, v7
	v_cvt_pk_bf16_f32 v7, v8, v9
	v_cvt_pk_bf16_f32 v8, v2, v3
	v_cvt_pk_bf16_f32 v9, v4, v5
	global_store_dwordx4 v[18:19], v[6:9], off offset:256
	s_mov_b32 s100, 1
	s_cbranch_vccnz .LBB0_851
	s_andn2_b64 vcc, exec, s[4:5]
	s_cbranch_vccnz .LBB0_850
	s_barrier
	s_branch .LBB0_850

.LBB0_1013:
	s_mov_b32 s100, 0
	s_cmp_lt_i32 s72, 16
	s_cselect_b64 s[0:1], -1, 0
	s_cmp_gt_i32 s73, 15
	s_cselect_b64 s[4:5], -1, 0
	s_and_b64 s[0:1], s[0:1], s[4:5]
	s_andn2_b64 vcc, exec, s[0:1]
	s_cbranch_vccnz .LBB0_1088
	s_cmpk_gt_i32 s2, 0x1ff
	v_readfirstlane_b32 s12, v0
	s_cbranch_scc1 .LBB0_1038
	s_ashr_i32 s3, s2, 31
	s_lshr_b32 s0, s3, 29
	s_add_i32 s5, s2, s0
	s_and_b32 s0, s5, -8
	s_sub_i32 s6, s2, s0
	s_cmp_gt_i32 s6, -1
	s_cbranch_scc0 .LBB0_1017
	s_lshl_b32 s4, s6, 6
	s_cbranch_execz .LBB0_1018
	s_branch .LBB0_1019

.LBB0_1031:
	ds_read_b128 v[154:157], v150
	ds_read_b128 v[158:161], v150 offset:1024
	ds_read_b128 v[162:165], v150 offset:2048
	ds_read_b128 v[166:169], v150 offset:3072
	ds_read_b128 v[170:173], v151
	ds_read_b128 v[174:177], v151 offset:1024
	ds_read_b128 v[178:181], v151 offset:2048
	ds_read_b128 v[182:185], v151 offset:3072
	s_add_u32 s34, s30, 0xfffc0080
	s_addc_u32 s35, s31, -1
	s_cmp_eq_u32 s65, 12
	s_cselect_b32 s37, s23, s35
	s_cselect_b32 s36, s61, s34
	s_cselect_b32 s35, s21, s64
	s_cselect_b32 s34, s62, s63
	v_lshl_add_u64 v[146:147], s[30:31], 0, v[138:139]
	s_add_i32 m0, s29, 0xc000
	ds_read_b128 v[186:189], v152
	ds_read_b128 v[190:193], v152 offset:1024
	ds_read_b128 v[194:197], v152 offset:2048
	ds_read_b128 v[198:201], v152 offset:3072
	ds_read_b128 v[202:205], v152 offset:4096
	ds_read_b128 v[206:209], v152 offset:5120
	ds_read_b128 v[210:213], v152 offset:6144
	ds_read_b128 v[214:217], v152 offset:7168
	global_load_lds_dwordx4 v[146:147], off
	v_lshl_add_u64 v[146:147], s[30:31], 0, v[140:141]
	s_add_i32 m0, s29, 0xe000
	s_nop 0
	global_load_lds_dwordx4 v[146:147], off
	s_cmp_lg_u32 s100, 0
	s_cbranch_scc1 .Lrw4_0a
	s_waitcnt vmcnt(8)
	s_branch .Lrw4_0b

.Lrw4_0b:
	s_waitcnt lgkmcnt(0)
	s_barrier
	s_setprio 1
	s_waitcnt lgkmcnt(0)
	v_mfma_f32_16x16x32_bf16 v[126:129], v[154:157], v[186:189], v[126:129]
	v_mfma_f32_16x16x32_bf16 v[122:125], v[162:165], v[186:189], v[122:125]
	v_mfma_f32_16x16x32_bf16 v[118:121], v[154:157], v[194:197], v[118:121]
	v_mfma_f32_16x16x32_bf16 v[110:113], v[162:165], v[194:197], v[110:113]
	v_mfma_f32_16x16x32_bf16 v[102:105], v[154:157], v[202:205], v[102:105]
	v_mfma_f32_16x16x32_bf16 v[94:97], v[162:165], v[202:205], v[94:97]
	v_mfma_f32_16x16x32_bf16 v[86:89], v[154:157], v[210:213], v[86:89]
	v_mfma_f32_16x16x32_bf16 v[78:81], v[162:165], v[210:213], v[78:81]
	v_mfma_f32_16x16x32_bf16 v[126:129], v[158:161], v[190:193], v[126:129]
	v_mfma_f32_16x16x32_bf16 v[122:125], v[166:169], v[190:193], v[122:125]
	v_mfma_f32_16x16x32_bf16 v[118:121], v[158:161], v[198:201], v[118:121]
	v_mfma_f32_16x16x32_bf16 v[110:113], v[166:169], v[198:201], v[110:113]
	v_mfma_f32_16x16x32_bf16 v[102:105], v[158:161], v[206:209], v[102:105]
	v_mfma_f32_16x16x32_bf16 v[94:97], v[166:169], v[206:209], v[94:97]
	v_mfma_f32_16x16x32_bf16 v[86:89], v[158:161], v[214:217], v[86:89]
	v_mfma_f32_16x16x32_bf16 v[78:81], v[166:169], v[214:217], v[78:81]
	s_setprio 0
	s_setprio 1
	v_mfma_f32_16x16x32_bf16 v[114:117], v[170:173], v[186:189], v[114:117]
	v_mfma_f32_16x16x32_bf16 v[106:109], v[178:181], v[186:189], v[106:109]
	v_mfma_f32_16x16x32_bf16 v[98:101], v[170:173], v[194:197], v[98:101]
	v_mfma_f32_16x16x32_bf16 v[90:93], v[178:181], v[194:197], v[90:93]
	v_mfma_f32_16x16x32_bf16 v[82:85], v[170:173], v[202:205], v[82:85]
	v_mfma_f32_16x16x32_bf16 v[74:77], v[178:181], v[202:205], v[74:77]
	v_mfma_f32_16x16x32_bf16 v[70:73], v[170:173], v[210:213], v[70:73]
	v_mfma_f32_16x16x32_bf16 v[66:69], v[178:181], v[210:213], v[66:69]
	v_mfma_f32_16x16x32_bf16 v[114:117], v[174:177], v[190:193], v[114:117]
	v_mfma_f32_16x16x32_bf16 v[106:109], v[182:185], v[190:193], v[106:109]
	v_mfma_f32_16x16x32_bf16 v[98:101], v[174:177], v[198:201], v[98:101]
	v_mfma_f32_16x16x32_bf16 v[90:93], v[182:185], v[198:201], v[90:93]
	v_mfma_f32_16x16x32_bf16 v[82:85], v[174:177], v[206:209], v[82:85]
	v_mfma_f32_16x16x32_bf16 v[74:77], v[182:185], v[206:209], v[74:77]
	v_mfma_f32_16x16x32_bf16 v[70:73], v[174:177], v[214:217], v[70:73]
	v_mfma_f32_16x16x32_bf16 v[66:69], v[182:185], v[214:217], v[66:69]
	s_setprio 0
	s_barrier
	s_add_i32 s66, s54, s41
	v_lshl_add_u64 v[146:147], s[34:35], 0, v[132:133]
	s_mov_b32 m0, s66
	ds_read_b128 v[186:189], v152 offset:16384
	ds_read_b128 v[190:193], v152 offset:17408
	ds_read_b128 v[194:197], v152 offset:18432
	ds_read_b128 v[198:201], v152 offset:19456
	ds_read_b128 v[202:205], v152 offset:20480
	ds_read_b128 v[206:209], v152 offset:21504
	ds_read_b128 v[210:213], v152 offset:22528
	ds_read_b128 v[214:217], v152 offset:23552
	global_load_lds_dwordx4 v[146:147], off
	s_add_i32 m0, s66, 0x2000
	s_add_u32 s66, s34, 0x40000
	v_lshl_add_u64 v[218:219], s[34:35], 0, v[136:137]
	s_addc_u32 s67, s35, 0
	s_add_i32 s68, s55, s41
	global_load_lds_dwordx4 v[218:219], off
	v_lshl_add_u64 v[220:221], s[66:67], 0, v[132:133]
	s_mov_b32 m0, s68
	v_lshl_add_u64 v[222:223], s[36:37], 0, v[134:135]
	global_load_lds_dwordx4 v[220:221], off
	v_lshl_add_u64 v[220:221], s[66:67], 0, v[136:137]
	s_add_i32 m0, s68, 0x2000
	s_nop 0
	global_load_lds_dwordx4 v[220:221], off
	v_lshl_add_u64 v[220:221], s[36:37], 0, v[130:131]
	s_mov_b32 m0, s29
	s_nop 0
	global_load_lds_dwordx4 v[220:221], off
	s_mov_b32 m0, s42
	s_nop 0
	global_load_lds_dwordx4 v[222:223], off
	s_cmp_lg_u32 s100, 0
	s_cbranch_scc1 .Lrw4_1a
	s_waitcnt vmcnt(8)
	s_branch .Lrw4_1b

.Lrw4_1b:
	s_waitcnt lgkmcnt(0)
	s_barrier
	s_setprio 1
	s_waitcnt lgkmcnt(0)
	v_mfma_f32_16x16x32_bf16 v[62:65], v[154:157], v[186:189], v[62:65]
	v_mfma_f32_16x16x32_bf16 v[58:61], v[162:165], v[186:189], v[58:61]
	v_mfma_f32_16x16x32_bf16 v[54:57], v[154:157], v[194:197], v[54:57]
	v_mfma_f32_16x16x32_bf16 v[46:49], v[162:165], v[194:197], v[46:49]
	v_mfma_f32_16x16x32_bf16 v[38:41], v[154:157], v[202:205], v[38:41]
	v_mfma_f32_16x16x32_bf16 v[30:33], v[162:165], v[202:205], v[30:33]
	v_mfma_f32_16x16x32_bf16 v[22:25], v[154:157], v[210:213], v[22:25]
	v_mfma_f32_16x16x32_bf16 v[14:17], v[162:165], v[210:213], v[14:17]
	v_mfma_f32_16x16x32_bf16 v[62:65], v[158:161], v[190:193], v[62:65]
	v_mfma_f32_16x16x32_bf16 v[58:61], v[166:169], v[190:193], v[58:61]
	v_mfma_f32_16x16x32_bf16 v[54:57], v[158:161], v[198:201], v[54:57]
	v_mfma_f32_16x16x32_bf16 v[46:49], v[166:169], v[198:201], v[46:49]
	v_mfma_f32_16x16x32_bf16 v[38:41], v[158:161], v[206:209], v[38:41]
	v_mfma_f32_16x16x32_bf16 v[30:33], v[166:169], v[206:209], v[30:33]
	v_mfma_f32_16x16x32_bf16 v[22:25], v[158:161], v[214:217], v[22:25]
	v_mfma_f32_16x16x32_bf16 v[14:17], v[166:169], v[214:217], v[14:17]
	s_setprio 0
	s_setprio 1
	v_mfma_f32_16x16x32_bf16 v[50:53], v[170:173], v[186:189], v[50:53]
	v_mfma_f32_16x16x32_bf16 v[42:45], v[178:181], v[186:189], v[42:45]
	v_mfma_f32_16x16x32_bf16 v[34:37], v[170:173], v[194:197], v[34:37]
	v_mfma_f32_16x16x32_bf16 v[26:29], v[178:181], v[194:197], v[26:29]
	v_mfma_f32_16x16x32_bf16 v[18:21], v[170:173], v[202:205], v[18:21]
	v_mfma_f32_16x16x32_bf16 v[10:13], v[178:181], v[202:205], v[10:13]
	v_mfma_f32_16x16x32_bf16 v[6:9], v[170:173], v[210:213], v[6:9]
	v_mfma_f32_16x16x32_bf16 v[2:5], v[178:181], v[210:213], v[2:5]
	v_mfma_f32_16x16x32_bf16 v[50:53], v[174:177], v[190:193], v[50:53]
	v_mfma_f32_16x16x32_bf16 v[42:45], v[182:185], v[190:193], v[42:45]
	v_mfma_f32_16x16x32_bf16 v[34:37], v[174:177], v[198:201], v[34:37]
	v_mfma_f32_16x16x32_bf16 v[26:29], v[182:185], v[198:201], v[26:29]
	v_mfma_f32_16x16x32_bf16 v[18:21], v[174:177], v[206:209], v[18:21]
	v_mfma_f32_16x16x32_bf16 v[10:13], v[182:185], v[206:209], v[10:13]
	v_mfma_f32_16x16x32_bf16 v[6:9], v[174:177], v[214:217], v[6:9]
	v_mfma_f32_16x16x32_bf16 v[2:5], v[182:185], v[214:217], v[2:5]
	s_setprio 0
	s_barrier
	s_add_i32 s66, 0, 0x18000
	v_add_u32_e32 v153, s66, v148
	s_add_i32 s67, 0, 0x1c000
	ds_read_b128 v[154:157], v153
	ds_read_b128 v[158:161], v153 offset:1024
	ds_read_b128 v[162:165], v153 offset:2048
	ds_read_b128 v[166:169], v153 offset:3072
	v_add_u32_e32 v153, s67, v148
	ds_read_b128 v[170:173], v153
	ds_read_b128 v[174:177], v153 offset:1024
	ds_read_b128 v[178:181], v153 offset:2048
	ds_read_b128 v[182:185], v153 offset:3072
	s_add_u32 s36, s36, 0x40000
	s_addc_u32 s37, s37, 0
	s_mov_b32 m0, s43
	v_lshl_add_u64 v[224:225], s[36:37], 0, v[130:131]
	ds_read_b128 v[186:189], v152 offset:32768
	ds_read_b128 v[190:193], v152 offset:33792
	ds_read_b128 v[194:197], v152 offset:34816
	ds_read_b128 v[198:201], v152 offset:35840
	ds_read_b128 v[202:205], v152 offset:36864
	ds_read_b128 v[206:209], v152 offset:37888
	ds_read_b128 v[210:213], v152 offset:38912
	ds_read_b128 v[214:217], v152 offset:39936
	global_load_lds_dwordx4 v[224:225], off
	v_lshl_add_u64 v[224:225], s[36:37], 0, v[134:135]
	s_mov_b32 m0, s44
	s_nop 0
	global_load_lds_dwordx4 v[224:225], off
	s_waitcnt vmcnt(8)
	s_waitcnt lgkmcnt(0)
	s_barrier
	s_setprio 1
	s_waitcnt lgkmcnt(0)
	v_mfma_f32_16x16x32_bf16 v[126:129], v[154:157], v[186:189], v[126:129]
	v_mfma_f32_16x16x32_bf16 v[122:125], v[162:165], v[186:189], v[122:125]
	v_mfma_f32_16x16x32_bf16 v[118:121], v[154:157], v[194:197], v[118:121]
	v_mfma_f32_16x16x32_bf16 v[110:113], v[162:165], v[194:197], v[110:113]
	v_mfma_f32_16x16x32_bf16 v[102:105], v[154:157], v[202:205], v[102:105]
	v_mfma_f32_16x16x32_bf16 v[94:97], v[162:165], v[202:205], v[94:97]
	v_mfma_f32_16x16x32_bf16 v[86:89], v[154:157], v[210:213], v[86:89]
	v_mfma_f32_16x16x32_bf16 v[78:81], v[162:165], v[210:213], v[78:81]
	v_mfma_f32_16x16x32_bf16 v[126:129], v[158:161], v[190:193], v[126:129]
	v_mfma_f32_16x16x32_bf16 v[122:125], v[166:169], v[190:193], v[122:125]
	v_mfma_f32_16x16x32_bf16 v[118:121], v[158:161], v[198:201], v[118:121]
	v_mfma_f32_16x16x32_bf16 v[110:113], v[166:169], v[198:201], v[110:113]
	v_mfma_f32_16x16x32_bf16 v[102:105], v[158:161], v[206:209], v[102:105]
	v_mfma_f32_16x16x32_bf16 v[94:97], v[166:169], v[206:209], v[94:97]
	v_mfma_f32_16x16x32_bf16 v[86:89], v[158:161], v[214:217], v[86:89]
	v_mfma_f32_16x16x32_bf16 v[78:81], v[166:169], v[214:217], v[78:81]
	s_setprio 0
	s_setprio 1
	v_mfma_f32_16x16x32_bf16 v[114:117], v[170:173], v[186:189], v[114:117]
	v_mfma_f32_16x16x32_bf16 v[106:109], v[178:181], v[186:189], v[106:109]
	v_mfma_f32_16x16x32_bf16 v[98:101], v[170:173], v[194:197], v[98:101]
	v_mfma_f32_16x16x32_bf16 v[90:93], v[178:181], v[194:197], v[90:93]
	v_mfma_f32_16x16x32_bf16 v[82:85], v[170:173], v[202:205], v[82:85]
	v_mfma_f32_16x16x32_bf16 v[74:77], v[178:181], v[202:205], v[74:77]
	v_mfma_f32_16x16x32_bf16 v[70:73], v[170:173], v[210:213], v[70:73]
	v_mfma_f32_16x16x32_bf16 v[66:69], v[178:181], v[210:213], v[66:69]
	v_mfma_f32_16x16x32_bf16 v[114:117], v[174:177], v[190:193], v[114:117]
	v_mfma_f32_16x16x32_bf16 v[106:109], v[182:185], v[190:193], v[106:109]
	v_mfma_f32_16x16x32_bf16 v[98:101], v[174:177], v[198:201], v[98:101]
	v_mfma_f32_16x16x32_bf16 v[90:93], v[182:185], v[198:201], v[90:93]
	v_mfma_f32_16x16x32_bf16 v[82:85], v[174:177], v[206:209], v[82:85]
	v_mfma_f32_16x16x32_bf16 v[74:77], v[182:185], v[206:209], v[74:77]
	v_mfma_f32_16x16x32_bf16 v[70:73], v[174:177], v[214:217], v[70:73]
	v_mfma_f32_16x16x32_bf16 v[66:69], v[182:185], v[214:217], v[66:69]
	s_setprio 0
	s_barrier
	s_add_i32 s36, s66, s41
	v_lshl_add_u64 v[146:147], v[146:147], 0, s[10:11]
	s_mov_b32 m0, s36
	ds_read_b128 v[186:189], v152 offset:49152
	ds_read_b128 v[190:193], v152 offset:50176
	ds_read_b128 v[194:197], v152 offset:51200
	ds_read_b128 v[198:201], v152 offset:52224
	ds_read_b128 v[202:205], v152 offset:53248
	ds_read_b128 v[206:209], v152 offset:54272
	ds_read_b128 v[210:213], v152 offset:55296
	ds_read_b128 v[214:217], v152 offset:56320
	global_load_lds_dwordx4 v[146:147], off
	s_add_i32 m0, s36, 0x2000
	s_add_u32 s34, s34, 0x40080
	v_lshl_add_u64 v[146:147], v[218:219], 0, s[10:11]
	s_addc_u32 s35, s35, 0
	s_add_i32 s36, s67, s41
	global_load_lds_dwordx4 v[146:147], off
	v_lshl_add_u64 v[146:147], s[34:35], 0, v[132:133]
	s_mov_b32 m0, s36
	s_nop 0
	global_load_lds_dwordx4 v[146:147], off
	v_lshl_add_u64 v[146:147], s[34:35], 0, v[136:137]
	s_add_i32 m0, s36, 0x2000
	s_nop 0
	global_load_lds_dwordx4 v[146:147], off
	v_lshl_add_u64 v[146:147], v[220:221], 0, s[10:11]
	s_mov_b32 m0, s46
	s_nop 0
	global_load_lds_dwordx4 v[146:147], off
	v_lshl_add_u64 v[146:147], v[222:223], 0, s[10:11]
	s_mov_b32 m0, s47
	s_nop 0
	global_load_lds_dwordx4 v[146:147], off
	s_waitcnt vmcnt(8)
	s_waitcnt lgkmcnt(0)
	s_barrier
	s_setprio 1
	s_waitcnt lgkmcnt(0)
	v_mfma_f32_16x16x32_bf16 v[62:65], v[154:157], v[186:189], v[62:65]
	v_mfma_f32_16x16x32_bf16 v[58:61], v[162:165], v[186:189], v[58:61]
	v_mfma_f32_16x16x32_bf16 v[54:57], v[154:157], v[194:197], v[54:57]
	v_mfma_f32_16x16x32_bf16 v[46:49], v[162:165], v[194:197], v[46:49]
	v_mfma_f32_16x16x32_bf16 v[38:41], v[154:157], v[202:205], v[38:41]
	v_mfma_f32_16x16x32_bf16 v[30:33], v[162:165], v[202:205], v[30:33]
	v_mfma_f32_16x16x32_bf16 v[22:25], v[154:157], v[210:213], v[22:25]
	v_mfma_f32_16x16x32_bf16 v[14:17], v[162:165], v[210:213], v[14:17]
	v_mfma_f32_16x16x32_bf16 v[62:65], v[158:161], v[190:193], v[62:65]
	v_mfma_f32_16x16x32_bf16 v[58:61], v[166:169], v[190:193], v[58:61]
	v_mfma_f32_16x16x32_bf16 v[54:57], v[158:161], v[198:201], v[54:57]
	v_mfma_f32_16x16x32_bf16 v[46:49], v[166:169], v[198:201], v[46:49]
	v_mfma_f32_16x16x32_bf16 v[38:41], v[158:161], v[206:209], v[38:41]
	v_mfma_f32_16x16x32_bf16 v[30:33], v[166:169], v[206:209], v[30:33]
	v_mfma_f32_16x16x32_bf16 v[22:25], v[158:161], v[214:217], v[22:25]
	v_mfma_f32_16x16x32_bf16 v[14:17], v[166:169], v[214:217], v[14:17]
	s_setprio 0
	s_setprio 1
	v_mfma_f32_16x16x32_bf16 v[50:53], v[170:173], v[186:189], v[50:53]
	v_mfma_f32_16x16x32_bf16 v[42:45], v[178:181], v[186:189], v[42:45]
	v_mfma_f32_16x16x32_bf16 v[34:37], v[170:173], v[194:197], v[34:37]
	v_mfma_f32_16x16x32_bf16 v[26:29], v[178:181], v[194:197], v[26:29]
	v_mfma_f32_16x16x32_bf16 v[18:21], v[170:173], v[202:205], v[18:21]
	v_mfma_f32_16x16x32_bf16 v[10:13], v[178:181], v[202:205], v[10:13]
	v_mfma_f32_16x16x32_bf16 v[6:9], v[170:173], v[210:213], v[6:9]
	v_mfma_f32_16x16x32_bf16 v[2:5], v[178:181], v[210:213], v[2:5]
	v_mfma_f32_16x16x32_bf16 v[50:53], v[174:177], v[190:193], v[50:53]
	v_mfma_f32_16x16x32_bf16 v[42:45], v[182:185], v[190:193], v[42:45]
	v_mfma_f32_16x16x32_bf16 v[34:37], v[174:177], v[198:201], v[34:37]
	v_mfma_f32_16x16x32_bf16 v[26:29], v[182:185], v[198:201], v[26:29]
	v_mfma_f32_16x16x32_bf16 v[18:21], v[174:177], v[206:209], v[18:21]
	v_mfma_f32_16x16x32_bf16 v[10:13], v[182:185], v[206:209], v[10:13]
	v_mfma_f32_16x16x32_bf16 v[6:9], v[174:177], v[214:217], v[6:9]
	v_mfma_f32_16x16x32_bf16 v[2:5], v[182:185], v[214:217], v[2:5]
	s_setprio 0
	s_barrier
	s_add_i32 s65, s65, 2
	s_add_u32 s30, s30, 0x100
	s_addc_u32 s31, s31, 0
	s_add_u32 s63, s63, 0x100
	s_addc_u32 s64, s64, 0
	s_mov_b32 s100, 0
	s_cmp_gt_u32 s65, 13
	s_cbranch_scc0 .LBB0_1031
	s_and_b64 vcc, exec, s[12:13]
	s_cbranch_vccz .LBB0_1034
	s_barrier
.LBB0_1034:
	v_lshl_add_u32 v154, s28, 8, v1
	v_lshl_or_b32 v146, s60, 8, v149
	v_ashrrev_i32_e32 v155, 31, v154
	v_ashrrev_i32_e32 v147, 31, v146
	v_lshlrev_b64 v[156:157], 11, v[154:155]
	v_lshl_add_u64 v[156:157], s[8:9], 0, v[156:157]
	v_lshlrev_b64 v[158:159], 1, v[146:147]
	v_lshl_add_u64 v[146:147], v[156:157], 0, v[158:159]
	v_cvt_pk_bf16_f32 v126, v126, v127
	v_cvt_pk_bf16_f32 v127, v128, v129
	v_cvt_pk_bf16_f32 v128, v122, v123
	v_cvt_pk_bf16_f32 v129, v124, v125
	global_store_dwordx4 v[146:147], v[126:129], off
	v_cvt_pk_bf16_f32 v114, v114, v115
	v_cvt_pk_bf16_f32 v115, v116, v117
	v_cvt_pk_bf16_f32 v116, v106, v107
	v_or_b32_e32 v106, 16, v154
	v_ashrrev_i32_e32 v107, 31, v106
	v_lshlrev_b64 v[106:107], 11, v[106:107]
	v_lshl_add_u64 v[106:107], s[8:9], 0, v[106:107]
	v_cvt_pk_bf16_f32 v117, v108, v109
	global_store_dwordx4 v[146:147], v[114:117], off offset:256
	s_nop 1
	v_lshl_add_u64 v[114:115], v[106:107], 0, v[158:159]
	v_cvt_pk_bf16_f32 v106, v118, v119
	v_cvt_pk_bf16_f32 v107, v120, v121
	v_cvt_pk_bf16_f32 v108, v110, v111
	v_cvt_pk_bf16_f32 v109, v112, v113
	global_store_dwordx4 v[114:115], v[106:109], off
	v_cvt_pk_bf16_f32 v98, v98, v99
	v_cvt_pk_bf16_f32 v99, v100, v101
	v_cvt_pk_bf16_f32 v100, v90, v91
	v_or_b32_e32 v90, 32, v154
	v_ashrrev_i32_e32 v91, 31, v90
	v_lshlrev_b64 v[90:91], 11, v[90:91]
	v_lshl_add_u64 v[90:91], s[8:9], 0, v[90:91]
	v_cvt_pk_bf16_f32 v101, v92, v93
	global_store_dwordx4 v[114:115], v[98:101], off offset:256
	s_nop 1
	v_lshl_add_u64 v[98:99], v[90:91], 0, v[158:159]
	v_cvt_pk_bf16_f32 v90, v102, v103
	v_cvt_pk_bf16_f32 v91, v104, v105
	v_cvt_pk_bf16_f32 v92, v94, v95
	v_cvt_pk_bf16_f32 v93, v96, v97
	global_store_dwordx4 v[98:99], v[90:93], off
	v_cvt_pk_bf16_f32 v82, v82, v83
	v_cvt_pk_bf16_f32 v83, v84, v85
	v_cvt_pk_bf16_f32 v84, v74, v75
	v_or_b32_e32 v74, 48, v154
	v_ashrrev_i32_e32 v75, 31, v74
	v_lshlrev_b64 v[74:75], 11, v[74:75]
	v_lshl_add_u64 v[74:75], s[8:9], 0, v[74:75]
	v_cvt_pk_bf16_f32 v85, v76, v77
	global_store_dwordx4 v[98:99], v[82:85], off offset:256
	s_nop 1
	v_lshl_add_u64 v[82:83], v[74:75], 0, v[158:159]
	v_cvt_pk_bf16_f32 v74, v86, v87
	v_cvt_pk_bf16_f32 v75, v88, v89
	v_cvt_pk_bf16_f32 v76, v78, v79
	v_cvt_pk_bf16_f32 v77, v80, v81
	global_store_dwordx4 v[82:83], v[74:77], off
	v_cvt_pk_bf16_f32 v70, v70, v71
	v_cvt_pk_bf16_f32 v71, v72, v73
	v_cvt_pk_bf16_f32 v72, v66, v67
	v_cvt_pk_bf16_f32 v73, v68, v69
	global_store_dwordx4 v[82:83], v[70:73], off offset:256
	v_cvt_pk_bf16_f32 v62, v62, v63
	v_cvt_pk_bf16_f32 v63, v64, v65
	v_cvt_pk_bf16_f32 v64, v58, v59
	v_add_co_u32_e32 v58, vcc, s56, v146
	v_lshl_add_u64 v[66:67], v[146:147], 0, s[4:5]
	s_nop 0
	v_addc_co_u32_e32 v59, vcc, 0, v147, vcc
	v_cvt_pk_bf16_f32 v65, v60, v61
	global_store_dwordx4 v[58:59], v[62:65], off
	v_cvt_pk_bf16_f32 v50, v50, v51
	v_cvt_pk_bf16_f32 v51, v52, v53
	v_cvt_pk_bf16_f32 v52, v42, v43
	v_cvt_pk_bf16_f32 v53, v44, v45
	global_store_dwordx4 v[66:67], v[50:53], off offset:256
	v_cvt_pk_bf16_f32 v42, v54, v55
	v_cvt_pk_bf16_f32 v43, v56, v57
	v_cvt_pk_bf16_f32 v44, v46, v47
	v_add_co_u32_e32 v46, vcc, s57, v146
	s_nop 0
	v_lshl_add_u64 v[50:51], v[146:147], 0, s[14:15]
	v_addc_co_u32_e32 v47, vcc, 0, v147, vcc
	v_cvt_pk_bf16_f32 v45, v48, v49
	global_store_dwordx4 v[46:47], v[42:45], off
	v_cvt_pk_bf16_f32 v34, v34, v35
	v_cvt_pk_bf16_f32 v35, v36, v37
	v_cvt_pk_bf16_f32 v36, v26, v27
	v_cvt_pk_bf16_f32 v37, v28, v29
	global_store_dwordx4 v[50:51], v[34:37], off offset:256
	v_cvt_pk_bf16_f32 v26, v38, v39
	v_cvt_pk_bf16_f32 v27, v40, v41
	v_cvt_pk_bf16_f32 v28, v30, v31
	v_add_co_u32_e32 v30, vcc, s58, v146
	s_nop 0
	v_lshl_add_u64 v[34:35], v[146:147], 0, s[16:17]
	v_addc_co_u32_e32 v31, vcc, 0, v147, vcc
	v_cvt_pk_bf16_f32 v29, v32, v33
	global_store_dwordx4 v[30:31], v[26:29], off
	v_cvt_pk_bf16_f32 v18, v18, v19
	v_cvt_pk_bf16_f32 v19, v20, v21
	v_cvt_pk_bf16_f32 v20, v10, v11
	v_cvt_pk_bf16_f32 v21, v12, v13
	global_store_dwordx4 v[34:35], v[18:21], off offset:256
	v_cvt_pk_bf16_f32 v10, v22, v23
	v_cvt_pk_bf16_f32 v11, v24, v25
	v_cvt_pk_bf16_f32 v12, v14, v15
	v_add_co_u32_e32 v14, vcc, s59, v146
	s_nop 0
	v_lshl_add_u64 v[18:19], v[146:147], 0, s[18:19]
	v_addc_co_u32_e32 v15, vcc, 0, v147, vcc
	s_andn2_b64 vcc, exec, s[0:1]
	s_mov_b64 s[0:1], -1
	v_cvt_pk_bf16_f32 v13, v16, v17
	global_store_dwordx4 v[14:15], v[10:13], off
	v_cvt_pk_bf16_f32 v6, v6, v7
	v_cvt_pk_bf16_f32 v7, v8, v9
	v_cvt_pk_bf16_f32 v8, v2, v3
	v_cvt_pk_bf16_f32 v9, v4, v5
	global_store_dwordx4 v[18:19], v[6:9], off offset:256
	s_mov_b32 s100, 1
	s_cbranch_vccnz .LBB0_1023
	s_andn2_b64 vcc, exec, s[6:7]
	s_cbranch_vccnz .LBB0_1022
	s_barrier
	s_branch .LBB0_1022

.LBB0_1148:
	s_mov_b32 s100, 0
	s_cmp_lt_i32 s72, 18
	s_cselect_b64 s[0:1], -1, 0
	s_cmp_gt_i32 s73, 17
	s_cselect_b64 s[4:5], -1, 0
	s_and_b64 s[0:1], s[0:1], s[4:5]
	s_andn2_b64 vcc, exec, s[0:1]
	s_cbranch_vccnz .LBB0_1223
	s_cmpk_gt_i32 s2, 0x7ff
	v_readfirstlane_b32 s10, v0
	s_cbranch_scc1 .LBB0_1173
	s_ashr_i32 s3, s2, 31
	s_lshr_b32 s0, s3, 29
	s_add_i32 s5, s2, s0
	s_and_b32 s0, s5, -8
	s_sub_i32 s6, s2, s0
	s_cmp_gt_i32 s6, -1
	s_cbranch_scc0 .LBB0_1152
	s_lshl_b32 s4, s6, 8
	s_cbranch_execz .LBB0_1153
	s_branch .LBB0_1154

.Lrw5_0b:
	s_waitcnt lgkmcnt(0)
	s_barrier
	s_setprio 1
	s_waitcnt lgkmcnt(0)
	v_mfma_f32_16x16x32_bf16 v[126:129], v[154:157], v[186:189], v[126:129]
	v_mfma_f32_16x16x32_bf16 v[122:125], v[162:165], v[186:189], v[122:125]
	v_mfma_f32_16x16x32_bf16 v[110:113], v[154:157], v[194:197], v[110:113]
	v_mfma_f32_16x16x32_bf16 v[106:109], v[162:165], v[194:197], v[106:109]
	v_mfma_f32_16x16x32_bf16 v[94:97], v[154:157], v[202:205], v[94:97]
	v_mfma_f32_16x16x32_bf16 v[90:93], v[162:165], v[202:205], v[90:93]
	v_mfma_f32_16x16x32_bf16 v[78:81], v[154:157], v[210:213], v[78:81]
	v_mfma_f32_16x16x32_bf16 v[74:77], v[162:165], v[210:213], v[74:77]
	v_mfma_f32_16x16x32_bf16 v[126:129], v[158:161], v[190:193], v[126:129]
	v_mfma_f32_16x16x32_bf16 v[122:125], v[166:169], v[190:193], v[122:125]
	v_mfma_f32_16x16x32_bf16 v[110:113], v[158:161], v[198:201], v[110:113]
	v_mfma_f32_16x16x32_bf16 v[106:109], v[166:169], v[198:201], v[106:109]
	v_mfma_f32_16x16x32_bf16 v[94:97], v[158:161], v[206:209], v[94:97]
	v_mfma_f32_16x16x32_bf16 v[90:93], v[166:169], v[206:209], v[90:93]
	v_mfma_f32_16x16x32_bf16 v[78:81], v[158:161], v[214:217], v[78:81]
	v_mfma_f32_16x16x32_bf16 v[74:77], v[166:169], v[214:217], v[74:77]
	s_setprio 0
	s_setprio 1
	v_mfma_f32_16x16x32_bf16 v[118:121], v[170:173], v[186:189], v[118:121]
	v_mfma_f32_16x16x32_bf16 v[114:117], v[178:181], v[186:189], v[114:117]
	v_mfma_f32_16x16x32_bf16 v[102:105], v[170:173], v[194:197], v[102:105]
	v_mfma_f32_16x16x32_bf16 v[98:101], v[178:181], v[194:197], v[98:101]
	v_mfma_f32_16x16x32_bf16 v[86:89], v[170:173], v[202:205], v[86:89]
	v_mfma_f32_16x16x32_bf16 v[82:85], v[178:181], v[202:205], v[82:85]
	v_mfma_f32_16x16x32_bf16 v[70:73], v[170:173], v[210:213], v[70:73]
	v_mfma_f32_16x16x32_bf16 v[66:69], v[178:181], v[210:213], v[66:69]
	v_mfma_f32_16x16x32_bf16 v[118:121], v[174:177], v[190:193], v[118:121]
	v_mfma_f32_16x16x32_bf16 v[114:117], v[182:185], v[190:193], v[114:117]
	v_mfma_f32_16x16x32_bf16 v[102:105], v[174:177], v[198:201], v[102:105]
	v_mfma_f32_16x16x32_bf16 v[98:101], v[182:185], v[198:201], v[98:101]
	v_mfma_f32_16x16x32_bf16 v[86:89], v[174:177], v[206:209], v[86:89]
	v_mfma_f32_16x16x32_bf16 v[82:85], v[182:185], v[206:209], v[82:85]
	v_mfma_f32_16x16x32_bf16 v[70:73], v[174:177], v[214:217], v[70:73]
	v_mfma_f32_16x16x32_bf16 v[66:69], v[182:185], v[214:217], v[66:69]
	s_setprio 0
	s_barrier
	s_add_i32 s66, s54, s41
	v_lshl_add_u64 v[146:147], s[34:35], 0, v[132:133]
	s_mov_b32 m0, s66
	ds_read_b128 v[186:189], v152 offset:16384
	ds_read_b128 v[190:193], v152 offset:17408
	ds_read_b128 v[194:197], v152 offset:18432
	ds_read_b128 v[198:201], v152 offset:19456
	ds_read_b128 v[202:205], v152 offset:20480
	ds_read_b128 v[206:209], v152 offset:21504
	ds_read_b128 v[210:213], v152 offset:22528
	ds_read_b128 v[214:217], v152 offset:23552
	global_load_lds_dwordx4 v[146:147], off
	s_add_i32 m0, s66, 0x2000
	s_add_u32 s66, s34, 0x40000
	v_lshl_add_u64 v[218:219], s[34:35], 0, v[136:137]
	s_addc_u32 s67, s35, 0
	s_add_i32 s68, s55, s41
	global_load_lds_dwordx4 v[218:219], off
	v_lshl_add_u64 v[220:221], s[66:67], 0, v[132:133]
	s_mov_b32 m0, s68
	v_lshl_add_u64 v[222:223], s[36:37], 0, v[134:135]
	global_load_lds_dwordx4 v[220:221], off
	v_lshl_add_u64 v[220:221], s[66:67], 0, v[136:137]
	s_add_i32 m0, s68, 0x2000
	s_nop 0
	global_load_lds_dwordx4 v[220:221], off
	v_lshl_add_u64 v[220:221], s[36:37], 0, v[130:131]
	s_mov_b32 m0, s29
	s_nop 0
	global_load_lds_dwordx4 v[220:221], off
	s_mov_b32 m0, s42
	s_nop 0
	global_load_lds_dwordx4 v[222:223], off
	s_cmp_lg_u32 s100, 0
	s_cbranch_scc1 .Lrw5_1a
	s_waitcnt vmcnt(8)
	s_branch .Lrw5_1b

.Lrw5_1b:
	s_waitcnt lgkmcnt(0)
	s_barrier
	s_setprio 1
	s_waitcnt lgkmcnt(0)
	v_mfma_f32_16x16x32_bf16 v[62:65], v[154:157], v[186:189], v[62:65]
	v_mfma_f32_16x16x32_bf16 v[58:61], v[162:165], v[186:189], v[58:61]
	v_mfma_f32_16x16x32_bf16 v[46:49], v[154:157], v[194:197], v[46:49]
	v_mfma_f32_16x16x32_bf16 v[42:45], v[162:165], v[194:197], v[42:45]
	v_mfma_f32_16x16x32_bf16 v[30:33], v[154:157], v[202:205], v[30:33]
	v_mfma_f32_16x16x32_bf16 v[26:29], v[162:165], v[202:205], v[26:29]
	v_mfma_f32_16x16x32_bf16 v[14:17], v[154:157], v[210:213], v[14:17]
	v_mfma_f32_16x16x32_bf16 v[10:13], v[162:165], v[210:213], v[10:13]
	v_mfma_f32_16x16x32_bf16 v[62:65], v[158:161], v[190:193], v[62:65]
	v_mfma_f32_16x16x32_bf16 v[58:61], v[166:169], v[190:193], v[58:61]
	v_mfma_f32_16x16x32_bf16 v[46:49], v[158:161], v[198:201], v[46:49]
	v_mfma_f32_16x16x32_bf16 v[42:45], v[166:169], v[198:201], v[42:45]
	v_mfma_f32_16x16x32_bf16 v[30:33], v[158:161], v[206:209], v[30:33]
	v_mfma_f32_16x16x32_bf16 v[26:29], v[166:169], v[206:209], v[26:29]
	v_mfma_f32_16x16x32_bf16 v[14:17], v[158:161], v[214:217], v[14:17]
	v_mfma_f32_16x16x32_bf16 v[10:13], v[166:169], v[214:217], v[10:13]
	s_setprio 0
	s_setprio 1
	v_mfma_f32_16x16x32_bf16 v[54:57], v[170:173], v[186:189], v[54:57]
	v_mfma_f32_16x16x32_bf16 v[50:53], v[178:181], v[186:189], v[50:53]
	v_mfma_f32_16x16x32_bf16 v[38:41], v[170:173], v[194:197], v[38:41]
	v_mfma_f32_16x16x32_bf16 v[34:37], v[178:181], v[194:197], v[34:37]
	v_mfma_f32_16x16x32_bf16 v[22:25], v[170:173], v[202:205], v[22:25]
	v_mfma_f32_16x16x32_bf16 v[18:21], v[178:181], v[202:205], v[18:21]
	v_mfma_f32_16x16x32_bf16 v[6:9], v[170:173], v[210:213], v[6:9]
	v_mfma_f32_16x16x32_bf16 v[2:5], v[178:181], v[210:213], v[2:5]
	v_mfma_f32_16x16x32_bf16 v[54:57], v[174:177], v[190:193], v[54:57]
	v_mfma_f32_16x16x32_bf16 v[50:53], v[182:185], v[190:193], v[50:53]
	v_mfma_f32_16x16x32_bf16 v[38:41], v[174:177], v[198:201], v[38:41]
	v_mfma_f32_16x16x32_bf16 v[34:37], v[182:185], v[198:201], v[34:37]
	v_mfma_f32_16x16x32_bf16 v[22:25], v[174:177], v[206:209], v[22:25]
	v_mfma_f32_16x16x32_bf16 v[18:21], v[182:185], v[206:209], v[18:21]
	v_mfma_f32_16x16x32_bf16 v[6:9], v[174:177], v[214:217], v[6:9]
	v_mfma_f32_16x16x32_bf16 v[2:5], v[182:185], v[214:217], v[2:5]
	s_setprio 0
	s_barrier
	s_add_i32 s66, 0, 0x18000
	v_add_u32_e32 v153, s66, v148
	s_add_i32 s67, 0, 0x1c000
	ds_read_b128 v[154:157], v153
	ds_read_b128 v[158:161], v153 offset:1024
	ds_read_b128 v[162:165], v153 offset:2048
	ds_read_b128 v[166:169], v153 offset:3072
	v_add_u32_e32 v153, s67, v148
	ds_read_b128 v[170:173], v153
	ds_read_b128 v[174:177], v153 offset:1024
	ds_read_b128 v[178:181], v153 offset:2048
	ds_read_b128 v[182:185], v153 offset:3072
	s_add_u32 s36, s36, 0x40000
	s_addc_u32 s37, s37, 0
	s_mov_b32 m0, s43
	v_lshl_add_u64 v[224:225], s[36:37], 0, v[130:131]
	ds_read_b128 v[186:189], v152 offset:32768
	ds_read_b128 v[190:193], v152 offset:33792
	ds_read_b128 v[194:197], v152 offset:34816
	ds_read_b128 v[198:201], v152 offset:35840
	ds_read_b128 v[202:205], v152 offset:36864
	ds_read_b128 v[206:209], v152 offset:37888
	ds_read_b128 v[210:213], v152 offset:38912
	ds_read_b128 v[214:217], v152 offset:39936
	global_load_lds_dwordx4 v[224:225], off
	v_lshl_add_u64 v[224:225], s[36:37], 0, v[134:135]
	s_mov_b32 m0, s44
	s_nop 0
	global_load_lds_dwordx4 v[224:225], off
	s_waitcnt vmcnt(8)
	s_waitcnt lgkmcnt(0)
	s_barrier
	s_setprio 1
	s_waitcnt lgkmcnt(0)
	v_mfma_f32_16x16x32_bf16 v[126:129], v[154:157], v[186:189], v[126:129]
	v_mfma_f32_16x16x32_bf16 v[122:125], v[162:165], v[186:189], v[122:125]
	v_mfma_f32_16x16x32_bf16 v[110:113], v[154:157], v[194:197], v[110:113]
	v_mfma_f32_16x16x32_bf16 v[106:109], v[162:165], v[194:197], v[106:109]
	v_mfma_f32_16x16x32_bf16 v[94:97], v[154:157], v[202:205], v[94:97]
	v_mfma_f32_16x16x32_bf16 v[90:93], v[162:165], v[202:205], v[90:93]
	v_mfma_f32_16x16x32_bf16 v[78:81], v[154:157], v[210:213], v[78:81]
	v_mfma_f32_16x16x32_bf16 v[74:77], v[162:165], v[210:213], v[74:77]
	v_mfma_f32_16x16x32_bf16 v[126:129], v[158:161], v[190:193], v[126:129]
	v_mfma_f32_16x16x32_bf16 v[122:125], v[166:169], v[190:193], v[122:125]
	v_mfma_f32_16x16x32_bf16 v[110:113], v[158:161], v[198:201], v[110:113]
	v_mfma_f32_16x16x32_bf16 v[106:109], v[166:169], v[198:201], v[106:109]
	v_mfma_f32_16x16x32_bf16 v[94:97], v[158:161], v[206:209], v[94:97]
	v_mfma_f32_16x16x32_bf16 v[90:93], v[166:169], v[206:209], v[90:93]
	v_mfma_f32_16x16x32_bf16 v[78:81], v[158:161], v[214:217], v[78:81]
	v_mfma_f32_16x16x32_bf16 v[74:77], v[166:169], v[214:217], v[74:77]
	s_setprio 0
	s_setprio 1
	v_mfma_f32_16x16x32_bf16 v[118:121], v[170:173], v[186:189], v[118:121]
	v_mfma_f32_16x16x32_bf16 v[114:117], v[178:181], v[186:189], v[114:117]
	v_mfma_f32_16x16x32_bf16 v[102:105], v[170:173], v[194:197], v[102:105]
	v_mfma_f32_16x16x32_bf16 v[98:101], v[178:181], v[194:197], v[98:101]
	v_mfma_f32_16x16x32_bf16 v[86:89], v[170:173], v[202:205], v[86:89]
	v_mfma_f32_16x16x32_bf16 v[82:85], v[178:181], v[202:205], v[82:85]
	v_mfma_f32_16x16x32_bf16 v[70:73], v[170:173], v[210:213], v[70:73]
	v_mfma_f32_16x16x32_bf16 v[66:69], v[178:181], v[210:213], v[66:69]
	v_mfma_f32_16x16x32_bf16 v[118:121], v[174:177], v[190:193], v[118:121]
	v_mfma_f32_16x16x32_bf16 v[114:117], v[182:185], v[190:193], v[114:117]
	v_mfma_f32_16x16x32_bf16 v[102:105], v[174:177], v[198:201], v[102:105]
	v_mfma_f32_16x16x32_bf16 v[98:101], v[182:185], v[198:201], v[98:101]
	v_mfma_f32_16x16x32_bf16 v[86:89], v[174:177], v[206:209], v[86:89]
	v_mfma_f32_16x16x32_bf16 v[82:85], v[182:185], v[206:209], v[82:85]
	v_mfma_f32_16x16x32_bf16 v[70:73], v[174:177], v[214:217], v[70:73]
	v_mfma_f32_16x16x32_bf16 v[66:69], v[182:185], v[214:217], v[66:69]
	s_setprio 0
	s_barrier
	s_add_i32 s36, s66, s41
	v_lshl_add_u64 v[146:147], v[146:147], 0, s[8:9]
	s_mov_b32 m0, s36
	ds_read_b128 v[186:189], v152 offset:49152
	ds_read_b128 v[190:193], v152 offset:50176
	ds_read_b128 v[194:197], v152 offset:51200
	ds_read_b128 v[198:201], v152 offset:52224
	ds_read_b128 v[202:205], v152 offset:53248
	ds_read_b128 v[206:209], v152 offset:54272
	ds_read_b128 v[210:213], v152 offset:55296
	ds_read_b128 v[214:217], v152 offset:56320
	global_load_lds_dwordx4 v[146:147], off
	s_add_i32 m0, s36, 0x2000
	s_add_u32 s34, s34, 0x40080
	v_lshl_add_u64 v[146:147], v[218:219], 0, s[8:9]
	s_addc_u32 s35, s35, 0
	s_add_i32 s36, s67, s41
	global_load_lds_dwordx4 v[146:147], off
	v_lshl_add_u64 v[146:147], s[34:35], 0, v[132:133]
	s_mov_b32 m0, s36
	s_nop 0
	global_load_lds_dwordx4 v[146:147], off
	v_lshl_add_u64 v[146:147], s[34:35], 0, v[136:137]
	s_add_i32 m0, s36, 0x2000
	s_nop 0
	global_load_lds_dwordx4 v[146:147], off
	v_lshl_add_u64 v[146:147], v[220:221], 0, s[8:9]
	s_mov_b32 m0, s46
	s_nop 0
	global_load_lds_dwordx4 v[146:147], off
	v_lshl_add_u64 v[146:147], v[222:223], 0, s[8:9]
	s_mov_b32 m0, s47
	s_nop 0
	global_load_lds_dwordx4 v[146:147], off
	s_waitcnt vmcnt(8)
	s_waitcnt lgkmcnt(0)
	s_barrier
	s_setprio 1
	s_waitcnt lgkmcnt(0)
	v_mfma_f32_16x16x32_bf16 v[62:65], v[154:157], v[186:189], v[62:65]
	v_mfma_f32_16x16x32_bf16 v[58:61], v[162:165], v[186:189], v[58:61]
	v_mfma_f32_16x16x32_bf16 v[46:49], v[154:157], v[194:197], v[46:49]
	v_mfma_f32_16x16x32_bf16 v[42:45], v[162:165], v[194:197], v[42:45]
	v_mfma_f32_16x16x32_bf16 v[30:33], v[154:157], v[202:205], v[30:33]
	v_mfma_f32_16x16x32_bf16 v[26:29], v[162:165], v[202:205], v[26:29]
	v_mfma_f32_16x16x32_bf16 v[14:17], v[154:157], v[210:213], v[14:17]
	v_mfma_f32_16x16x32_bf16 v[10:13], v[162:165], v[210:213], v[10:13]
	v_mfma_f32_16x16x32_bf16 v[62:65], v[158:161], v[190:193], v[62:65]
	v_mfma_f32_16x16x32_bf16 v[58:61], v[166:169], v[190:193], v[58:61]
	v_mfma_f32_16x16x32_bf16 v[46:49], v[158:161], v[198:201], v[46:49]
	v_mfma_f32_16x16x32_bf16 v[42:45], v[166:169], v[198:201], v[42:45]
	v_mfma_f32_16x16x32_bf16 v[30:33], v[158:161], v[206:209], v[30:33]
	v_mfma_f32_16x16x32_bf16 v[26:29], v[166:169], v[206:209], v[26:29]
	v_mfma_f32_16x16x32_bf16 v[14:17], v[158:161], v[214:217], v[14:17]
	v_mfma_f32_16x16x32_bf16 v[10:13], v[166:169], v[214:217], v[10:13]
	s_setprio 0
	s_setprio 1
	v_mfma_f32_16x16x32_bf16 v[54:57], v[170:173], v[186:189], v[54:57]
	v_mfma_f32_16x16x32_bf16 v[50:53], v[178:181], v[186:189], v[50:53]
	v_mfma_f32_16x16x32_bf16 v[38:41], v[170:173], v[194:197], v[38:41]
	v_mfma_f32_16x16x32_bf16 v[34:37], v[178:181], v[194:197], v[34:37]
	v_mfma_f32_16x16x32_bf16 v[22:25], v[170:173], v[202:205], v[22:25]
	v_mfma_f32_16x16x32_bf16 v[18:21], v[178:181], v[202:205], v[18:21]
	v_mfma_f32_16x16x32_bf16 v[6:9], v[170:173], v[210:213], v[6:9]
	v_mfma_f32_16x16x32_bf16 v[2:5], v[178:181], v[210:213], v[2:5]
	v_mfma_f32_16x16x32_bf16 v[54:57], v[174:177], v[190:193], v[54:57]
	v_mfma_f32_16x16x32_bf16 v[50:53], v[182:185], v[190:193], v[50:53]
	v_mfma_f32_16x16x32_bf16 v[38:41], v[174:177], v[198:201], v[38:41]
	v_mfma_f32_16x16x32_bf16 v[34:37], v[182:185], v[198:201], v[34:37]
	v_mfma_f32_16x16x32_bf16 v[22:25], v[174:177], v[206:209], v[22:25]
	v_mfma_f32_16x16x32_bf16 v[18:21], v[182:185], v[206:209], v[18:21]
	v_mfma_f32_16x16x32_bf16 v[6:9], v[174:177], v[214:217], v[6:9]
	v_mfma_f32_16x16x32_bf16 v[2:5], v[182:185], v[214:217], v[2:5]
	s_setprio 0
	s_barrier
	s_add_i32 s65, s65, 2
	s_add_u32 s30, s30, 0x100
	s_addc_u32 s31, s31, 0
	s_add_u32 s63, s63, 0x100
	s_addc_u32 s64, s64, 0
	s_mov_b32 s100, 0
	s_cmp_gt_u32 s65, 13
	s_cbranch_scc0 .LBB0_1166
	s_and_b64 vcc, exec, s[10:11]
	s_cbranch_vccz .LBB0_1169
	s_barrier
.LBB0_1169:
	v_max_f32_e32 v122, v122, v122
	v_lshl_add_u32 v154, s28, 8, v1
	v_max_f32_e32 v122, 0, v122
	v_max_f32_e32 v123, v123, v123
	v_max_f32_e32 v124, v124, v124
	v_lshl_or_b32 v146, s60, 8, v149
	v_ashrrev_i32_e32 v155, 31, v154
	v_mul_f32_e32 v153, v122, v122
	v_max_f32_e32 v122, v127, v127
	v_max_f32_e32 v123, 0, v123
	v_max_f32_e32 v124, 0, v124
	v_ashrrev_i32_e32 v147, 31, v146
	v_lshlrev_b64 v[156:157], 13, v[154:155]
	v_max_f32_e32 v126, v126, v126
	v_max_f32_e32 v122, 0, v122
	v_mul_f32_e32 v127, v123, v123
	v_max_f32_e32 v123, v128, v128
	v_mul_f32_e32 v128, v124, v124
	v_max_f32_e32 v124, v129, v129
	v_max_f32_e32 v125, v125, v125
	v_lshl_add_u64 v[156:157], s[6:7], 0, v[156:157]
	v_lshlrev_b64 v[158:159], 1, v[146:147]
	v_max_f32_e32 v126, 0, v126
	v_mul_f32_e32 v122, v122, v122
	v_max_f32_e32 v123, 0, v123
	v_max_f32_e32 v124, 0, v124
	v_max_f32_e32 v125, 0, v125
	v_max_f32_e32 v114, v114, v114
	v_lshl_add_u64 v[146:147], v[156:157], 0, v[158:159]
	v_mul_f32_e32 v126, v126, v126
	v_mul_f32_e32 v123, v123, v123
	v_mul_f32_e32 v124, v124, v124
	v_mul_f32_e32 v125, v125, v125
	v_cvt_pk_bf16_f32 v122, v126, v122
	v_max_f32_e32 v114, 0, v114
	v_max_f32_e32 v115, v115, v115
	v_max_f32_e32 v116, v116, v116
	v_cvt_pk_bf16_f32 v123, v123, v124
	v_cvt_pk_bf16_f32 v124, v153, v127
	v_cvt_pk_bf16_f32 v125, v128, v125
	global_store_dwordx4 v[146:147], v[122:125], off
	v_max_f32_e32 v115, 0, v115
	v_max_f32_e32 v116, 0, v116
	v_mul_f32_e32 v122, v114, v114
	v_max_f32_e32 v114, v119, v119
	v_max_f32_e32 v118, v118, v118
	v_max_f32_e32 v114, 0, v114
	v_mul_f32_e32 v119, v115, v115
	v_max_f32_e32 v115, v120, v120
	v_mul_f32_e32 v120, v116, v116
	v_max_f32_e32 v116, v121, v121
	v_max_f32_e32 v117, v117, v117
	v_max_f32_e32 v118, 0, v118
	v_mul_f32_e32 v114, v114, v114
	v_max_f32_e32 v115, 0, v115
	v_max_f32_e32 v116, 0, v116
	v_max_f32_e32 v117, 0, v117
	v_mul_f32_e32 v118, v118, v118
	v_mul_f32_e32 v115, v115, v115
	v_mul_f32_e32 v116, v116, v116
	v_mul_f32_e32 v117, v117, v117
	v_cvt_pk_bf16_f32 v114, v118, v114
	v_max_f32_e32 v106, v106, v106
	v_cvt_pk_bf16_f32 v115, v115, v116
	v_cvt_pk_bf16_f32 v116, v122, v119
	v_cvt_pk_bf16_f32 v117, v120, v117
	global_store_dwordx4 v[146:147], v[114:117], off offset:256
	v_max_f32_e32 v106, 0, v106
	v_max_f32_e32 v107, v107, v107
	v_or_b32_e32 v114, 16, v154
	v_max_f32_e32 v108, v108, v108
	v_ashrrev_i32_e32 v115, 31, v114
	v_mul_f32_e32 v116, v106, v106
	v_max_f32_e32 v106, v111, v111
	v_max_f32_e32 v107, 0, v107
	v_max_f32_e32 v108, 0, v108
	v_lshlrev_b64 v[114:115], 13, v[114:115]
	v_max_f32_e32 v110, v110, v110
	v_max_f32_e32 v106, 0, v106
	v_mul_f32_e32 v111, v107, v107
	v_max_f32_e32 v107, v112, v112
	v_mul_f32_e32 v112, v108, v108
	v_max_f32_e32 v108, v113, v113
	v_max_f32_e32 v109, v109, v109
	v_lshl_add_u64 v[114:115], s[6:7], 0, v[114:115]
	v_max_f32_e32 v110, 0, v110
	v_mul_f32_e32 v106, v106, v106
	v_max_f32_e32 v107, 0, v107
	v_max_f32_e32 v108, 0, v108
	v_max_f32_e32 v109, 0, v109
	v_max_f32_e32 v98, v98, v98
	v_lshl_add_u64 v[114:115], v[114:115], 0, v[158:159]
	v_mul_f32_e32 v110, v110, v110
	v_mul_f32_e32 v107, v107, v107
	v_mul_f32_e32 v108, v108, v108
	v_mul_f32_e32 v109, v109, v109
	v_cvt_pk_bf16_f32 v106, v110, v106
	v_max_f32_e32 v98, 0, v98
	v_max_f32_e32 v99, v99, v99
	v_max_f32_e32 v100, v100, v100
	v_cvt_pk_bf16_f32 v107, v107, v108
	v_cvt_pk_bf16_f32 v108, v116, v111
	v_cvt_pk_bf16_f32 v109, v112, v109
	global_store_dwordx4 v[114:115], v[106:109], off
	v_max_f32_e32 v99, 0, v99
	v_max_f32_e32 v100, 0, v100
	v_mul_f32_e32 v106, v98, v98
	v_max_f32_e32 v98, v103, v103
	v_max_f32_e32 v102, v102, v102
	v_max_f32_e32 v98, 0, v98
	v_mul_f32_e32 v103, v99, v99
	v_max_f32_e32 v99, v104, v104
	v_mul_f32_e32 v104, v100, v100
	v_max_f32_e32 v100, v105, v105
	v_max_f32_e32 v101, v101, v101
	v_max_f32_e32 v102, 0, v102
	v_mul_f32_e32 v98, v98, v98
	v_max_f32_e32 v99, 0, v99
	v_max_f32_e32 v100, 0, v100
	v_max_f32_e32 v101, 0, v101
	v_mul_f32_e32 v102, v102, v102
	v_mul_f32_e32 v99, v99, v99
	v_mul_f32_e32 v100, v100, v100
	v_mul_f32_e32 v101, v101, v101
	v_cvt_pk_bf16_f32 v98, v102, v98
	v_max_f32_e32 v90, v90, v90
	v_cvt_pk_bf16_f32 v99, v99, v100
	v_cvt_pk_bf16_f32 v100, v106, v103
	v_cvt_pk_bf16_f32 v101, v104, v101
	global_store_dwordx4 v[114:115], v[98:101], off offset:256
	v_max_f32_e32 v90, 0, v90
	v_max_f32_e32 v91, v91, v91
	v_or_b32_e32 v98, 32, v154
	v_max_f32_e32 v92, v92, v92
	v_ashrrev_i32_e32 v99, 31, v98
	v_mul_f32_e32 v100, v90, v90
	v_max_f32_e32 v90, v95, v95
	v_max_f32_e32 v91, 0, v91
	v_max_f32_e32 v92, 0, v92
	v_lshlrev_b64 v[98:99], 13, v[98:99]
	v_max_f32_e32 v94, v94, v94
	v_max_f32_e32 v90, 0, v90
	v_mul_f32_e32 v95, v91, v91
	v_max_f32_e32 v91, v96, v96
	v_mul_f32_e32 v96, v92, v92
	v_max_f32_e32 v92, v97, v97
	v_max_f32_e32 v93, v93, v93
	v_lshl_add_u64 v[98:99], s[6:7], 0, v[98:99]
	v_max_f32_e32 v94, 0, v94
	v_mul_f32_e32 v90, v90, v90
	v_max_f32_e32 v91, 0, v91
	v_max_f32_e32 v92, 0, v92
	v_max_f32_e32 v93, 0, v93
	v_max_f32_e32 v82, v82, v82
	v_lshl_add_u64 v[98:99], v[98:99], 0, v[158:159]
	v_mul_f32_e32 v94, v94, v94
	v_mul_f32_e32 v91, v91, v91
	v_mul_f32_e32 v92, v92, v92
	v_mul_f32_e32 v93, v93, v93
	v_cvt_pk_bf16_f32 v90, v94, v90
	v_max_f32_e32 v82, 0, v82
	v_max_f32_e32 v83, v83, v83
	v_max_f32_e32 v84, v84, v84
	v_cvt_pk_bf16_f32 v91, v91, v92
	v_cvt_pk_bf16_f32 v92, v100, v95
	v_cvt_pk_bf16_f32 v93, v96, v93
	global_store_dwordx4 v[98:99], v[90:93], off
	v_max_f32_e32 v83, 0, v83
	v_max_f32_e32 v84, 0, v84
	v_mul_f32_e32 v90, v82, v82
	v_max_f32_e32 v82, v87, v87
	v_max_f32_e32 v86, v86, v86
	v_max_f32_e32 v82, 0, v82
	v_mul_f32_e32 v87, v83, v83
	v_max_f32_e32 v83, v88, v88
	v_mul_f32_e32 v88, v84, v84
	v_max_f32_e32 v84, v89, v89
	v_max_f32_e32 v85, v85, v85
	v_max_f32_e32 v86, 0, v86
	v_mul_f32_e32 v82, v82, v82
	v_max_f32_e32 v83, 0, v83
	v_max_f32_e32 v84, 0, v84
	v_max_f32_e32 v85, 0, v85
	v_mul_f32_e32 v86, v86, v86
	v_mul_f32_e32 v83, v83, v83
	v_mul_f32_e32 v84, v84, v84
	v_mul_f32_e32 v85, v85, v85
	v_cvt_pk_bf16_f32 v82, v86, v82
	v_max_f32_e32 v74, v74, v74
	v_cvt_pk_bf16_f32 v83, v83, v84
	v_cvt_pk_bf16_f32 v84, v90, v87
	v_cvt_pk_bf16_f32 v85, v88, v85
	global_store_dwordx4 v[98:99], v[82:85], off offset:256
	v_max_f32_e32 v74, 0, v74
	v_max_f32_e32 v75, v75, v75
	v_or_b32_e32 v82, 48, v154
	v_max_f32_e32 v76, v76, v76
	v_ashrrev_i32_e32 v83, 31, v82
	v_mul_f32_e32 v84, v74, v74
	v_max_f32_e32 v74, v79, v79
	v_max_f32_e32 v75, 0, v75
	v_max_f32_e32 v76, 0, v76
	v_lshlrev_b64 v[82:83], 13, v[82:83]
	v_max_f32_e32 v78, v78, v78
	v_max_f32_e32 v74, 0, v74
	v_mul_f32_e32 v79, v75, v75
	v_max_f32_e32 v75, v80, v80
	v_mul_f32_e32 v80, v76, v76
	v_max_f32_e32 v76, v81, v81
	v_max_f32_e32 v77, v77, v77
	v_lshl_add_u64 v[82:83], s[6:7], 0, v[82:83]
	v_max_f32_e32 v78, 0, v78
	v_mul_f32_e32 v74, v74, v74
	v_max_f32_e32 v75, 0, v75
	v_max_f32_e32 v76, 0, v76
	v_max_f32_e32 v77, 0, v77
	v_max_f32_e32 v66, v66, v66
	v_max_f32_e32 v67, v67, v67
	v_max_f32_e32 v68, v68, v68
	v_lshl_add_u64 v[82:83], v[82:83], 0, v[158:159]
	v_mul_f32_e32 v78, v78, v78
	v_mul_f32_e32 v75, v75, v75
	v_mul_f32_e32 v76, v76, v76
	v_mul_f32_e32 v77, v77, v77
	v_cvt_pk_bf16_f32 v74, v78, v74
	v_max_f32_e32 v66, 0, v66
	v_max_f32_e32 v67, 0, v67
	v_max_f32_e32 v68, 0, v68
	v_cvt_pk_bf16_f32 v75, v75, v76
	v_cvt_pk_bf16_f32 v76, v84, v79
	v_cvt_pk_bf16_f32 v77, v80, v77
	global_store_dwordx4 v[82:83], v[74:77], off
	v_max_f32_e32 v70, v70, v70
	v_max_f32_e32 v69, v69, v69
	v_mul_f32_e32 v74, v66, v66
	v_max_f32_e32 v66, v71, v71
	v_mul_f32_e32 v71, v67, v67
	v_max_f32_e32 v67, v72, v72
	v_mul_f32_e32 v72, v68, v68
	v_max_f32_e32 v68, v73, v73
	v_max_f32_e32 v66, 0, v66
	v_max_f32_e32 v67, 0, v67
	v_max_f32_e32 v68, 0, v68
	v_max_f32_e32 v70, 0, v70
	v_mul_f32_e32 v66, v66, v66
	v_mul_f32_e32 v67, v67, v67
	v_max_f32_e32 v69, 0, v69
	v_mul_f32_e32 v68, v68, v68
	v_max_f32_e32 v58, v58, v58
	v_mul_f32_e32 v70, v70, v70
	v_mul_f32_e32 v69, v69, v69
	v_cvt_pk_bf16_f32 v66, v70, v66
	v_cvt_pk_bf16_f32 v67, v67, v68
	v_cvt_pk_bf16_f32 v68, v74, v71
	v_max_f32_e32 v58, 0, v58
	v_max_f32_e32 v59, v59, v59
	v_max_f32_e32 v60, v60, v60
	v_cvt_pk_bf16_f32 v69, v72, v69
	global_store_dwordx4 v[82:83], v[66:69], off offset:256
	v_max_f32_e32 v62, v62, v62
	v_max_f32_e32 v59, 0, v59
	v_mul_f32_e32 v68, v58, v58
	v_max_f32_e32 v58, v63, v63
	v_max_f32_e32 v60, 0, v60
	v_max_f32_e32 v62, 0, v62
	v_max_f32_e32 v58, 0, v58
	v_mul_f32_e32 v63, v59, v59
	v_max_f32_e32 v59, v64, v64
	v_mul_f32_e32 v64, v60, v60
	v_max_f32_e32 v60, v65, v65
	v_mul_f32_e32 v62, v62, v62
	v_mul_f32_e32 v58, v58, v58
	v_max_f32_e32 v59, 0, v59
	v_max_f32_e32 v60, 0, v60
	v_max_f32_e32 v61, v61, v61
	v_mul_f32_e32 v59, v59, v59
	v_max_f32_e32 v61, 0, v61
	v_mul_f32_e32 v60, v60, v60
	v_cvt_pk_bf16_f32 v58, v62, v58
	v_add_co_u32_e32 v62, vcc, s56, v146
	v_max_f32_e32 v50, v50, v50
	v_max_f32_e32 v51, v51, v51
	v_max_f32_e32 v52, v52, v52
	v_mul_f32_e32 v61, v61, v61
	v_cvt_pk_bf16_f32 v59, v59, v60
	v_cvt_pk_bf16_f32 v60, v68, v63
	v_addc_co_u32_e32 v63, vcc, 0, v147, vcc
	v_max_f32_e32 v50, 0, v50
	v_max_f32_e32 v51, 0, v51
	v_max_f32_e32 v52, 0, v52
	v_cvt_pk_bf16_f32 v61, v64, v61
	global_store_dwordx4 v[62:63], v[58:61], off
	v_max_f32_e32 v54, v54, v54
	v_max_f32_e32 v53, v53, v53
	v_mul_f32_e32 v58, v50, v50
	v_max_f32_e32 v50, v55, v55
	v_mul_f32_e32 v55, v51, v51
	v_max_f32_e32 v51, v56, v56
	v_mul_f32_e32 v56, v52, v52
	v_max_f32_e32 v52, v57, v57
	v_max_f32_e32 v50, 0, v50
	v_max_f32_e32 v51, 0, v51
	v_max_f32_e32 v52, 0, v52
	v_max_f32_e32 v54, 0, v54
	v_mul_f32_e32 v50, v50, v50
	v_mul_f32_e32 v51, v51, v51
	v_max_f32_e32 v53, 0, v53
	v_mul_f32_e32 v52, v52, v52
	v_max_f32_e32 v42, v42, v42
	v_lshl_add_u64 v[66:67], v[146:147], 0, s[12:13]
	v_mul_f32_e32 v54, v54, v54
	v_mul_f32_e32 v53, v53, v53
	v_cvt_pk_bf16_f32 v50, v54, v50
	v_cvt_pk_bf16_f32 v51, v51, v52
	v_cvt_pk_bf16_f32 v52, v58, v55
	v_max_f32_e32 v42, 0, v42
	v_max_f32_e32 v43, v43, v43
	v_max_f32_e32 v44, v44, v44
	v_cvt_pk_bf16_f32 v53, v56, v53
	global_store_dwordx4 v[66:67], v[50:53], off offset:256
	v_max_f32_e32 v46, v46, v46
	v_max_f32_e32 v43, 0, v43
	v_mul_f32_e32 v52, v42, v42
	v_max_f32_e32 v42, v47, v47
	v_max_f32_e32 v44, 0, v44
	v_max_f32_e32 v46, 0, v46
	v_max_f32_e32 v42, 0, v42
	v_mul_f32_e32 v47, v43, v43
	v_max_f32_e32 v43, v48, v48
	v_mul_f32_e32 v48, v44, v44
	v_max_f32_e32 v44, v49, v49
	v_mul_f32_e32 v46, v46, v46
	v_mul_f32_e32 v42, v42, v42
	v_max_f32_e32 v43, 0, v43
	v_max_f32_e32 v44, 0, v44
	v_max_f32_e32 v45, v45, v45
	v_mul_f32_e32 v43, v43, v43
	v_max_f32_e32 v45, 0, v45
	v_mul_f32_e32 v44, v44, v44
	v_cvt_pk_bf16_f32 v42, v46, v42
	v_add_co_u32_e32 v46, vcc, s57, v146
	v_max_f32_e32 v34, v34, v34
	v_max_f32_e32 v35, v35, v35
	v_max_f32_e32 v36, v36, v36
	v_mul_f32_e32 v45, v45, v45
	v_cvt_pk_bf16_f32 v43, v43, v44
	v_cvt_pk_bf16_f32 v44, v52, v47
	v_addc_co_u32_e32 v47, vcc, 0, v147, vcc
	v_max_f32_e32 v34, 0, v34
	v_max_f32_e32 v35, 0, v35
	v_max_f32_e32 v36, 0, v36
	v_cvt_pk_bf16_f32 v45, v48, v45
	global_store_dwordx4 v[46:47], v[42:45], off
	v_max_f32_e32 v38, v38, v38
	v_max_f32_e32 v37, v37, v37
	v_mul_f32_e32 v42, v34, v34
	v_max_f32_e32 v34, v39, v39
	v_mul_f32_e32 v39, v35, v35
	v_max_f32_e32 v35, v40, v40
	v_mul_f32_e32 v40, v36, v36
	v_max_f32_e32 v36, v41, v41
	v_max_f32_e32 v34, 0, v34
	v_max_f32_e32 v35, 0, v35
	v_max_f32_e32 v36, 0, v36
	v_max_f32_e32 v38, 0, v38
	v_mul_f32_e32 v34, v34, v34
	v_mul_f32_e32 v35, v35, v35
	v_max_f32_e32 v37, 0, v37
	v_mul_f32_e32 v36, v36, v36
	v_max_f32_e32 v26, v26, v26
	v_lshl_add_u64 v[50:51], v[146:147], 0, s[14:15]
	v_mul_f32_e32 v38, v38, v38
	v_mul_f32_e32 v37, v37, v37
	v_cvt_pk_bf16_f32 v34, v38, v34
	v_cvt_pk_bf16_f32 v35, v35, v36
	v_cvt_pk_bf16_f32 v36, v42, v39
	v_max_f32_e32 v26, 0, v26
	v_max_f32_e32 v27, v27, v27
	v_max_f32_e32 v28, v28, v28
	v_cvt_pk_bf16_f32 v37, v40, v37
	global_store_dwordx4 v[50:51], v[34:37], off offset:256
	v_max_f32_e32 v30, v30, v30
	v_max_f32_e32 v27, 0, v27
	v_mul_f32_e32 v36, v26, v26
	v_max_f32_e32 v26, v31, v31
	v_max_f32_e32 v28, 0, v28
	v_max_f32_e32 v30, 0, v30
	v_max_f32_e32 v26, 0, v26
	v_mul_f32_e32 v31, v27, v27
	v_max_f32_e32 v27, v32, v32
	v_mul_f32_e32 v32, v28, v28
	v_max_f32_e32 v28, v33, v33
	v_mul_f32_e32 v30, v30, v30
	v_mul_f32_e32 v26, v26, v26
	v_max_f32_e32 v27, 0, v27
	v_max_f32_e32 v28, 0, v28
	v_max_f32_e32 v29, v29, v29
	v_mul_f32_e32 v27, v27, v27
	v_max_f32_e32 v29, 0, v29
	v_mul_f32_e32 v28, v28, v28
	v_cvt_pk_bf16_f32 v26, v30, v26
	v_add_co_u32_e32 v30, vcc, s58, v146
	v_max_f32_e32 v18, v18, v18
	v_max_f32_e32 v19, v19, v19
	v_max_f32_e32 v20, v20, v20
	v_mul_f32_e32 v29, v29, v29
	v_cvt_pk_bf16_f32 v27, v27, v28
	v_cvt_pk_bf16_f32 v28, v36, v31
	v_addc_co_u32_e32 v31, vcc, 0, v147, vcc
	v_max_f32_e32 v18, 0, v18
	v_max_f32_e32 v19, 0, v19
	v_max_f32_e32 v20, 0, v20
	v_cvt_pk_bf16_f32 v29, v32, v29
	global_store_dwordx4 v[30:31], v[26:29], off
	v_max_f32_e32 v22, v22, v22
	v_max_f32_e32 v21, v21, v21
	v_mul_f32_e32 v26, v18, v18
	v_max_f32_e32 v18, v23, v23
	v_mul_f32_e32 v23, v19, v19
	v_max_f32_e32 v19, v24, v24
	v_mul_f32_e32 v24, v20, v20
	v_max_f32_e32 v20, v25, v25
	v_max_f32_e32 v18, 0, v18
	v_max_f32_e32 v19, 0, v19
	v_max_f32_e32 v20, 0, v20
	v_max_f32_e32 v22, 0, v22
	v_mul_f32_e32 v18, v18, v18
	v_mul_f32_e32 v19, v19, v19
	v_max_f32_e32 v21, 0, v21
	v_mul_f32_e32 v20, v20, v20
	v_max_f32_e32 v10, v10, v10
	v_lshl_add_u64 v[34:35], v[146:147], 0, s[16:17]
	v_mul_f32_e32 v22, v22, v22
	v_mul_f32_e32 v21, v21, v21
	v_cvt_pk_bf16_f32 v18, v22, v18
	v_cvt_pk_bf16_f32 v19, v19, v20
	v_cvt_pk_bf16_f32 v20, v26, v23
	v_max_f32_e32 v10, 0, v10
	v_max_f32_e32 v11, v11, v11
	v_max_f32_e32 v12, v12, v12
	v_cvt_pk_bf16_f32 v21, v24, v21
	global_store_dwordx4 v[34:35], v[18:21], off offset:256
	v_max_f32_e32 v14, v14, v14
	v_max_f32_e32 v11, 0, v11
	v_mul_f32_e32 v20, v10, v10
	v_max_f32_e32 v10, v15, v15
	v_max_f32_e32 v12, 0, v12
	v_max_f32_e32 v14, 0, v14
	v_max_f32_e32 v10, 0, v10
	v_mul_f32_e32 v15, v11, v11
	v_max_f32_e32 v11, v16, v16
	v_mul_f32_e32 v16, v12, v12
	v_max_f32_e32 v12, v17, v17
	v_mul_f32_e32 v14, v14, v14
	v_mul_f32_e32 v10, v10, v10
	v_max_f32_e32 v11, 0, v11
	v_max_f32_e32 v12, 0, v12
	v_max_f32_e32 v13, v13, v13
	v_mul_f32_e32 v11, v11, v11
	v_max_f32_e32 v13, 0, v13
	v_mul_f32_e32 v12, v12, v12
	v_cvt_pk_bf16_f32 v10, v14, v10
	v_add_co_u32_e32 v14, vcc, s59, v146
	v_max_f32_e32 v2, v2, v2
	v_max_f32_e32 v3, v3, v3
	v_max_f32_e32 v4, v4, v4
	v_mul_f32_e32 v13, v13, v13
	v_cvt_pk_bf16_f32 v11, v11, v12
	v_cvt_pk_bf16_f32 v12, v20, v15
	v_addc_co_u32_e32 v15, vcc, 0, v147, vcc
	v_max_f32_e32 v2, 0, v2
	v_max_f32_e32 v3, 0, v3
	v_max_f32_e32 v4, 0, v4
	v_cvt_pk_bf16_f32 v13, v16, v13
	global_store_dwordx4 v[14:15], v[10:13], off
	v_max_f32_e32 v5, v5, v5
	v_max_f32_e32 v6, v6, v6
	v_mul_f32_e32 v10, v2, v2
	v_max_f32_e32 v2, v7, v7
	v_mul_f32_e32 v7, v3, v3
	v_max_f32_e32 v3, v8, v8
	v_mul_f32_e32 v8, v4, v4
	v_max_f32_e32 v4, v9, v9
	v_max_f32_e32 v2, 0, v2
	v_max_f32_e32 v3, 0, v3
	v_max_f32_e32 v4, 0, v4
	v_max_f32_e32 v5, 0, v5
	v_lshl_add_u64 v[18:19], v[146:147], 0, s[18:19]
	v_max_f32_e32 v6, 0, v6
	v_mul_f32_e32 v2, v2, v2
	v_mul_f32_e32 v3, v3, v3
	v_mul_f32_e32 v4, v4, v4
	v_mul_f32_e32 v5, v5, v5
	s_andn2_b64 vcc, exec, s[0:1]
	s_mov_b64 s[0:1], -1
	v_mul_f32_e32 v6, v6, v6
	v_cvt_pk_bf16_f32 v2, v6, v2
	v_cvt_pk_bf16_f32 v3, v3, v4
	v_cvt_pk_bf16_f32 v4, v10, v7
	v_cvt_pk_bf16_f32 v5, v8, v5
	global_store_dwordx4 v[18:19], v[2:5], off offset:256
	s_mov_b32 s100, 1
	s_cbranch_vccnz .LBB0_1158
	s_andn2_b64 vcc, exec, s[4:5]
	s_cbranch_vccnz .LBB0_1157
	s_barrier
	s_branch .LBB0_1157

.LBB0_1223:
	s_mov_b32 s100, 0
	s_cmp_lt_i32 s72, 19
	s_cselect_b64 s[0:1], -1, 0
	s_cmp_gt_i32 s73, 18
	s_cselect_b64 s[4:5], -1, 0
	s_and_b64 s[0:1], s[0:1], s[4:5]
	s_andn2_b64 vcc, exec, s[0:1]
	s_cbranch_vccnz .LBB0_1298
	s_cmpk_gt_i32 s2, 0x1ff
	v_readfirstlane_b32 s10, v0
	s_cbranch_scc1 .LBB0_1248
	s_ashr_i32 s3, s2, 31
	s_lshr_b32 s0, s3, 29
	s_add_i32 s6, s2, s0
	s_and_b32 s0, s6, -8
	s_sub_i32 s5, s2, s0
	s_cmp_gt_i32 s5, -1
	s_cbranch_scc0 .LBB0_1227
	s_lshl_b32 s4, s5, 6
	s_ashr_i32 s0, s6, 3
	s_cbranch_execz .LBB0_1228
	s_branch .LBB0_1229

.LBB0_1241:
	ds_read_b128 v[154:157], v150
	ds_read_b128 v[158:161], v150 offset:1024
	ds_read_b128 v[162:165], v150 offset:2048
	ds_read_b128 v[166:169], v150 offset:3072
	ds_read_b128 v[170:173], v151
	ds_read_b128 v[174:177], v151 offset:1024
	ds_read_b128 v[178:181], v151 offset:2048
	ds_read_b128 v[182:185], v151 offset:3072
	s_add_u32 s34, s30, 0xfff00080
	s_addc_u32 s35, s31, -1
	s_cmp_eq_u32 s65, 60
	s_cselect_b32 s37, s23, s35
	s_cselect_b32 s36, s61, s34
	s_cselect_b32 s35, s21, s64
	s_cselect_b32 s34, s62, s63
	v_lshl_add_u64 v[146:147], s[30:31], 0, v[138:139]
	s_add_i32 m0, s29, 0xc000
	ds_read_b128 v[186:189], v152
	ds_read_b128 v[190:193], v152 offset:1024
	ds_read_b128 v[194:197], v152 offset:2048
	ds_read_b128 v[198:201], v152 offset:3072
	ds_read_b128 v[202:205], v152 offset:4096
	ds_read_b128 v[206:209], v152 offset:5120
	ds_read_b128 v[210:213], v152 offset:6144
	ds_read_b128 v[214:217], v152 offset:7168
	global_load_lds_dwordx4 v[146:147], off
	v_lshl_add_u64 v[146:147], s[30:31], 0, v[140:141]
	s_add_i32 m0, s29, 0xe000
	s_nop 0
	global_load_lds_dwordx4 v[146:147], off
	s_cmp_lg_u32 s100, 0
	s_cbranch_scc1 .Lrw6_0a
	s_waitcnt vmcnt(8)
	s_branch .Lrw6_0b

.Lrw6_0b:
	s_waitcnt lgkmcnt(0)
	s_barrier
	s_setprio 1
	s_waitcnt lgkmcnt(0)
	v_mfma_f32_16x16x32_bf16 v[126:129], v[154:157], v[186:189], v[126:129]
	v_mfma_f32_16x16x32_bf16 v[122:125], v[162:165], v[186:189], v[122:125]
	v_mfma_f32_16x16x32_bf16 v[118:121], v[154:157], v[194:197], v[118:121]
	v_mfma_f32_16x16x32_bf16 v[110:113], v[162:165], v[194:197], v[110:113]
	v_mfma_f32_16x16x32_bf16 v[102:105], v[154:157], v[202:205], v[102:105]
	v_mfma_f32_16x16x32_bf16 v[94:97], v[162:165], v[202:205], v[94:97]
	v_mfma_f32_16x16x32_bf16 v[86:89], v[154:157], v[210:213], v[86:89]
	v_mfma_f32_16x16x32_bf16 v[78:81], v[162:165], v[210:213], v[78:81]
	v_mfma_f32_16x16x32_bf16 v[126:129], v[158:161], v[190:193], v[126:129]
	v_mfma_f32_16x16x32_bf16 v[122:125], v[166:169], v[190:193], v[122:125]
	v_mfma_f32_16x16x32_bf16 v[118:121], v[158:161], v[198:201], v[118:121]
	v_mfma_f32_16x16x32_bf16 v[110:113], v[166:169], v[198:201], v[110:113]
	v_mfma_f32_16x16x32_bf16 v[102:105], v[158:161], v[206:209], v[102:105]
	v_mfma_f32_16x16x32_bf16 v[94:97], v[166:169], v[206:209], v[94:97]
	v_mfma_f32_16x16x32_bf16 v[86:89], v[158:161], v[214:217], v[86:89]
	v_mfma_f32_16x16x32_bf16 v[78:81], v[166:169], v[214:217], v[78:81]
	s_setprio 0
	s_setprio 1
	v_mfma_f32_16x16x32_bf16 v[114:117], v[170:173], v[186:189], v[114:117]
	v_mfma_f32_16x16x32_bf16 v[106:109], v[178:181], v[186:189], v[106:109]
	v_mfma_f32_16x16x32_bf16 v[98:101], v[170:173], v[194:197], v[98:101]
	v_mfma_f32_16x16x32_bf16 v[90:93], v[178:181], v[194:197], v[90:93]
	v_mfma_f32_16x16x32_bf16 v[82:85], v[170:173], v[202:205], v[82:85]
	v_mfma_f32_16x16x32_bf16 v[74:77], v[178:181], v[202:205], v[74:77]
	v_mfma_f32_16x16x32_bf16 v[70:73], v[170:173], v[210:213], v[70:73]
	v_mfma_f32_16x16x32_bf16 v[66:69], v[178:181], v[210:213], v[66:69]
	v_mfma_f32_16x16x32_bf16 v[114:117], v[174:177], v[190:193], v[114:117]
	v_mfma_f32_16x16x32_bf16 v[106:109], v[182:185], v[190:193], v[106:109]
	v_mfma_f32_16x16x32_bf16 v[98:101], v[174:177], v[198:201], v[98:101]
	v_mfma_f32_16x16x32_bf16 v[90:93], v[182:185], v[198:201], v[90:93]
	v_mfma_f32_16x16x32_bf16 v[82:85], v[174:177], v[206:209], v[82:85]
	v_mfma_f32_16x16x32_bf16 v[74:77], v[182:185], v[206:209], v[74:77]
	v_mfma_f32_16x16x32_bf16 v[70:73], v[174:177], v[214:217], v[70:73]
	v_mfma_f32_16x16x32_bf16 v[66:69], v[182:185], v[214:217], v[66:69]
	s_setprio 0
	s_barrier
	s_add_i32 s66, s54, s41
	v_lshl_add_u64 v[146:147], s[34:35], 0, v[132:133]
	s_mov_b32 m0, s66
	ds_read_b128 v[186:189], v152 offset:16384
	ds_read_b128 v[190:193], v152 offset:17408
	ds_read_b128 v[194:197], v152 offset:18432
	ds_read_b128 v[198:201], v152 offset:19456
	ds_read_b128 v[202:205], v152 offset:20480
	ds_read_b128 v[206:209], v152 offset:21504
	ds_read_b128 v[210:213], v152 offset:22528
	ds_read_b128 v[214:217], v152 offset:23552
	global_load_lds_dwordx4 v[146:147], off
	s_add_i32 m0, s66, 0x2000
	s_add_u32 s66, s34, 0x100000
	v_lshl_add_u64 v[218:219], s[34:35], 0, v[136:137]
	s_addc_u32 s67, s35, 0
	s_add_i32 s68, s55, s41
	global_load_lds_dwordx4 v[218:219], off
	v_lshl_add_u64 v[220:221], s[66:67], 0, v[132:133]
	s_mov_b32 m0, s68
	v_lshl_add_u64 v[222:223], s[36:37], 0, v[134:135]
	global_load_lds_dwordx4 v[220:221], off
	v_lshl_add_u64 v[220:221], s[66:67], 0, v[136:137]
	s_add_i32 m0, s68, 0x2000
	s_nop 0
	global_load_lds_dwordx4 v[220:221], off
	v_lshl_add_u64 v[220:221], s[36:37], 0, v[130:131]
	s_mov_b32 m0, s29
	s_nop 0
	global_load_lds_dwordx4 v[220:221], off
	s_mov_b32 m0, s42
	s_nop 0
	global_load_lds_dwordx4 v[222:223], off
	s_cmp_lg_u32 s100, 0
	s_cbranch_scc1 .Lrw6_1a
	s_waitcnt vmcnt(8)
	s_branch .Lrw6_1b

.Lrw6_1b:
	s_waitcnt lgkmcnt(0)
	s_barrier
	s_setprio 1
	s_waitcnt lgkmcnt(0)
	v_mfma_f32_16x16x32_bf16 v[62:65], v[154:157], v[186:189], v[62:65]
	v_mfma_f32_16x16x32_bf16 v[58:61], v[162:165], v[186:189], v[58:61]
	v_mfma_f32_16x16x32_bf16 v[54:57], v[154:157], v[194:197], v[54:57]
	v_mfma_f32_16x16x32_bf16 v[46:49], v[162:165], v[194:197], v[46:49]
	v_mfma_f32_16x16x32_bf16 v[38:41], v[154:157], v[202:205], v[38:41]
	v_mfma_f32_16x16x32_bf16 v[30:33], v[162:165], v[202:205], v[30:33]
	v_mfma_f32_16x16x32_bf16 v[22:25], v[154:157], v[210:213], v[22:25]
	v_mfma_f32_16x16x32_bf16 v[14:17], v[162:165], v[210:213], v[14:17]
	v_mfma_f32_16x16x32_bf16 v[62:65], v[158:161], v[190:193], v[62:65]
	v_mfma_f32_16x16x32_bf16 v[58:61], v[166:169], v[190:193], v[58:61]
	v_mfma_f32_16x16x32_bf16 v[54:57], v[158:161], v[198:201], v[54:57]
	v_mfma_f32_16x16x32_bf16 v[46:49], v[166:169], v[198:201], v[46:49]
	v_mfma_f32_16x16x32_bf16 v[38:41], v[158:161], v[206:209], v[38:41]
	v_mfma_f32_16x16x32_bf16 v[30:33], v[166:169], v[206:209], v[30:33]
	v_mfma_f32_16x16x32_bf16 v[22:25], v[158:161], v[214:217], v[22:25]
	v_mfma_f32_16x16x32_bf16 v[14:17], v[166:169], v[214:217], v[14:17]
	s_setprio 0
	s_setprio 1
	v_mfma_f32_16x16x32_bf16 v[50:53], v[170:173], v[186:189], v[50:53]
	v_mfma_f32_16x16x32_bf16 v[42:45], v[178:181], v[186:189], v[42:45]
	v_mfma_f32_16x16x32_bf16 v[34:37], v[170:173], v[194:197], v[34:37]
	v_mfma_f32_16x16x32_bf16 v[26:29], v[178:181], v[194:197], v[26:29]
	v_mfma_f32_16x16x32_bf16 v[18:21], v[170:173], v[202:205], v[18:21]
	v_mfma_f32_16x16x32_bf16 v[10:13], v[178:181], v[202:205], v[10:13]
	v_mfma_f32_16x16x32_bf16 v[6:9], v[170:173], v[210:213], v[6:9]
	v_mfma_f32_16x16x32_bf16 v[2:5], v[178:181], v[210:213], v[2:5]
	v_mfma_f32_16x16x32_bf16 v[50:53], v[174:177], v[190:193], v[50:53]
	v_mfma_f32_16x16x32_bf16 v[42:45], v[182:185], v[190:193], v[42:45]
	v_mfma_f32_16x16x32_bf16 v[34:37], v[174:177], v[198:201], v[34:37]
	v_mfma_f32_16x16x32_bf16 v[26:29], v[182:185], v[198:201], v[26:29]
	v_mfma_f32_16x16x32_bf16 v[18:21], v[174:177], v[206:209], v[18:21]
	v_mfma_f32_16x16x32_bf16 v[10:13], v[182:185], v[206:209], v[10:13]
	v_mfma_f32_16x16x32_bf16 v[6:9], v[174:177], v[214:217], v[6:9]
	v_mfma_f32_16x16x32_bf16 v[2:5], v[182:185], v[214:217], v[2:5]
	s_setprio 0
	s_barrier
	s_add_i32 s66, 0, 0x18000
	v_add_u32_e32 v153, s66, v148
	s_add_i32 s67, 0, 0x1c000
	ds_read_b128 v[154:157], v153
	ds_read_b128 v[158:161], v153 offset:1024
	ds_read_b128 v[162:165], v153 offset:2048
	ds_read_b128 v[166:169], v153 offset:3072
	v_add_u32_e32 v153, s67, v148
	ds_read_b128 v[170:173], v153
	ds_read_b128 v[174:177], v153 offset:1024
	ds_read_b128 v[178:181], v153 offset:2048
	ds_read_b128 v[182:185], v153 offset:3072
	s_add_u32 s36, s36, 0x100000
	s_addc_u32 s37, s37, 0
	s_mov_b32 m0, s43
	v_lshl_add_u64 v[224:225], s[36:37], 0, v[130:131]
	ds_read_b128 v[186:189], v152 offset:32768
	ds_read_b128 v[190:193], v152 offset:33792
	ds_read_b128 v[194:197], v152 offset:34816
	ds_read_b128 v[198:201], v152 offset:35840
	ds_read_b128 v[202:205], v152 offset:36864
	ds_read_b128 v[206:209], v152 offset:37888
	ds_read_b128 v[210:213], v152 offset:38912
	ds_read_b128 v[214:217], v152 offset:39936
	global_load_lds_dwordx4 v[224:225], off
	v_lshl_add_u64 v[224:225], s[36:37], 0, v[134:135]
	s_mov_b32 m0, s44
	s_nop 0
	global_load_lds_dwordx4 v[224:225], off
	s_waitcnt vmcnt(8)
	s_waitcnt lgkmcnt(0)
	s_barrier
	s_setprio 1
	s_waitcnt lgkmcnt(0)
	v_mfma_f32_16x16x32_bf16 v[126:129], v[154:157], v[186:189], v[126:129]
	v_mfma_f32_16x16x32_bf16 v[122:125], v[162:165], v[186:189], v[122:125]
	v_mfma_f32_16x16x32_bf16 v[118:121], v[154:157], v[194:197], v[118:121]
	v_mfma_f32_16x16x32_bf16 v[110:113], v[162:165], v[194:197], v[110:113]
	v_mfma_f32_16x16x32_bf16 v[102:105], v[154:157], v[202:205], v[102:105]
	v_mfma_f32_16x16x32_bf16 v[94:97], v[162:165], v[202:205], v[94:97]
	v_mfma_f32_16x16x32_bf16 v[86:89], v[154:157], v[210:213], v[86:89]
	v_mfma_f32_16x16x32_bf16 v[78:81], v[162:165], v[210:213], v[78:81]
	v_mfma_f32_16x16x32_bf16 v[126:129], v[158:161], v[190:193], v[126:129]
	v_mfma_f32_16x16x32_bf16 v[122:125], v[166:169], v[190:193], v[122:125]
	v_mfma_f32_16x16x32_bf16 v[118:121], v[158:161], v[198:201], v[118:121]
	v_mfma_f32_16x16x32_bf16 v[110:113], v[166:169], v[198:201], v[110:113]
	v_mfma_f32_16x16x32_bf16 v[102:105], v[158:161], v[206:209], v[102:105]
	v_mfma_f32_16x16x32_bf16 v[94:97], v[166:169], v[206:209], v[94:97]
	v_mfma_f32_16x16x32_bf16 v[86:89], v[158:161], v[214:217], v[86:89]
	v_mfma_f32_16x16x32_bf16 v[78:81], v[166:169], v[214:217], v[78:81]
	s_setprio 0
	s_setprio 1
	v_mfma_f32_16x16x32_bf16 v[114:117], v[170:173], v[186:189], v[114:117]
	v_mfma_f32_16x16x32_bf16 v[106:109], v[178:181], v[186:189], v[106:109]
	v_mfma_f32_16x16x32_bf16 v[98:101], v[170:173], v[194:197], v[98:101]
	v_mfma_f32_16x16x32_bf16 v[90:93], v[178:181], v[194:197], v[90:93]
	v_mfma_f32_16x16x32_bf16 v[82:85], v[170:173], v[202:205], v[82:85]
	v_mfma_f32_16x16x32_bf16 v[74:77], v[178:181], v[202:205], v[74:77]
	v_mfma_f32_16x16x32_bf16 v[70:73], v[170:173], v[210:213], v[70:73]
	v_mfma_f32_16x16x32_bf16 v[66:69], v[178:181], v[210:213], v[66:69]
	v_mfma_f32_16x16x32_bf16 v[114:117], v[174:177], v[190:193], v[114:117]
	v_mfma_f32_16x16x32_bf16 v[106:109], v[182:185], v[190:193], v[106:109]
	v_mfma_f32_16x16x32_bf16 v[98:101], v[174:177], v[198:201], v[98:101]
	v_mfma_f32_16x16x32_bf16 v[90:93], v[182:185], v[198:201], v[90:93]
	v_mfma_f32_16x16x32_bf16 v[82:85], v[174:177], v[206:209], v[82:85]
	v_mfma_f32_16x16x32_bf16 v[74:77], v[182:185], v[206:209], v[74:77]
	v_mfma_f32_16x16x32_bf16 v[70:73], v[174:177], v[214:217], v[70:73]
	v_mfma_f32_16x16x32_bf16 v[66:69], v[182:185], v[214:217], v[66:69]
	s_setprio 0
	s_barrier
	s_add_i32 s36, s66, s41
	v_lshl_add_u64 v[146:147], v[146:147], 0, s[8:9]
	s_mov_b32 m0, s36
	ds_read_b128 v[186:189], v152 offset:49152
	ds_read_b128 v[190:193], v152 offset:50176
	ds_read_b128 v[194:197], v152 offset:51200
	ds_read_b128 v[198:201], v152 offset:52224
	ds_read_b128 v[202:205], v152 offset:53248
	ds_read_b128 v[206:209], v152 offset:54272
	ds_read_b128 v[210:213], v152 offset:55296
	ds_read_b128 v[214:217], v152 offset:56320
	global_load_lds_dwordx4 v[146:147], off
	s_add_i32 m0, s36, 0x2000
	s_add_u32 s34, s34, 0x100080
	v_lshl_add_u64 v[146:147], v[218:219], 0, s[8:9]
	s_addc_u32 s35, s35, 0
	s_add_i32 s36, s67, s41
	global_load_lds_dwordx4 v[146:147], off
	v_lshl_add_u64 v[146:147], s[34:35], 0, v[132:133]
	s_mov_b32 m0, s36
	s_nop 0
	global_load_lds_dwordx4 v[146:147], off
	v_lshl_add_u64 v[146:147], s[34:35], 0, v[136:137]
	s_add_i32 m0, s36, 0x2000
	s_nop 0
	global_load_lds_dwordx4 v[146:147], off
	v_lshl_add_u64 v[146:147], v[220:221], 0, s[8:9]
	s_mov_b32 m0, s46
	s_nop 0
	global_load_lds_dwordx4 v[146:147], off
	v_lshl_add_u64 v[146:147], v[222:223], 0, s[8:9]
	s_mov_b32 m0, s47
	s_nop 0
	global_load_lds_dwordx4 v[146:147], off
	s_waitcnt vmcnt(8)
	s_waitcnt lgkmcnt(0)
	s_barrier
	s_setprio 1
	s_waitcnt lgkmcnt(0)
	v_mfma_f32_16x16x32_bf16 v[62:65], v[154:157], v[186:189], v[62:65]
	v_mfma_f32_16x16x32_bf16 v[58:61], v[162:165], v[186:189], v[58:61]
	v_mfma_f32_16x16x32_bf16 v[54:57], v[154:157], v[194:197], v[54:57]
	v_mfma_f32_16x16x32_bf16 v[46:49], v[162:165], v[194:197], v[46:49]
	v_mfma_f32_16x16x32_bf16 v[38:41], v[154:157], v[202:205], v[38:41]
	v_mfma_f32_16x16x32_bf16 v[30:33], v[162:165], v[202:205], v[30:33]
	v_mfma_f32_16x16x32_bf16 v[22:25], v[154:157], v[210:213], v[22:25]
	v_mfma_f32_16x16x32_bf16 v[14:17], v[162:165], v[210:213], v[14:17]
	v_mfma_f32_16x16x32_bf16 v[62:65], v[158:161], v[190:193], v[62:65]
	v_mfma_f32_16x16x32_bf16 v[58:61], v[166:169], v[190:193], v[58:61]
	v_mfma_f32_16x16x32_bf16 v[54:57], v[158:161], v[198:201], v[54:57]
	v_mfma_f32_16x16x32_bf16 v[46:49], v[166:169], v[198:201], v[46:49]
	v_mfma_f32_16x16x32_bf16 v[38:41], v[158:161], v[206:209], v[38:41]
	v_mfma_f32_16x16x32_bf16 v[30:33], v[166:169], v[206:209], v[30:33]
	v_mfma_f32_16x16x32_bf16 v[22:25], v[158:161], v[214:217], v[22:25]
	v_mfma_f32_16x16x32_bf16 v[14:17], v[166:169], v[214:217], v[14:17]
	s_setprio 0
	s_setprio 1
	v_mfma_f32_16x16x32_bf16 v[50:53], v[170:173], v[186:189], v[50:53]
	v_mfma_f32_16x16x32_bf16 v[42:45], v[178:181], v[186:189], v[42:45]
	v_mfma_f32_16x16x32_bf16 v[34:37], v[170:173], v[194:197], v[34:37]
	v_mfma_f32_16x16x32_bf16 v[26:29], v[178:181], v[194:197], v[26:29]
	v_mfma_f32_16x16x32_bf16 v[18:21], v[170:173], v[202:205], v[18:21]
	v_mfma_f32_16x16x32_bf16 v[10:13], v[178:181], v[202:205], v[10:13]
	v_mfma_f32_16x16x32_bf16 v[6:9], v[170:173], v[210:213], v[6:9]
	v_mfma_f32_16x16x32_bf16 v[2:5], v[178:181], v[210:213], v[2:5]
	v_mfma_f32_16x16x32_bf16 v[50:53], v[174:177], v[190:193], v[50:53]
	v_mfma_f32_16x16x32_bf16 v[42:45], v[182:185], v[190:193], v[42:45]
	v_mfma_f32_16x16x32_bf16 v[34:37], v[174:177], v[198:201], v[34:37]
	v_mfma_f32_16x16x32_bf16 v[26:29], v[182:185], v[198:201], v[26:29]
	v_mfma_f32_16x16x32_bf16 v[18:21], v[174:177], v[206:209], v[18:21]
	v_mfma_f32_16x16x32_bf16 v[10:13], v[182:185], v[206:209], v[10:13]
	v_mfma_f32_16x16x32_bf16 v[6:9], v[174:177], v[214:217], v[6:9]
	v_mfma_f32_16x16x32_bf16 v[2:5], v[182:185], v[214:217], v[2:5]
	s_setprio 0
	s_barrier
	s_add_i32 s65, s65, 2
	s_add_u32 s30, s30, 0x100
	s_addc_u32 s31, s31, 0
	s_add_u32 s63, s63, 0x100
	s_addc_u32 s64, s64, 0
	s_mov_b32 s100, 0
	s_cmp_gt_u32 s65, 61
	s_cbranch_scc0 .LBB0_1241
	s_and_b64 vcc, exec, s[10:11]
	s_cbranch_vccz .LBB0_1244
	s_barrier
.LBB0_1244:
	v_lshl_add_u32 v154, s28, 8, v1
	v_lshl_or_b32 v146, s60, 8, v149
	v_ashrrev_i32_e32 v155, 31, v154
	v_ashrrev_i32_e32 v147, 31, v146
	v_lshlrev_b64 v[156:157], 11, v[154:155]
	v_lshl_add_u64 v[156:157], s[6:7], 0, v[156:157]
	v_lshlrev_b64 v[158:159], 1, v[146:147]
	v_lshl_add_u64 v[146:147], v[156:157], 0, v[158:159]
	v_cvt_pk_bf16_f32 v126, v126, v127
	v_cvt_pk_bf16_f32 v127, v128, v129
	v_cvt_pk_bf16_f32 v128, v122, v123
	v_cvt_pk_bf16_f32 v129, v124, v125
	global_store_dwordx4 v[146:147], v[126:129], off
	v_cvt_pk_bf16_f32 v114, v114, v115
	v_cvt_pk_bf16_f32 v115, v116, v117
	v_cvt_pk_bf16_f32 v116, v106, v107
	v_or_b32_e32 v106, 16, v154
	v_ashrrev_i32_e32 v107, 31, v106
	v_lshlrev_b64 v[106:107], 11, v[106:107]
	v_lshl_add_u64 v[106:107], s[6:7], 0, v[106:107]
	v_cvt_pk_bf16_f32 v117, v108, v109
	global_store_dwordx4 v[146:147], v[114:117], off offset:256
	s_nop 1
	v_lshl_add_u64 v[114:115], v[106:107], 0, v[158:159]
	v_cvt_pk_bf16_f32 v106, v118, v119
	v_cvt_pk_bf16_f32 v107, v120, v121
	v_cvt_pk_bf16_f32 v108, v110, v111
	v_cvt_pk_bf16_f32 v109, v112, v113
	global_store_dwordx4 v[114:115], v[106:109], off
	v_cvt_pk_bf16_f32 v98, v98, v99
	v_cvt_pk_bf16_f32 v99, v100, v101
	v_cvt_pk_bf16_f32 v100, v90, v91
	v_or_b32_e32 v90, 32, v154
	v_ashrrev_i32_e32 v91, 31, v90
	v_lshlrev_b64 v[90:91], 11, v[90:91]
	v_lshl_add_u64 v[90:91], s[6:7], 0, v[90:91]
	v_cvt_pk_bf16_f32 v101, v92, v93
	global_store_dwordx4 v[114:115], v[98:101], off offset:256
	s_nop 1
	v_lshl_add_u64 v[98:99], v[90:91], 0, v[158:159]
	v_cvt_pk_bf16_f32 v90, v102, v103
	v_cvt_pk_bf16_f32 v91, v104, v105
	v_cvt_pk_bf16_f32 v92, v94, v95
	v_cvt_pk_bf16_f32 v93, v96, v97
	global_store_dwordx4 v[98:99], v[90:93], off
	v_cvt_pk_bf16_f32 v82, v82, v83
	v_cvt_pk_bf16_f32 v83, v84, v85
	v_cvt_pk_bf16_f32 v84, v74, v75
	v_or_b32_e32 v74, 48, v154
	v_ashrrev_i32_e32 v75, 31, v74
	v_lshlrev_b64 v[74:75], 11, v[74:75]
	v_lshl_add_u64 v[74:75], s[6:7], 0, v[74:75]
	v_cvt_pk_bf16_f32 v85, v76, v77
	global_store_dwordx4 v[98:99], v[82:85], off offset:256
	s_nop 1
	v_lshl_add_u64 v[82:83], v[74:75], 0, v[158:159]
	v_cvt_pk_bf16_f32 v74, v86, v87
	v_cvt_pk_bf16_f32 v75, v88, v89
	v_cvt_pk_bf16_f32 v76, v78, v79
	v_cvt_pk_bf16_f32 v77, v80, v81
	global_store_dwordx4 v[82:83], v[74:77], off
	v_cvt_pk_bf16_f32 v70, v70, v71
	v_cvt_pk_bf16_f32 v71, v72, v73
	v_cvt_pk_bf16_f32 v72, v66, v67
	v_cvt_pk_bf16_f32 v73, v68, v69
	global_store_dwordx4 v[82:83], v[70:73], off offset:256
	v_cvt_pk_bf16_f32 v62, v62, v63
	v_cvt_pk_bf16_f32 v63, v64, v65
	v_cvt_pk_bf16_f32 v64, v58, v59
	v_add_co_u32_e32 v58, vcc, s56, v146
	v_lshl_add_u64 v[66:67], v[146:147], 0, s[12:13]
	s_nop 0
	v_addc_co_u32_e32 v59, vcc, 0, v147, vcc
	v_cvt_pk_bf16_f32 v65, v60, v61
	global_store_dwordx4 v[58:59], v[62:65], off
	v_cvt_pk_bf16_f32 v50, v50, v51
	v_cvt_pk_bf16_f32 v51, v52, v53
	v_cvt_pk_bf16_f32 v52, v42, v43
	v_cvt_pk_bf16_f32 v53, v44, v45
	global_store_dwordx4 v[66:67], v[50:53], off offset:256
	v_cvt_pk_bf16_f32 v42, v54, v55
	v_cvt_pk_bf16_f32 v43, v56, v57
	v_cvt_pk_bf16_f32 v44, v46, v47
	v_add_co_u32_e32 v46, vcc, s57, v146
	s_nop 0
	v_lshl_add_u64 v[50:51], v[146:147], 0, s[14:15]
	v_addc_co_u32_e32 v47, vcc, 0, v147, vcc
	v_cvt_pk_bf16_f32 v45, v48, v49
	global_store_dwordx4 v[46:47], v[42:45], off
	v_cvt_pk_bf16_f32 v34, v34, v35
	v_cvt_pk_bf16_f32 v35, v36, v37
	v_cvt_pk_bf16_f32 v36, v26, v27
	v_cvt_pk_bf16_f32 v37, v28, v29
	global_store_dwordx4 v[50:51], v[34:37], off offset:256
	v_cvt_pk_bf16_f32 v26, v38, v39
	v_cvt_pk_bf16_f32 v27, v40, v41
	v_cvt_pk_bf16_f32 v28, v30, v31
	v_add_co_u32_e32 v30, vcc, s58, v146
	s_nop 0
	v_lshl_add_u64 v[34:35], v[146:147], 0, s[16:17]
	v_addc_co_u32_e32 v31, vcc, 0, v147, vcc
	v_cvt_pk_bf16_f32 v29, v32, v33
	global_store_dwordx4 v[30:31], v[26:29], off
	v_cvt_pk_bf16_f32 v18, v18, v19
	v_cvt_pk_bf16_f32 v19, v20, v21
	v_cvt_pk_bf16_f32 v20, v10, v11
	v_cvt_pk_bf16_f32 v21, v12, v13
	global_store_dwordx4 v[34:35], v[18:21], off offset:256
	v_cvt_pk_bf16_f32 v10, v22, v23
	v_cvt_pk_bf16_f32 v11, v24, v25
	v_cvt_pk_bf16_f32 v12, v14, v15
	v_add_co_u32_e32 v14, vcc, s59, v146
	s_nop 0
	v_lshl_add_u64 v[18:19], v[146:147], 0, s[18:19]
	v_addc_co_u32_e32 v15, vcc, 0, v147, vcc
	s_andn2_b64 vcc, exec, s[0:1]
	s_mov_b64 s[0:1], -1
	v_cvt_pk_bf16_f32 v13, v16, v17
	global_store_dwordx4 v[14:15], v[10:13], off
	v_cvt_pk_bf16_f32 v6, v6, v7
	v_cvt_pk_bf16_f32 v7, v8, v9
	v_cvt_pk_bf16_f32 v8, v2, v3
	v_cvt_pk_bf16_f32 v9, v4, v5
	global_store_dwordx4 v[18:19], v[6:9], off offset:256
	s_mov_b32 s100, 1
	s_cbranch_vccnz .LBB0_1233
	s_andn2_b64 vcc, exec, s[4:5]
	s_cbranch_vccnz .LBB0_1232
	s_barrier
	s_branch .LBB0_1232

	.amdhsa_kernel _Z3fwd4Args
		.amdhsa_group_segment_fixed_size 0
		.amdhsa_private_segment_fixed_size 0
		.amdhsa_kernarg_size 392
		.amdhsa_user_sgpr_count 2
		.amdhsa_user_sgpr_dispatch_ptr 0
		.amdhsa_user_sgpr_queue_ptr 0
		.amdhsa_user_sgpr_kernarg_segment_ptr 1
		.amdhsa_user_sgpr_dispatch_id 0
		.amdhsa_user_sgpr_kernarg_preload_length 0
		.amdhsa_user_sgpr_kernarg_preload_offset 0
		.amdhsa_user_sgpr_private_segment_size 0
		.amdhsa_uses_dynamic_stack 0
		.amdhsa_enable_private_segment 0
		.amdhsa_system_sgpr_workgroup_id_x 1
		.amdhsa_system_sgpr_workgroup_id_y 0
		.amdhsa_system_sgpr_workgroup_id_z 0
		.amdhsa_system_sgpr_workgroup_info 0
		.amdhsa_system_vgpr_workitem_id 0
		.amdhsa_next_free_vgpr 234
		.amdhsa_next_free_sgpr 101
		.amdhsa_accum_offset 236
		.amdhsa_reserve_vcc 1
		.amdhsa_float_round_mode_32 0
		.amdhsa_float_round_mode_16_64 0
		.amdhsa_float_denorm_mode_32 3
		.amdhsa_float_denorm_mode_16_64 3
		.amdhsa_dx10_clamp 1
		.amdhsa_ieee_mode 1
		.amdhsa_fp16_overflow 0
		.amdhsa_tg_split 0
		.amdhsa_exception_fp_ieee_invalid_op 0
		.amdhsa_exception_fp_denorm_src 0
		.amdhsa_exception_fp_ieee_div_zero 0
		.amdhsa_exception_fp_ieee_overflow 0
		.amdhsa_exception_fp_ieee_underflow 0
		.amdhsa_exception_fp_ieee_inexact 0
		.amdhsa_exception_int_div_zero 0
	.end_amdhsa_kernel
